# branch GEMM: gated running sum kept in the f32 accumulators across the three units of a tile (rescale by 1+exp(-g) / sigmoid), no f32 partial-sum round trip through memory
# speedup vs baseline: 1.0186x; 1.0182x over previous
; template <class Epi, class Sched, bool ALIGN_EPI = false, bool SP2 = false>
; __device__ __forceinline__ void gemm_phase(PG8_LAS unsigned char* lds, const Gemm g, const Sched& S, const Epi& E) {
;     ...
;         const bool has_next = S.next(ui + 1, nxt);
;         const char* nA = has_next ? (const char*)g.A + (size_t)nxt.pm * tstepA + ((size_t)(nxt.z / g.zdiv) * g.zA + (size_t)(nxt.z % g.zdiv) * g.zA2) * 2 : cA; const char* nB = has_next ? (const char*)g.Bt + (size_t)nxt.pn * tstepB + ((size_t)(nxt.z / g.zdiv) * g.zB + (size_t)(nxt.z % g.zdiv) * g.zB2) * 2 : cB;
.LBB0_1688:
	s_nop 0
	v_cndmask_b32_e64 v144, 0, 1, s[4:5]
	v_cmp_ne_u32_e64 s[0:1], 1, v144
	s_andn2_b64 vcc, exec, s[4:5]
	s_mov_b64 s[56:57], s[10:11]
	s_cbranch_vccnz .LBB0_1690
	s_ashr_i32 s45, s44, 31
	v_readlane_b32 s60, v250, 30
	s_lshl_b64 s[4:5], s[44:45], 19
	v_readlane_b32 s70, v250, 40
	v_readlane_b32 s71, v250, 41
	s_add_u32 s4, s70, s4
	s_addc_u32 s5, s71, s5
	s_mul_i32 s22, s48, 0x1080000
	v_readlane_b32 s76, v250, 46
	s_mul_hi_i32 s21, s48, 0x1080000
	s_add_u32 s56, s4, s22
	v_readlane_b32 s77, v250, 47
	v_readlane_b32 s84, v250, 54
	v_readlane_b32 s85, v250, 55
	v_readlane_b32 s86, v250, 56
	v_readlane_b32 s87, v250, 57
	v_readlane_b32 s88, v250, 58
	v_readlane_b32 s89, v250, 59
	v_readlane_b32 s90, v250, 60
	v_readlane_b32 s91, v250, 61
	s_addc_u32 s57, s5, s21
	v_readlane_b32 s61, v250, 31
	v_readlane_b32 s62, v250, 32
	v_readlane_b32 s63, v250, 33
	v_readlane_b32 s64, v250, 34
	v_readlane_b32 s65, v250, 35
	v_readlane_b32 s66, v250, 36
	v_readlane_b32 s67, v250, 37
	v_readlane_b32 s68, v250, 38
	v_readlane_b32 s69, v250, 39
	v_readlane_b32 s72, v250, 42
	v_readlane_b32 s73, v250, 43
	v_readlane_b32 s74, v250, 44
	v_readlane_b32 s75, v250, 45
	v_readlane_b32 s78, v250, 48
	v_readlane_b32 s79, v250, 49
	v_readlane_b32 s80, v250, 50
	v_readlane_b32 s81, v250, 51
	v_readlane_b32 s82, v250, 52
	v_readlane_b32 s83, v250, 53

; #define PG8_STAGE(bufoff, gbase, voff) do { _Pragma("unroll") for (int _i = 0; _i < 2; ++_i) \
;         __builtin_amdgcn_global_load_lds((const unsigned*)((const char*)(gbase) + (voff)[_i]), (PG8_LAS unsigned*)(lds + (bufoff) + ldsw + _i * 8192), 16, 0, 0); } while (0)
; #define PG8_LDA(dst, b, h) do { _Pragma("unroll") for (int m = 0; m < 4; ++m) _Pragma("unroll") for (int k = 0; k < 2; ++k) dst[m][k] = *(const PG8_LAS bf16x8*)(lds + PG8_SA(b, h) + aoff + m * 2048 + k * 1024); } while (0)
; #define PG8_LDB(dst, b, h) do { _Pragma("unroll") for (int n = 0; n < 2; ++n) _Pragma("unroll") for (int k = 0; k < 2; ++k) dst[n][k] = *(const PG8_LAS bf16x8*)(lds + PG8_SB(b, h) + boff + n * 2048 + k * 1024); } while (0)
; #define PG8_MMA(ai, bj, At, Bt) do { __builtin_amdgcn_s_setprio(1); _Pragma("unroll") for (int m = 0; m < 4; ++m) _Pragma("unroll") for (int n = 0; n < 2; ++n) _Pragma("unroll") for (int k = 0; k < 2; ++k) \
;         acc[ai][bj][m][n] = __builtin_amdgcn_mfma_f32_16x16x32_bf16(Bt[n][k], At[m][k], acc[ai][bj][m][n], 0, 0, 0); __builtin_amdgcn_s_setprio(0); } while (0)
; #define PG8_WAIT_V(n) asm volatile("s_waitcnt vmcnt(" #n ")" ::: "memory")
; template <class Epi, class Sched, bool ALIGN_EPI = false, bool SP2 = false>
; __device__ __forceinline__ void gemm_phase(PG8_LAS unsigned char* lds, const Gemm g, const Sched& S, const Epi& E) {
;     ...
;         for (int t = 0; t < nt; t += 2) {
;             const bool last = (t == nt - 2);
;             const char* a1 = cA + (size_t)(t + 1) * kstep;
;             const char* a2 = last ? nA : cA + (size_t)(t + 2) * kstep; const char* b2 = last ? nB : cB + (size_t)(t + 2) * kstep;
;             const char* a3 = a2 + kstep; const char* b3 = b2 + kstep;
;             if (last && has_next) S.a_ready(nxt);
;             if constexpr (SP2) {
;             PG8_LDB(B0, 0, 0); PG8_LDB(B1, 0, 1); PG8_SCHED; PG8_LDA(At, 0, 0); PG8_STAGE(PG8_SA(1, 1), a1 + hstepA, voffA);
;             PG8_WAIT_V(8); PG8_WAIT_L(0); PG8_BAR; PG8_MMA(0, 0, At, B0); PG8_MMA(0, 1, At, B1); PG8_BAR; PG8_SCHED;
;     ...
; #pragma unroll
;         for (int a = 0; a < 2; ++a)
; #pragma unroll
;             for (int b = 0; b < 2; ++b)
; #pragma unroll
;                 for (int m = 0; m < 4; ++m)
; #pragma unroll
;                     for (int n = 0; n < 2; ++n) acc[a][b][m][n] = (f32x4){0.f, 0.f, 0.f, 0.f};
;         cur = nxt; cA = nA; cB = nB; ++ui;
.LBB0_1692:
	s_add_u32 s4, s10, 0x40080
	s_addc_u32 s5, s11, 0
	s_add_u32 s21, s8, 0x100
	s_addc_u32 s22, s9, 0
	s_mov_b32 s23, -2
	s_cmp_lg_u32 s6, 0
	s_cbranch_scc1 .Lemx_keepacc
	v_mov_b32_e32 v2, 0
	v_mov_b32_e32 v3, v2
	v_mov_b32_e32 v4, v2
	v_mov_b32_e32 v5, v2
	v_mov_b32_e32 v6, v2
	v_mov_b32_e32 v7, v2
	v_mov_b32_e32 v8, v2
	v_mov_b32_e32 v9, v2
	v_mov_b32_e32 v18, v2
	v_mov_b32_e32 v19, v2
	v_mov_b32_e32 v20, v2
	v_mov_b32_e32 v21, v2
	v_mov_b32_e32 v22, v2
	v_mov_b32_e32 v23, v2
	v_mov_b32_e32 v24, v2
	v_mov_b32_e32 v25, v2
	v_mov_b32_e32 v34, v2
	v_mov_b32_e32 v35, v2
	v_mov_b32_e32 v36, v2
	v_mov_b32_e32 v37, v2
	v_mov_b32_e32 v38, v2
	v_mov_b32_e32 v39, v2
	v_mov_b32_e32 v40, v2
	v_mov_b32_e32 v41, v2
	v_mov_b32_e32 v50, v2
	v_mov_b32_e32 v51, v2
	v_mov_b32_e32 v52, v2
	v_mov_b32_e32 v53, v2
	v_mov_b32_e32 v54, v2
	v_mov_b32_e32 v55, v2
	v_mov_b32_e32 v56, v2
	v_mov_b32_e32 v57, v2
	v_mov_b32_e32 v10, v2
	v_mov_b32_e32 v11, v2
	v_mov_b32_e32 v12, v2
	v_mov_b32_e32 v13, v2
	v_mov_b32_e32 v14, v2
	v_mov_b32_e32 v15, v2
	v_mov_b32_e32 v16, v2
	v_mov_b32_e32 v17, v2
	v_mov_b32_e32 v26, v2
	v_mov_b32_e32 v27, v2
	v_mov_b32_e32 v28, v2
	v_mov_b32_e32 v29, v2
	v_mov_b32_e32 v30, v2
	v_mov_b32_e32 v31, v2
	v_mov_b32_e32 v32, v2
	v_mov_b32_e32 v33, v2
	v_mov_b32_e32 v42, v2
	v_mov_b32_e32 v43, v2
	v_mov_b32_e32 v44, v2
	v_mov_b32_e32 v45, v2
	v_mov_b32_e32 v46, v2
	v_mov_b32_e32 v47, v2
	v_mov_b32_e32 v48, v2
	v_mov_b32_e32 v49, v2
	v_mov_b32_e32 v58, v2
	v_mov_b32_e32 v59, v2
	v_mov_b32_e32 v60, v2
	v_mov_b32_e32 v61, v2
	v_mov_b32_e32 v62, v2
	v_mov_b32_e32 v63, v2
	v_mov_b32_e32 v64, v2
	v_mov_b32_e32 v65, v2
	v_mov_b32_e32 v66, v2
	v_mov_b32_e32 v67, v2
	v_mov_b32_e32 v68, v2
	v_mov_b32_e32 v69, v2
	v_mov_b32_e32 v70, v2
	v_mov_b32_e32 v71, v2
	v_mov_b32_e32 v72, v2
	v_mov_b32_e32 v73, v2
	v_mov_b32_e32 v82, v2
	v_mov_b32_e32 v83, v2
	v_mov_b32_e32 v84, v2
	v_mov_b32_e32 v85, v2
	v_mov_b32_e32 v86, v2
	v_mov_b32_e32 v87, v2
	v_mov_b32_e32 v88, v2
	v_mov_b32_e32 v89, v2
	v_mov_b32_e32 v98, v2
	v_mov_b32_e32 v99, v2
	v_mov_b32_e32 v100, v2
	v_mov_b32_e32 v101, v2
	v_mov_b32_e32 v102, v2
	v_mov_b32_e32 v103, v2
	v_mov_b32_e32 v104, v2
	v_mov_b32_e32 v105, v2
	v_mov_b32_e32 v114, v2
	v_mov_b32_e32 v115, v2
	v_mov_b32_e32 v116, v2
	v_mov_b32_e32 v117, v2
	v_mov_b32_e32 v118, v2
	v_mov_b32_e32 v119, v2
	v_mov_b32_e32 v120, v2
	v_mov_b32_e32 v121, v2
	v_mov_b32_e32 v74, v2
	v_mov_b32_e32 v75, v2
	v_mov_b32_e32 v76, v2
	v_mov_b32_e32 v77, v2
	v_mov_b32_e32 v78, v2
	v_mov_b32_e32 v79, v2
	v_mov_b32_e32 v80, v2
	v_mov_b32_e32 v81, v2
	v_mov_b32_e32 v90, v2
	v_mov_b32_e32 v91, v2
	v_mov_b32_e32 v92, v2
	v_mov_b32_e32 v93, v2
	v_mov_b32_e32 v94, v2
	v_mov_b32_e32 v95, v2
	v_mov_b32_e32 v96, v2
	v_mov_b32_e32 v97, v2
	v_mov_b32_e32 v106, v2
	v_mov_b32_e32 v107, v2
	v_mov_b32_e32 v108, v2
	v_mov_b32_e32 v109, v2
	v_mov_b32_e32 v110, v2
	v_mov_b32_e32 v111, v2
	v_mov_b32_e32 v112, v2
	v_mov_b32_e32 v113, v2
	v_mov_b32_e32 v122, v2
	v_mov_b32_e32 v123, v2
	v_mov_b32_e32 v124, v2
	v_mov_b32_e32 v125, v2
	v_mov_b32_e32 v126, v2
	v_mov_b32_e32 v127, v2
	v_mov_b32_e32 v128, v2
	v_mov_b32_e32 v129, v2
.Lemx_keepacc:
.LBB0_1693:
	s_add_u32 s8, s4, 0xfffc0080
	s_addc_u32 s9, s5, -1
	s_add_i32 s24, 0, 0x10000
	s_cmp_eq_u32 s23, 12
	s_cselect_b32 s11, s57, s9
	s_cselect_b32 s10, s56, s8
	v_add_u32_e32 v148, s24, v150
	s_cselect_b32 s9, s93, s22
	s_cselect_b32 s8, s92, s21
	s_add_i32 s26, 0, 0x14000
	ds_read_b128 v[140:143], v148
	ds_read_b128 v[144:147], v148 offset:1024
	ds_read_b128 v[154:157], v148 offset:2048
	ds_read_b128 v[158:161], v148 offset:3072
	v_add_u32_e32 v148, s26, v150
	ds_read_b128 v[178:181], v148
	ds_read_b128 v[182:185], v148 offset:1024
	ds_read_b128 v[186:189], v148 offset:2048
	ds_read_b128 v[190:193], v148 offset:3072
	v_lshl_add_u64 v[148:149], s[4:5], 0, v[136:137]
	s_add_i32 m0, s13, 0xc000
	ds_read_b128 v[210:213], v152
	ds_read_b128 v[214:217], v152 offset:1024
	ds_read_b128 v[218:221], v152 offset:2048
	ds_read_b128 v[222:225], v152 offset:3072
	ds_read_b128 v[226:229], v152 offset:4096
	ds_read_b128 v[230:233], v152 offset:5120
	ds_read_b128 v[234:237], v152 offset:6144
	ds_read_b128 v[238:241], v152 offset:7168
	global_load_lds_dwordx4 v[148:149], off
	v_lshl_add_u64 v[148:149], s[4:5], 0, v[138:139]
	s_add_i32 m0, s13, 0xe000
	s_nop 0
	global_load_lds_dwordx4 v[148:149], off
	s_waitcnt vmcnt(8)
	s_waitcnt lgkmcnt(0)
	s_barrier
	s_setprio 1
	s_waitcnt lgkmcnt(0)
	v_mfma_f32_16x16x32_bf16 v[126:129], v[140:143], v[210:213], v[126:129]
	v_mfma_f32_16x16x32_bf16 v[122:125], v[154:157], v[210:213], v[122:125]
	v_mfma_f32_16x16x32_bf16 v[110:113], v[140:143], v[218:221], v[110:113]
	v_mfma_f32_16x16x32_bf16 v[106:109], v[154:157], v[218:221], v[106:109]
	v_mfma_f32_16x16x32_bf16 v[94:97], v[140:143], v[226:229], v[94:97]
	v_mfma_f32_16x16x32_bf16 v[90:93], v[154:157], v[226:229], v[90:93]
	v_mfma_f32_16x16x32_bf16 v[78:81], v[140:143], v[234:237], v[78:81]
	v_mfma_f32_16x16x32_bf16 v[74:77], v[154:157], v[234:237], v[74:77]
	v_mfma_f32_16x16x32_bf16 v[126:129], v[144:147], v[214:217], v[126:129]
	v_mfma_f32_16x16x32_bf16 v[122:125], v[158:161], v[214:217], v[122:125]
	v_mfma_f32_16x16x32_bf16 v[110:113], v[144:147], v[222:225], v[110:113]
	v_mfma_f32_16x16x32_bf16 v[106:109], v[158:161], v[222:225], v[106:109]
	v_mfma_f32_16x16x32_bf16 v[94:97], v[144:147], v[230:233], v[94:97]
	v_mfma_f32_16x16x32_bf16 v[90:93], v[158:161], v[230:233], v[90:93]
	v_mfma_f32_16x16x32_bf16 v[78:81], v[144:147], v[238:241], v[78:81]
	v_mfma_f32_16x16x32_bf16 v[74:77], v[158:161], v[238:241], v[74:77]
	v_mfma_f32_16x16x32_bf16 v[118:121], v[178:181], v[210:213], v[118:121]
	v_mfma_f32_16x16x32_bf16 v[114:117], v[186:189], v[210:213], v[114:117]
	v_mfma_f32_16x16x32_bf16 v[102:105], v[178:181], v[218:221], v[102:105]
	v_mfma_f32_16x16x32_bf16 v[98:101], v[186:189], v[218:221], v[98:101]
	v_mfma_f32_16x16x32_bf16 v[86:89], v[178:181], v[226:229], v[86:89]
	v_mfma_f32_16x16x32_bf16 v[82:85], v[186:189], v[226:229], v[82:85]
	v_mfma_f32_16x16x32_bf16 v[70:73], v[178:181], v[234:237], v[70:73]
	v_mfma_f32_16x16x32_bf16 v[66:69], v[186:189], v[234:237], v[66:69]
	v_mfma_f32_16x16x32_bf16 v[118:121], v[182:185], v[214:217], v[118:121]
	v_mfma_f32_16x16x32_bf16 v[114:117], v[190:193], v[214:217], v[114:117]
	v_mfma_f32_16x16x32_bf16 v[102:105], v[182:185], v[222:225], v[102:105]
	v_mfma_f32_16x16x32_bf16 v[98:101], v[190:193], v[222:225], v[98:101]
	v_mfma_f32_16x16x32_bf16 v[86:89], v[182:185], v[230:233], v[86:89]
	v_mfma_f32_16x16x32_bf16 v[82:85], v[190:193], v[230:233], v[82:85]
	v_mfma_f32_16x16x32_bf16 v[70:73], v[182:185], v[238:241], v[70:73]
	v_mfma_f32_16x16x32_bf16 v[66:69], v[190:193], v[238:241], v[66:69]
	s_setprio 0
	s_barrier
; #define PG8_STAGE(bufoff, gbase, voff) do { _Pragma("unroll") for (int _i = 0; _i < 2; ++_i) \
;         __builtin_amdgcn_global_load_lds((const unsigned*)((const char*)(gbase) + (voff)[_i]), (PG8_LAS unsigned*)(lds + (bufoff) + ldsw + _i * 8192), 16, 0, 0); } while (0)
; #define PG8_LDA(dst, b, h) do { _Pragma("unroll") for (int m = 0; m < 4; ++m) _Pragma("unroll") for (int k = 0; k < 2; ++k) dst[m][k] = *(const PG8_LAS bf16x8*)(lds + PG8_SA(b, h) + aoff + m * 2048 + k * 1024); } while (0)
; #define PG8_LDB(dst, b, h) do { _Pragma("unroll") for (int n = 0; n < 2; ++n) _Pragma("unroll") for (int k = 0; k < 2; ++k) dst[n][k] = *(const PG8_LAS bf16x8*)(lds + PG8_SB(b, h) + boff + n * 2048 + k * 1024); } while (0)
; #define PG8_MMA(ai, bj, At, Bt) do { __builtin_amdgcn_s_setprio(1); _Pragma("unroll") for (int m = 0; m < 4; ++m) _Pragma("unroll") for (int n = 0; n < 2; ++n) _Pragma("unroll") for (int k = 0; k < 2; ++k) \
;         acc[ai][bj][m][n] = __builtin_amdgcn_mfma_f32_16x16x32_bf16(Bt[n][k], At[m][k], acc[ai][bj][m][n], 0, 0, 0); __builtin_amdgcn_s_setprio(0); } while (0)
; #define PG8_WAIT_V(n) asm volatile("s_waitcnt vmcnt(" #n ")" ::: "memory")
; #define PG8_WAIT_L(n) asm volatile("s_waitcnt lgkmcnt(" #n ")" ::: "memory")
; #define PG8_BAR __builtin_amdgcn_s_barrier()
; #define PG8_SCHED __builtin_amdgcn_sched_barrier(0)
; template <class Epi, class Sched, bool ALIGN_EPI = false, bool SP2 = false>
; __device__ __forceinline__ void gemm_phase(PG8_LAS unsigned char* lds, const Gemm g, const Sched& S, const Epi& E) {
;     ...
;             PG8_LDA(At, 0, 1); PG8_STAGE(PG8_SB(0, 0), b2, voffB); PG8_STAGE(PG8_SB(0, 1), b2 + hstepB, voffB); PG8_STAGE(PG8_SA(0, 0), a2, voffA);
;             PG8_WAIT_V(8); PG8_WAIT_L(0); PG8_BAR; PG8_MMA(1, 0, At, B0); PG8_MMA(1, 1, At, B1); PG8_BAR; PG8_SCHED;
;             PG8_LDB(B0, 1, 0); PG8_LDB(B1, 1, 1); PG8_SCHED; PG8_LDA(At, 1, 0); PG8_STAGE(PG8_SA(0, 1), a2 + hstepA, voffA);
;             PG8_WAIT_V(8); PG8_WAIT_L(0); PG8_BAR; PG8_MMA(0, 0, At, B0); PG8_MMA(0, 1, At, B1); PG8_BAR; PG8_SCHED;
	s_add_i32 s24, s24, s12
	v_lshl_add_u64 v[148:149], s[8:9], 0, v[162:163]
	s_mov_b32 m0, s24
	ds_read_b128 v[210:213], v152 offset:16384
	ds_read_b128 v[214:217], v152 offset:17408
	ds_read_b128 v[218:221], v152 offset:18432
	ds_read_b128 v[222:225], v152 offset:19456
	ds_read_b128 v[226:229], v152 offset:20480
	ds_read_b128 v[230:233], v152 offset:21504
	ds_read_b128 v[234:237], v152 offset:22528
	ds_read_b128 v[238:241], v152 offset:23552
	global_load_lds_dwordx4 v[148:149], off
	s_add_i32 m0, s24, 0x2000
	s_add_u32 s24, s8, 0x40000
	v_lshl_add_u64 v[168:169], s[8:9], 0, v[130:131]
	s_addc_u32 s25, s9, 0
	s_add_i32 s26, s26, s12
	global_load_lds_dwordx4 v[168:169], off
	v_lshl_add_u64 v[170:171], s[24:25], 0, v[162:163]
	s_mov_b32 m0, s26
	v_lshl_add_u64 v[172:173], s[10:11], 0, v[132:133]
	global_load_lds_dwordx4 v[170:171], off
	v_lshl_add_u64 v[170:171], s[24:25], 0, v[130:131]
	s_add_i32 m0, s26, 0x2000
	s_nop 0
	global_load_lds_dwordx4 v[170:171], off
	v_lshl_add_u64 v[170:171], s[10:11], 0, v[134:135]
	s_mov_b32 m0, s13
	s_nop 0
	global_load_lds_dwordx4 v[170:171], off
	s_mov_b32 m0, s14
	s_nop 0
	global_load_lds_dwordx4 v[172:173], off
	s_waitcnt vmcnt(8)
	s_waitcnt lgkmcnt(0)
	s_barrier
	s_setprio 1
	s_waitcnt lgkmcnt(0)
	v_mfma_f32_16x16x32_bf16 v[62:65], v[140:143], v[210:213], v[62:65]
	v_mfma_f32_16x16x32_bf16 v[58:61], v[154:157], v[210:213], v[58:61]
	v_mfma_f32_16x16x32_bf16 v[46:49], v[140:143], v[218:221], v[46:49]
	v_mfma_f32_16x16x32_bf16 v[42:45], v[154:157], v[218:221], v[42:45]
	v_mfma_f32_16x16x32_bf16 v[30:33], v[140:143], v[226:229], v[30:33]
	v_mfma_f32_16x16x32_bf16 v[26:29], v[154:157], v[226:229], v[26:29]
	v_mfma_f32_16x16x32_bf16 v[14:17], v[140:143], v[234:237], v[14:17]
	v_mfma_f32_16x16x32_bf16 v[10:13], v[154:157], v[234:237], v[10:13]
	v_mfma_f32_16x16x32_bf16 v[62:65], v[144:147], v[214:217], v[62:65]
	v_mfma_f32_16x16x32_bf16 v[58:61], v[158:161], v[214:217], v[58:61]
	v_mfma_f32_16x16x32_bf16 v[46:49], v[144:147], v[222:225], v[46:49]
	v_mfma_f32_16x16x32_bf16 v[42:45], v[158:161], v[222:225], v[42:45]
	v_mfma_f32_16x16x32_bf16 v[30:33], v[144:147], v[230:233], v[30:33]
	v_mfma_f32_16x16x32_bf16 v[26:29], v[158:161], v[230:233], v[26:29]
	v_mfma_f32_16x16x32_bf16 v[14:17], v[144:147], v[238:241], v[14:17]
	v_mfma_f32_16x16x32_bf16 v[10:13], v[158:161], v[238:241], v[10:13]
	v_mfma_f32_16x16x32_bf16 v[54:57], v[178:181], v[210:213], v[54:57]
	v_mfma_f32_16x16x32_bf16 v[50:53], v[186:189], v[210:213], v[50:53]
	v_mfma_f32_16x16x32_bf16 v[38:41], v[178:181], v[218:221], v[38:41]
	v_mfma_f32_16x16x32_bf16 v[34:37], v[186:189], v[218:221], v[34:37]
	v_mfma_f32_16x16x32_bf16 v[22:25], v[178:181], v[226:229], v[22:25]
	v_mfma_f32_16x16x32_bf16 v[18:21], v[186:189], v[226:229], v[18:21]
	v_mfma_f32_16x16x32_bf16 v[6:9], v[178:181], v[234:237], v[6:9]
	v_mfma_f32_16x16x32_bf16 v[2:5], v[186:189], v[234:237], v[2:5]
	v_mfma_f32_16x16x32_bf16 v[54:57], v[182:185], v[214:217], v[54:57]
	v_mfma_f32_16x16x32_bf16 v[50:53], v[190:193], v[214:217], v[50:53]
	v_mfma_f32_16x16x32_bf16 v[38:41], v[182:185], v[222:225], v[38:41]
	v_mfma_f32_16x16x32_bf16 v[34:37], v[190:193], v[222:225], v[34:37]
	v_mfma_f32_16x16x32_bf16 v[22:25], v[182:185], v[230:233], v[22:25]
	v_mfma_f32_16x16x32_bf16 v[18:21], v[190:193], v[230:233], v[18:21]
	v_mfma_f32_16x16x32_bf16 v[6:9], v[182:185], v[238:241], v[6:9]
	v_mfma_f32_16x16x32_bf16 v[2:5], v[190:193], v[238:241], v[2:5]
	s_setprio 0
	s_barrier
	s_add_i32 s24, 0, 0x18000
	v_add_u32_e32 v153, s24, v150
	s_add_i32 s25, 0, 0x1c000
	ds_read_b128 v[140:143], v153
	ds_read_b128 v[144:147], v153 offset:1024
	ds_read_b128 v[154:157], v153 offset:2048
	ds_read_b128 v[158:161], v153 offset:3072
	v_add_u32_e32 v153, s25, v150
	ds_read_b128 v[178:181], v153
	ds_read_b128 v[182:185], v153 offset:1024
	ds_read_b128 v[186:189], v153 offset:2048
	ds_read_b128 v[190:193], v153 offset:3072
	s_add_u32 s10, s10, 0x40000
	s_addc_u32 s11, s11, 0
	s_mov_b32 m0, s15
	v_lshl_add_u64 v[194:195], s[10:11], 0, v[134:135]
	ds_read_b128 v[210:213], v152 offset:32768
	ds_read_b128 v[214:217], v152 offset:33792
	ds_read_b128 v[218:221], v152 offset:34816
	ds_read_b128 v[222:225], v152 offset:35840
	ds_read_b128 v[226:229], v152 offset:36864
	ds_read_b128 v[230:233], v152 offset:37888
	ds_read_b128 v[234:237], v152 offset:38912
	ds_read_b128 v[238:241], v152 offset:39936
	global_load_lds_dwordx4 v[194:195], off
	v_lshl_add_u64 v[194:195], s[10:11], 0, v[132:133]
	s_mov_b32 m0, s16
	s_nop 0
	global_load_lds_dwordx4 v[194:195], off
	s_waitcnt vmcnt(8)
	s_waitcnt lgkmcnt(0)
	s_barrier
; #define PG8_STAGE(bufoff, gbase, voff) do { _Pragma("unroll") for (int _i = 0; _i < 2; ++_i) \
;         __builtin_amdgcn_global_load_lds((const unsigned*)((const char*)(gbase) + (voff)[_i]), (PG8_LAS unsigned*)(lds + (bufoff) + ldsw + _i * 8192), 16, 0, 0); } while (0)
; #define PG8_LDA(dst, b, h) do { _Pragma("unroll") for (int m = 0; m < 4; ++m) _Pragma("unroll") for (int k = 0; k < 2; ++k) dst[m][k] = *(const PG8_LAS bf16x8*)(lds + PG8_SA(b, h) + aoff + m * 2048 + k * 1024); } while (0)
; #define PG8_MMA(ai, bj, At, Bt) do { __builtin_amdgcn_s_setprio(1); _Pragma("unroll") for (int m = 0; m < 4; ++m) _Pragma("unroll") for (int n = 0; n < 2; ++n) _Pragma("unroll") for (int k = 0; k < 2; ++k) \
;         acc[ai][bj][m][n] = __builtin_amdgcn_mfma_f32_16x16x32_bf16(Bt[n][k], At[m][k], acc[ai][bj][m][n], 0, 0, 0); __builtin_amdgcn_s_setprio(0); } while (0)
; #define PG8_WAIT_V(n) asm volatile("s_waitcnt vmcnt(" #n ")" ::: "memory")
; #define PG8_WAIT_L(n) asm volatile("s_waitcnt lgkmcnt(" #n ")" ::: "memory")
; #define PG8_BAR __builtin_amdgcn_s_barrier()
; #define PG8_SCHED __builtin_amdgcn_sched_barrier(0)
; template <class Epi, class Sched, bool ALIGN_EPI = false, bool SP2 = false>
; __device__ __forceinline__ void gemm_phase(PG8_LAS unsigned char* lds, const Gemm g, const Sched& S, const Epi& E) {
;     ...
;         for (int t = 0; t < nt; t += 2) {
;     ...
;             PG8_WAIT_V(8); PG8_WAIT_L(0); PG8_BAR; PG8_MMA(0, 0, At, B0); PG8_MMA(0, 1, At, B1); PG8_BAR; PG8_SCHED;
;             PG8_LDA(At, 1, 1); PG8_STAGE(PG8_SB(1, 0), b3, voffB); PG8_STAGE(PG8_SB(1, 1), b3 + hstepB, voffB); PG8_STAGE(PG8_SA(1, 0), a3, voffA);
;             PG8_WAIT_V(8); PG8_WAIT_L(0); PG8_BAR; PG8_MMA(1, 0, At, B0); PG8_MMA(1, 1, At, B1); PG8_BAR; PG8_SCHED;
	s_setprio 1
	s_waitcnt lgkmcnt(0)
	v_mfma_f32_16x16x32_bf16 v[126:129], v[140:143], v[210:213], v[126:129]
	v_mfma_f32_16x16x32_bf16 v[122:125], v[154:157], v[210:213], v[122:125]
	v_mfma_f32_16x16x32_bf16 v[110:113], v[140:143], v[218:221], v[110:113]
	v_mfma_f32_16x16x32_bf16 v[106:109], v[154:157], v[218:221], v[106:109]
	v_mfma_f32_16x16x32_bf16 v[94:97], v[140:143], v[226:229], v[94:97]
	v_mfma_f32_16x16x32_bf16 v[90:93], v[154:157], v[226:229], v[90:93]
	v_mfma_f32_16x16x32_bf16 v[78:81], v[140:143], v[234:237], v[78:81]
	v_mfma_f32_16x16x32_bf16 v[74:77], v[154:157], v[234:237], v[74:77]
	v_mfma_f32_16x16x32_bf16 v[126:129], v[144:147], v[214:217], v[126:129]
	v_mfma_f32_16x16x32_bf16 v[122:125], v[158:161], v[214:217], v[122:125]
	v_mfma_f32_16x16x32_bf16 v[110:113], v[144:147], v[222:225], v[110:113]
	v_mfma_f32_16x16x32_bf16 v[106:109], v[158:161], v[222:225], v[106:109]
	v_mfma_f32_16x16x32_bf16 v[94:97], v[144:147], v[230:233], v[94:97]
	v_mfma_f32_16x16x32_bf16 v[90:93], v[158:161], v[230:233], v[90:93]
	v_mfma_f32_16x16x32_bf16 v[78:81], v[144:147], v[238:241], v[78:81]
	v_mfma_f32_16x16x32_bf16 v[74:77], v[158:161], v[238:241], v[74:77]
	v_mfma_f32_16x16x32_bf16 v[118:121], v[178:181], v[210:213], v[118:121]
	v_mfma_f32_16x16x32_bf16 v[114:117], v[186:189], v[210:213], v[114:117]
	v_mfma_f32_16x16x32_bf16 v[102:105], v[178:181], v[218:221], v[102:105]
	v_mfma_f32_16x16x32_bf16 v[98:101], v[186:189], v[218:221], v[98:101]
	v_mfma_f32_16x16x32_bf16 v[86:89], v[178:181], v[226:229], v[86:89]
	v_mfma_f32_16x16x32_bf16 v[82:85], v[186:189], v[226:229], v[82:85]
	v_mfma_f32_16x16x32_bf16 v[70:73], v[178:181], v[234:237], v[70:73]
	v_mfma_f32_16x16x32_bf16 v[66:69], v[186:189], v[234:237], v[66:69]
	v_mfma_f32_16x16x32_bf16 v[118:121], v[182:185], v[214:217], v[118:121]
	v_mfma_f32_16x16x32_bf16 v[114:117], v[190:193], v[214:217], v[114:117]
	v_mfma_f32_16x16x32_bf16 v[102:105], v[182:185], v[222:225], v[102:105]
	v_mfma_f32_16x16x32_bf16 v[98:101], v[190:193], v[222:225], v[98:101]
	v_mfma_f32_16x16x32_bf16 v[86:89], v[182:185], v[230:233], v[86:89]
	v_mfma_f32_16x16x32_bf16 v[82:85], v[190:193], v[230:233], v[82:85]
	v_mfma_f32_16x16x32_bf16 v[70:73], v[182:185], v[238:241], v[70:73]
	v_mfma_f32_16x16x32_bf16 v[66:69], v[190:193], v[238:241], v[66:69]
	s_setprio 0
	s_barrier
	s_add_i32 s10, s24, s12
	v_lshl_add_u64 v[148:149], v[148:149], 0, s[50:51]
	s_mov_b32 m0, s10
	ds_read_b128 v[210:213], v152 offset:49152
	ds_read_b128 v[214:217], v152 offset:50176
	ds_read_b128 v[218:221], v152 offset:51200
	ds_read_b128 v[222:225], v152 offset:52224
	ds_read_b128 v[226:229], v152 offset:53248
	ds_read_b128 v[230:233], v152 offset:54272
	ds_read_b128 v[234:237], v152 offset:55296
	ds_read_b128 v[238:241], v152 offset:56320
	global_load_lds_dwordx4 v[148:149], off
	s_add_i32 m0, s10, 0x2000
	s_add_u32 s8, s8, 0x40080
	v_lshl_add_u64 v[148:149], v[168:169], 0, s[50:51]
	s_addc_u32 s9, s9, 0
	s_add_i32 s10, s25, s12
	global_load_lds_dwordx4 v[148:149], off
	v_lshl_add_u64 v[148:149], s[8:9], 0, v[162:163]
	s_mov_b32 m0, s10
	s_nop 0
	global_load_lds_dwordx4 v[148:149], off
	v_lshl_add_u64 v[148:149], s[8:9], 0, v[130:131]
	s_add_i32 m0, s10, 0x2000
	s_nop 0
	global_load_lds_dwordx4 v[148:149], off
	v_lshl_add_u64 v[148:149], v[170:171], 0, s[50:51]
	s_mov_b32 m0, s17
	s_nop 0
	global_load_lds_dwordx4 v[148:149], off
	v_lshl_add_u64 v[148:149], v[172:173], 0, s[50:51]
	s_mov_b32 m0, s18
	s_nop 0
	global_load_lds_dwordx4 v[148:149], off
	s_waitcnt vmcnt(8)
	s_waitcnt lgkmcnt(0)
	s_barrier
	s_setprio 1
	s_waitcnt lgkmcnt(0)
	v_mfma_f32_16x16x32_bf16 v[62:65], v[140:143], v[210:213], v[62:65]
	v_mfma_f32_16x16x32_bf16 v[58:61], v[154:157], v[210:213], v[58:61]
	v_mfma_f32_16x16x32_bf16 v[46:49], v[140:143], v[218:221], v[46:49]
	v_mfma_f32_16x16x32_bf16 v[42:45], v[154:157], v[218:221], v[42:45]
	v_mfma_f32_16x16x32_bf16 v[30:33], v[140:143], v[226:229], v[30:33]
	v_mfma_f32_16x16x32_bf16 v[26:29], v[154:157], v[226:229], v[26:29]
	v_mfma_f32_16x16x32_bf16 v[14:17], v[140:143], v[234:237], v[14:17]
	v_mfma_f32_16x16x32_bf16 v[10:13], v[154:157], v[234:237], v[10:13]
	v_mfma_f32_16x16x32_bf16 v[62:65], v[144:147], v[214:217], v[62:65]
	v_mfma_f32_16x16x32_bf16 v[58:61], v[158:161], v[214:217], v[58:61]
	v_mfma_f32_16x16x32_bf16 v[46:49], v[144:147], v[222:225], v[46:49]
	v_mfma_f32_16x16x32_bf16 v[42:45], v[158:161], v[222:225], v[42:45]
	v_mfma_f32_16x16x32_bf16 v[30:33], v[144:147], v[230:233], v[30:33]
	v_mfma_f32_16x16x32_bf16 v[26:29], v[158:161], v[230:233], v[26:29]
	v_mfma_f32_16x16x32_bf16 v[14:17], v[144:147], v[238:241], v[14:17]
	v_mfma_f32_16x16x32_bf16 v[10:13], v[158:161], v[238:241], v[10:13]
	v_mfma_f32_16x16x32_bf16 v[54:57], v[178:181], v[210:213], v[54:57]
	v_mfma_f32_16x16x32_bf16 v[50:53], v[186:189], v[210:213], v[50:53]
	v_mfma_f32_16x16x32_bf16 v[38:41], v[178:181], v[218:221], v[38:41]
	v_mfma_f32_16x16x32_bf16 v[34:37], v[186:189], v[218:221], v[34:37]
	v_mfma_f32_16x16x32_bf16 v[22:25], v[178:181], v[226:229], v[22:25]
	v_mfma_f32_16x16x32_bf16 v[18:21], v[186:189], v[226:229], v[18:21]
	v_mfma_f32_16x16x32_bf16 v[6:9], v[178:181], v[234:237], v[6:9]
	v_mfma_f32_16x16x32_bf16 v[2:5], v[186:189], v[234:237], v[2:5]
	v_mfma_f32_16x16x32_bf16 v[54:57], v[182:185], v[214:217], v[54:57]
	v_mfma_f32_16x16x32_bf16 v[50:53], v[190:193], v[214:217], v[50:53]
	v_mfma_f32_16x16x32_bf16 v[38:41], v[182:185], v[222:225], v[38:41]
	v_mfma_f32_16x16x32_bf16 v[34:37], v[190:193], v[222:225], v[34:37]
	v_mfma_f32_16x16x32_bf16 v[22:25], v[182:185], v[230:233], v[22:25]
	v_mfma_f32_16x16x32_bf16 v[18:21], v[190:193], v[230:233], v[18:21]
	v_mfma_f32_16x16x32_bf16 v[6:9], v[182:185], v[238:241], v[6:9]
	v_mfma_f32_16x16x32_bf16 v[2:5], v[190:193], v[238:241], v[2:5]
	s_setprio 0
	s_barrier
	s_add_i32 s23, s23, 2
	s_add_u32 s4, s4, 0x100
	s_addc_u32 s5, s5, 0
	s_add_u32 s21, s21, 0x100
	s_addc_u32 s22, s22, 0
	s_cmp_gt_u32 s23, 13
	s_cbranch_scc0 .LBB0_1693
	s_and_b64 vcc, exec, s[42:43]
	s_cbranch_vccz .LBB0_1696
	s_barrier
; __device__ __forceinline__ float sigmoidf_(float x) { return __builtin_amdgcn_rcpf(1.f + __expf(-x)); }
;     __device__ __forceinline__ void operator()(const pg8::f32x4 (&acc)[2][2][4][2], const pg8::Unit& u, int wr, int wc, int fr, int fq) const {
;         const int row0 = u.pm * 256 + wr * 64 + fr, col0 = u.pn * 256 + wc * 32 + 8 * fq;
; #pragma unroll
;         for (int ai = 0; ai < 2; ++ai)
; #pragma unroll
;             for (int m = 0; m < 4; ++m) {
;                 const size_t r = (size_t)(row0 + ai * 128 + m * 16);
; #pragma unroll
;                 for (int bj = 0; bj < 2; ++bj) {
;                     const int col = col0 + bj * 128;
;                     const u32x4v gw = *(const u32x4v*)(mg + r * PP + (size_t)u.z * D + col);
;                     float gt[8];
;                     gt[0] = __builtin_bit_cast(float, gw.x << 16); gt[1] = __builtin_bit_cast(float, gw.x & 0xffff0000u); gt[2] = __builtin_bit_cast(float, gw.y << 16); gt[3] = __builtin_bit_cast(float, gw.y & 0xffff0000u);
;                     gt[4] = __builtin_bit_cast(float, gw.z << 16); gt[5] = __builtin_bit_cast(float, gw.z & 0xffff0000u); gt[6] = __builtin_bit_cast(float, gw.w << 16); gt[7] = __builtin_bit_cast(float, gw.w & 0xffff0000u);
;                     pg8::f32x4 v0 = acc[ai][bj][m][0], v1 = acc[ai][bj][m][1];
; #pragma unroll
;                     for (int e = 0; e < 4; ++e) { v0[e] *= sigmoidf_(gt[e]); v1[e] *= sigmoidf_(gt[4 + e]); }
.LBB0_1696:
	v_lshl_or_b32 v140, s7, 8, v151
	v_lshl_add_u32 v142, s20, 8, v1
	v_readlane_b32 s10, v252, 8
	v_readlane_b32 s11, v252, 9
	v_lshlrev_b32_e32 v153, 1, v140
	v_mad_u32_u24 v153, v142, s27, v153
	v_lshlrev_b32_e32 v149, 12, v142
	v_lshl_add_u32 v149, v140, 1, v149
	s_lshl_b32 s4, s6, 12
	s_add_u32 s10, s10, s4
	s_addc_u32 s11, s11, 0
	s_cmp_gt_i32 s6, 1
	s_cbranch_scc1 .Lemx_final
	s_add_u32 s4, s10, 0x0
	s_addc_u32 s5, s11, 0
	global_load_dwordx4 v[178:181], v153, s[4:5]
	global_load_dwordx4 v[182:185], v153, s[4:5] offset:256
	s_add_u32 s8, s10, 0x1000
	s_addc_u32 s9, s11, 0
	global_load_dwordx4 v[226:229], v153, s[8:9]
	global_load_dwordx4 v[230:233], v153, s[8:9] offset:256
	s_add_u32 s38, s10, 0x76000
	s_addc_u32 s39, s11, 0
	global_load_dwordx4 v[186:189], v153, s[38:39]
	global_load_dwordx4 v[190:193], v153, s[38:39] offset:256
	s_add_u32 s60, s10, 0x77000
	s_addc_u32 s61, s11, 0
	global_load_dwordx4 v[234:237], v153, s[60:61]
	global_load_dwordx4 v[238:241], v153, s[60:61] offset:256
	s_waitcnt vmcnt(0)
	s_add_u32 s62, s10, 0xec000
	s_addc_u32 s63, s11, 0
	global_load_dwordx4 v[210:213], v153, s[62:63]
	global_load_dwordx4 v[214:217], v153, s[62:63] offset:256
	s_add_u32 s64, s10, 0xed000
	s_addc_u32 s65, s11, 0
	global_load_dwordx4 v[154:157], v153, s[64:65]
	global_load_dwordx4 v[158:161], v153, s[64:65] offset:256
	s_add_u32 s4, s10, 0x162000
	s_addc_u32 s5, s11, 0
	global_load_dwordx4 v[218:221], v153, s[4:5]
	global_load_dwordx4 v[222:225], v153, s[4:5] offset:256
	s_add_u32 s8, s10, 0x163000
	s_addc_u32 s9, s11, 0
	global_load_dwordx4 v[168:171], v153, s[8:9]
	global_load_dwordx4 v[140:143], v153, s[8:9] offset:256
	v_lshlrev_b32_e32 v194, 16, v178
	v_and_b32_e32 v195, 0xffff0000, v178
	v_lshlrev_b32_e32 v172, 16, v179
	v_and_b32_e32 v173, 0xffff0000, v179
	v_lshlrev_b32_e32 v178, 16, v180
	v_and_b32_e32 v179, 0xffff0000, v180
	v_lshlrev_b32_e32 v180, 16, v181
	v_and_b32_e32 v181, 0xffff0000, v181
	v_mul_f32_e32 v194, 0xbfb8aa3b, v194
	v_mul_f32_e32 v195, 0xbfb8aa3b, v195
	v_mul_f32_e32 v172, 0xbfb8aa3b, v172
	v_mul_f32_e32 v173, 0xbfb8aa3b, v173
	v_mul_f32_e32 v178, 0xbfb8aa3b, v178
	v_mul_f32_e32 v179, 0xbfb8aa3b, v179
	v_mul_f32_e32 v180, 0xbfb8aa3b, v180
	v_mul_f32_e32 v181, 0xbfb8aa3b, v181
	v_min_f32_e32 v194, 0x42700000, v194
	v_min_f32_e32 v195, 0x42700000, v195
	v_min_f32_e32 v172, 0x42700000, v172
	v_min_f32_e32 v173, 0x42700000, v173
	v_min_f32_e32 v178, 0x42700000, v178
	v_min_f32_e32 v179, 0x42700000, v179
	v_min_f32_e32 v180, 0x42700000, v180
	v_min_f32_e32 v181, 0x42700000, v181
	v_exp_f32_e32 v194, v194
	v_exp_f32_e32 v195, v195
	v_exp_f32_e32 v172, v172
	v_exp_f32_e32 v173, v173
	v_exp_f32_e32 v178, v178
	v_exp_f32_e32 v179, v179
	v_exp_f32_e32 v180, v180
	v_exp_f32_e32 v181, v181
	v_add_f32_e32 v194, 1.0, v194
	v_add_f32_e32 v195, 1.0, v195
	v_add_f32_e32 v172, 1.0, v172
	v_add_f32_e32 v173, 1.0, v173
	v_add_f32_e32 v178, 1.0, v178
	v_add_f32_e32 v179, 1.0, v179
	v_add_f32_e32 v180, 1.0, v180
	v_add_f32_e32 v181, 1.0, v181
	v_lshlrev_b32_e32 v144, 16, v226
	v_and_b32_e32 v145, 0xffff0000, v226
	v_lshlrev_b32_e32 v146, 16, v227
	v_and_b32_e32 v147, 0xffff0000, v227
	v_lshlrev_b32_e32 v226, 16, v228
	v_and_b32_e32 v227, 0xffff0000, v228
	v_lshlrev_b32_e32 v228, 16, v229
	v_and_b32_e32 v229, 0xffff0000, v229
	v_mul_f32_e32 v144, 0xbfb8aa3b, v144
	v_mul_f32_e32 v145, 0xbfb8aa3b, v145
	v_mul_f32_e32 v146, 0xbfb8aa3b, v146
	v_mul_f32_e32 v147, 0xbfb8aa3b, v147
	v_mul_f32_e32 v226, 0xbfb8aa3b, v226
	v_mul_f32_e32 v227, 0xbfb8aa3b, v227
	v_mul_f32_e32 v228, 0xbfb8aa3b, v228
	v_mul_f32_e32 v229, 0xbfb8aa3b, v229
	v_min_f32_e32 v144, 0x42700000, v144
	v_min_f32_e32 v145, 0x42700000, v145
	v_min_f32_e32 v146, 0x42700000, v146
	v_min_f32_e32 v147, 0x42700000, v147
	v_min_f32_e32 v226, 0x42700000, v226
	v_min_f32_e32 v227, 0x42700000, v227
	v_min_f32_e32 v228, 0x42700000, v228
	v_min_f32_e32 v229, 0x42700000, v229
	v_exp_f32_e32 v144, v144
	v_exp_f32_e32 v145, v145
	v_exp_f32_e32 v146, v146
	v_exp_f32_e32 v147, v147
	v_exp_f32_e32 v226, v226
	v_exp_f32_e32 v227, v227
	v_exp_f32_e32 v228, v228
	v_exp_f32_e32 v229, v229
	v_add_f32_e32 v144, 1.0, v144
	v_add_f32_e32 v145, 1.0, v145
	v_add_f32_e32 v146, 1.0, v146
	v_add_f32_e32 v147, 1.0, v147
	v_add_f32_e32 v226, 1.0, v226
	v_add_f32_e32 v227, 1.0, v227
	v_add_f32_e32 v228, 1.0, v228
	v_add_f32_e32 v229, 1.0, v229
	v_rcp_f32_e32 v194, v194
	v_rcp_f32_e32 v195, v195
	v_rcp_f32_e32 v172, v172
	v_rcp_f32_e32 v173, v173
	v_rcp_f32_e32 v178, v178
	v_rcp_f32_e32 v179, v179
	v_rcp_f32_e32 v180, v180
	v_rcp_f32_e32 v181, v181
	v_mul_f32_e32 v194, v194, v144
	v_mul_f32_e32 v195, v195, v145
	v_mul_f32_e32 v172, v172, v146
	v_mul_f32_e32 v173, v173, v147
	v_mul_f32_e32 v178, v178, v226
	v_mul_f32_e32 v179, v179, v227
	v_mul_f32_e32 v180, v180, v228
	v_mul_f32_e32 v181, v181, v229
	v_pk_mul_f32 v[126:127], v[126:127], v[194:195]
	v_pk_mul_f32 v[128:129], v[128:129], v[172:173]
	v_pk_mul_f32 v[122:123], v[122:123], v[178:179]
	v_pk_mul_f32 v[124:125], v[124:125], v[180:181]
	v_lshlrev_b32_e32 v194, 16, v182
	v_and_b32_e32 v195, 0xffff0000, v182
	v_lshlrev_b32_e32 v172, 16, v183
	v_and_b32_e32 v173, 0xffff0000, v183
	v_lshlrev_b32_e32 v182, 16, v184
	v_and_b32_e32 v183, 0xffff0000, v184
	v_lshlrev_b32_e32 v184, 16, v185
	v_and_b32_e32 v185, 0xffff0000, v185
	v_mul_f32_e32 v194, 0xbfb8aa3b, v194
	v_mul_f32_e32 v195, 0xbfb8aa3b, v195
	v_mul_f32_e32 v172, 0xbfb8aa3b, v172
	v_mul_f32_e32 v173, 0xbfb8aa3b, v173
	v_mul_f32_e32 v182, 0xbfb8aa3b, v182
	v_mul_f32_e32 v183, 0xbfb8aa3b, v183
	v_mul_f32_e32 v184, 0xbfb8aa3b, v184
	v_mul_f32_e32 v185, 0xbfb8aa3b, v185
; __device__ __forceinline__ float sigmoidf_(float x) { return __builtin_amdgcn_rcpf(1.f + __expf(-x)); }
;     __device__ __forceinline__ void operator()(const pg8::f32x4 (&acc)[2][2][4][2], const pg8::Unit& u, int wr, int wc, int fr, int fq) const {
;     ...
;                     const u32x4v gw = *(const u32x4v*)(mg + r * PP + (size_t)u.z * D + col);
;                     float gt[8];
;                     gt[0] = __builtin_bit_cast(float, gw.x << 16); gt[1] = __builtin_bit_cast(float, gw.x & 0xffff0000u); gt[2] = __builtin_bit_cast(float, gw.y << 16); gt[3] = __builtin_bit_cast(float, gw.y & 0xffff0000u);
;                     gt[4] = __builtin_bit_cast(float, gw.z << 16); gt[5] = __builtin_bit_cast(float, gw.z & 0xffff0000u); gt[6] = __builtin_bit_cast(float, gw.w << 16); gt[7] = __builtin_bit_cast(float, gw.w & 0xffff0000u);
;                     pg8::f32x4 v0 = acc[ai][bj][m][0], v1 = acc[ai][bj][m][1];
; #pragma unroll
;                     for (int e = 0; e < 4; ++e) { v0[e] *= sigmoidf_(gt[e]); v1[e] *= sigmoidf_(gt[4 + e]); }
	v_min_f32_e32 v194, 0x42700000, v194
	v_min_f32_e32 v195, 0x42700000, v195
	v_min_f32_e32 v172, 0x42700000, v172
	v_min_f32_e32 v173, 0x42700000, v173
	v_min_f32_e32 v182, 0x42700000, v182
	v_min_f32_e32 v183, 0x42700000, v183
	v_min_f32_e32 v184, 0x42700000, v184
	v_min_f32_e32 v185, 0x42700000, v185
	v_exp_f32_e32 v194, v194
	v_exp_f32_e32 v195, v195
	v_exp_f32_e32 v172, v172
	v_exp_f32_e32 v173, v173
	v_exp_f32_e32 v182, v182
	v_exp_f32_e32 v183, v183
	v_exp_f32_e32 v184, v184
	v_exp_f32_e32 v185, v185
	v_add_f32_e32 v194, 1.0, v194
	v_add_f32_e32 v195, 1.0, v195
	v_add_f32_e32 v172, 1.0, v172
	v_add_f32_e32 v173, 1.0, v173
	v_add_f32_e32 v182, 1.0, v182
	v_add_f32_e32 v183, 1.0, v183
	v_add_f32_e32 v184, 1.0, v184
	v_add_f32_e32 v185, 1.0, v185
	v_lshlrev_b32_e32 v144, 16, v230
	v_and_b32_e32 v145, 0xffff0000, v230
	v_lshlrev_b32_e32 v146, 16, v231
	v_and_b32_e32 v147, 0xffff0000, v231
	v_lshlrev_b32_e32 v230, 16, v232
	v_and_b32_e32 v231, 0xffff0000, v232
	v_lshlrev_b32_e32 v232, 16, v233
	v_and_b32_e32 v233, 0xffff0000, v233
	v_mul_f32_e32 v144, 0xbfb8aa3b, v144
	v_mul_f32_e32 v145, 0xbfb8aa3b, v145
	v_mul_f32_e32 v146, 0xbfb8aa3b, v146
	v_mul_f32_e32 v147, 0xbfb8aa3b, v147
	v_mul_f32_e32 v230, 0xbfb8aa3b, v230
	v_mul_f32_e32 v231, 0xbfb8aa3b, v231
	v_mul_f32_e32 v232, 0xbfb8aa3b, v232
	v_mul_f32_e32 v233, 0xbfb8aa3b, v233
	v_min_f32_e32 v144, 0x42700000, v144
	v_min_f32_e32 v145, 0x42700000, v145
	v_min_f32_e32 v146, 0x42700000, v146
	v_min_f32_e32 v147, 0x42700000, v147
	v_min_f32_e32 v230, 0x42700000, v230
	v_min_f32_e32 v231, 0x42700000, v231
	v_min_f32_e32 v232, 0x42700000, v232
	v_min_f32_e32 v233, 0x42700000, v233
	v_exp_f32_e32 v144, v144
	v_exp_f32_e32 v145, v145
	v_exp_f32_e32 v146, v146
	v_exp_f32_e32 v147, v147
	v_exp_f32_e32 v230, v230
	v_exp_f32_e32 v231, v231
	v_exp_f32_e32 v232, v232
	v_exp_f32_e32 v233, v233
	v_add_f32_e32 v144, 1.0, v144
	v_add_f32_e32 v145, 1.0, v145
	v_add_f32_e32 v146, 1.0, v146
	v_add_f32_e32 v147, 1.0, v147
	v_add_f32_e32 v230, 1.0, v230
	v_add_f32_e32 v231, 1.0, v231
	v_add_f32_e32 v232, 1.0, v232
	v_add_f32_e32 v233, 1.0, v233
	v_rcp_f32_e32 v194, v194
	v_rcp_f32_e32 v195, v195
	v_rcp_f32_e32 v172, v172
	v_rcp_f32_e32 v173, v173
	v_rcp_f32_e32 v182, v182
	v_rcp_f32_e32 v183, v183
	v_rcp_f32_e32 v184, v184
	v_rcp_f32_e32 v185, v185
	v_mul_f32_e32 v194, v194, v144
	v_mul_f32_e32 v195, v195, v145
	v_mul_f32_e32 v172, v172, v146
	v_mul_f32_e32 v173, v173, v147
	v_mul_f32_e32 v182, v182, v230
	v_mul_f32_e32 v183, v183, v231
	v_mul_f32_e32 v184, v184, v232
	v_mul_f32_e32 v185, v185, v233
	v_pk_mul_f32 v[118:119], v[118:119], v[194:195]
	v_pk_mul_f32 v[120:121], v[120:121], v[172:173]
	v_pk_mul_f32 v[114:115], v[114:115], v[182:183]
	v_pk_mul_f32 v[116:117], v[116:117], v[184:185]
	v_lshlrev_b32_e32 v194, 16, v186
	v_and_b32_e32 v195, 0xffff0000, v186
	v_lshlrev_b32_e32 v172, 16, v187
	v_and_b32_e32 v173, 0xffff0000, v187
	v_lshlrev_b32_e32 v186, 16, v188
	v_and_b32_e32 v187, 0xffff0000, v188
	v_lshlrev_b32_e32 v188, 16, v189
	v_and_b32_e32 v189, 0xffff0000, v189
	v_mul_f32_e32 v194, 0xbfb8aa3b, v194
	v_mul_f32_e32 v195, 0xbfb8aa3b, v195
	v_mul_f32_e32 v172, 0xbfb8aa3b, v172
	v_mul_f32_e32 v173, 0xbfb8aa3b, v173
	v_mul_f32_e32 v186, 0xbfb8aa3b, v186
	v_mul_f32_e32 v187, 0xbfb8aa3b, v187
	v_mul_f32_e32 v188, 0xbfb8aa3b, v188
	v_mul_f32_e32 v189, 0xbfb8aa3b, v189
	v_min_f32_e32 v194, 0x42700000, v194
	v_min_f32_e32 v195, 0x42700000, v195
	v_min_f32_e32 v172, 0x42700000, v172
	v_min_f32_e32 v173, 0x42700000, v173
	v_min_f32_e32 v186, 0x42700000, v186
	v_min_f32_e32 v187, 0x42700000, v187
	v_min_f32_e32 v188, 0x42700000, v188
	v_min_f32_e32 v189, 0x42700000, v189
	v_exp_f32_e32 v194, v194
	v_exp_f32_e32 v195, v195
	v_exp_f32_e32 v172, v172
	v_exp_f32_e32 v173, v173
	v_exp_f32_e32 v186, v186
	v_exp_f32_e32 v187, v187
	v_exp_f32_e32 v188, v188
	v_exp_f32_e32 v189, v189
	v_add_f32_e32 v194, 1.0, v194
	v_add_f32_e32 v195, 1.0, v195
	v_add_f32_e32 v172, 1.0, v172
	v_add_f32_e32 v173, 1.0, v173
	v_add_f32_e32 v186, 1.0, v186
	v_add_f32_e32 v187, 1.0, v187
	v_add_f32_e32 v188, 1.0, v188
	v_add_f32_e32 v189, 1.0, v189
	v_lshlrev_b32_e32 v144, 16, v234
	v_and_b32_e32 v145, 0xffff0000, v234
	v_lshlrev_b32_e32 v146, 16, v235
	v_and_b32_e32 v147, 0xffff0000, v235
	v_lshlrev_b32_e32 v234, 16, v236
	v_and_b32_e32 v235, 0xffff0000, v236
	v_lshlrev_b32_e32 v236, 16, v237
	v_and_b32_e32 v237, 0xffff0000, v237
	v_mul_f32_e32 v144, 0xbfb8aa3b, v144
	v_mul_f32_e32 v145, 0xbfb8aa3b, v145
	v_mul_f32_e32 v146, 0xbfb8aa3b, v146
	v_mul_f32_e32 v147, 0xbfb8aa3b, v147
	v_mul_f32_e32 v234, 0xbfb8aa3b, v234
	v_mul_f32_e32 v235, 0xbfb8aa3b, v235
	v_mul_f32_e32 v236, 0xbfb8aa3b, v236
	v_mul_f32_e32 v237, 0xbfb8aa3b, v237
	v_min_f32_e32 v144, 0x42700000, v144
	v_min_f32_e32 v145, 0x42700000, v145
	v_min_f32_e32 v146, 0x42700000, v146
	v_min_f32_e32 v147, 0x42700000, v147
	v_min_f32_e32 v234, 0x42700000, v234
	v_min_f32_e32 v235, 0x42700000, v235
	v_min_f32_e32 v236, 0x42700000, v236
	v_min_f32_e32 v237, 0x42700000, v237
	v_exp_f32_e32 v144, v144
	v_exp_f32_e32 v145, v145
	v_exp_f32_e32 v146, v146
	v_exp_f32_e32 v147, v147
	v_exp_f32_e32 v234, v234
	v_exp_f32_e32 v235, v235
	v_exp_f32_e32 v236, v236
	v_exp_f32_e32 v237, v237
	v_add_f32_e32 v144, 1.0, v144
	v_add_f32_e32 v145, 1.0, v145
	v_add_f32_e32 v146, 1.0, v146
	v_add_f32_e32 v147, 1.0, v147
	v_add_f32_e32 v234, 1.0, v234
	v_add_f32_e32 v235, 1.0, v235
	v_add_f32_e32 v236, 1.0, v236
	v_add_f32_e32 v237, 1.0, v237
	v_rcp_f32_e32 v194, v194
	v_rcp_f32_e32 v195, v195
	v_rcp_f32_e32 v172, v172
	v_rcp_f32_e32 v173, v173
	v_rcp_f32_e32 v186, v186
	v_rcp_f32_e32 v187, v187
; __device__ __forceinline__ float sigmoidf_(float x) { return __builtin_amdgcn_rcpf(1.f + __expf(-x)); }
;     __device__ __forceinline__ void operator()(const pg8::f32x4 (&acc)[2][2][4][2], const pg8::Unit& u, int wr, int wc, int fr, int fq) const {
;     ...
;                     const u32x4v gw = *(const u32x4v*)(mg + r * PP + (size_t)u.z * D + col);
;                     float gt[8];
;                     gt[0] = __builtin_bit_cast(float, gw.x << 16); gt[1] = __builtin_bit_cast(float, gw.x & 0xffff0000u); gt[2] = __builtin_bit_cast(float, gw.y << 16); gt[3] = __builtin_bit_cast(float, gw.y & 0xffff0000u);
;                     gt[4] = __builtin_bit_cast(float, gw.z << 16); gt[5] = __builtin_bit_cast(float, gw.z & 0xffff0000u); gt[6] = __builtin_bit_cast(float, gw.w << 16); gt[7] = __builtin_bit_cast(float, gw.w & 0xffff0000u);
;                     pg8::f32x4 v0 = acc[ai][bj][m][0], v1 = acc[ai][bj][m][1];
; #pragma unroll
;                     for (int e = 0; e < 4; ++e) { v0[e] *= sigmoidf_(gt[e]); v1[e] *= sigmoidf_(gt[4 + e]); }
	v_rcp_f32_e32 v188, v188
	v_rcp_f32_e32 v189, v189
	v_mul_f32_e32 v194, v194, v144
	v_mul_f32_e32 v195, v195, v145
	v_mul_f32_e32 v172, v172, v146
	v_mul_f32_e32 v173, v173, v147
	v_mul_f32_e32 v186, v186, v234
	v_mul_f32_e32 v187, v187, v235
	v_mul_f32_e32 v188, v188, v236
	v_mul_f32_e32 v189, v189, v237
	v_pk_mul_f32 v[110:111], v[110:111], v[194:195]
	v_pk_mul_f32 v[112:113], v[112:113], v[172:173]
	v_pk_mul_f32 v[106:107], v[106:107], v[186:187]
	v_pk_mul_f32 v[108:109], v[108:109], v[188:189]
	v_lshlrev_b32_e32 v194, 16, v190
	v_and_b32_e32 v195, 0xffff0000, v190
	v_lshlrev_b32_e32 v172, 16, v191
	v_and_b32_e32 v173, 0xffff0000, v191
	v_lshlrev_b32_e32 v190, 16, v192
	v_and_b32_e32 v191, 0xffff0000, v192
	v_lshlrev_b32_e32 v192, 16, v193
	v_and_b32_e32 v193, 0xffff0000, v193
	v_mul_f32_e32 v194, 0xbfb8aa3b, v194
	v_mul_f32_e32 v195, 0xbfb8aa3b, v195
	v_mul_f32_e32 v172, 0xbfb8aa3b, v172
	v_mul_f32_e32 v173, 0xbfb8aa3b, v173
	v_mul_f32_e32 v190, 0xbfb8aa3b, v190
	v_mul_f32_e32 v191, 0xbfb8aa3b, v191
	v_mul_f32_e32 v192, 0xbfb8aa3b, v192
	v_mul_f32_e32 v193, 0xbfb8aa3b, v193
	v_min_f32_e32 v194, 0x42700000, v194
	v_min_f32_e32 v195, 0x42700000, v195
	v_min_f32_e32 v172, 0x42700000, v172
	v_min_f32_e32 v173, 0x42700000, v173
	v_min_f32_e32 v190, 0x42700000, v190
	v_min_f32_e32 v191, 0x42700000, v191
	v_min_f32_e32 v192, 0x42700000, v192
	v_min_f32_e32 v193, 0x42700000, v193
	v_exp_f32_e32 v194, v194
	v_exp_f32_e32 v195, v195
	v_exp_f32_e32 v172, v172
	v_exp_f32_e32 v173, v173
	v_exp_f32_e32 v190, v190
	v_exp_f32_e32 v191, v191
	v_exp_f32_e32 v192, v192
	v_exp_f32_e32 v193, v193
	v_add_f32_e32 v194, 1.0, v194
	v_add_f32_e32 v195, 1.0, v195
	v_add_f32_e32 v172, 1.0, v172
	v_add_f32_e32 v173, 1.0, v173
	v_add_f32_e32 v190, 1.0, v190
	v_add_f32_e32 v191, 1.0, v191
	v_add_f32_e32 v192, 1.0, v192
	v_add_f32_e32 v193, 1.0, v193
	v_lshlrev_b32_e32 v144, 16, v238
	v_and_b32_e32 v145, 0xffff0000, v238
	v_lshlrev_b32_e32 v146, 16, v239
	v_and_b32_e32 v147, 0xffff0000, v239
	v_lshlrev_b32_e32 v238, 16, v240
	v_and_b32_e32 v239, 0xffff0000, v240
	v_lshlrev_b32_e32 v240, 16, v241
	v_and_b32_e32 v241, 0xffff0000, v241
	v_mul_f32_e32 v144, 0xbfb8aa3b, v144
	v_mul_f32_e32 v145, 0xbfb8aa3b, v145
	v_mul_f32_e32 v146, 0xbfb8aa3b, v146
	v_mul_f32_e32 v147, 0xbfb8aa3b, v147
	v_mul_f32_e32 v238, 0xbfb8aa3b, v238
	v_mul_f32_e32 v239, 0xbfb8aa3b, v239
	v_mul_f32_e32 v240, 0xbfb8aa3b, v240
	v_mul_f32_e32 v241, 0xbfb8aa3b, v241
	v_min_f32_e32 v144, 0x42700000, v144
	v_min_f32_e32 v145, 0x42700000, v145
	v_min_f32_e32 v146, 0x42700000, v146
	v_min_f32_e32 v147, 0x42700000, v147
	v_min_f32_e32 v238, 0x42700000, v238
	v_min_f32_e32 v239, 0x42700000, v239
	v_min_f32_e32 v240, 0x42700000, v240
	v_min_f32_e32 v241, 0x42700000, v241
	v_exp_f32_e32 v144, v144
	v_exp_f32_e32 v145, v145
	v_exp_f32_e32 v146, v146
	v_exp_f32_e32 v147, v147
	v_exp_f32_e32 v238, v238
	v_exp_f32_e32 v239, v239
	v_exp_f32_e32 v240, v240
	v_exp_f32_e32 v241, v241
	v_add_f32_e32 v144, 1.0, v144
	v_add_f32_e32 v145, 1.0, v145
	v_add_f32_e32 v146, 1.0, v146
	v_add_f32_e32 v147, 1.0, v147
	v_add_f32_e32 v238, 1.0, v238
	v_add_f32_e32 v239, 1.0, v239
	v_add_f32_e32 v240, 1.0, v240
	v_add_f32_e32 v241, 1.0, v241
	v_rcp_f32_e32 v194, v194
	v_rcp_f32_e32 v195, v195
	v_rcp_f32_e32 v172, v172
	v_rcp_f32_e32 v173, v173
	v_rcp_f32_e32 v190, v190
	v_rcp_f32_e32 v191, v191
	v_rcp_f32_e32 v192, v192
	v_rcp_f32_e32 v193, v193
	v_mul_f32_e32 v194, v194, v144
	v_mul_f32_e32 v195, v195, v145
	v_mul_f32_e32 v172, v172, v146
	v_mul_f32_e32 v173, v173, v147
	v_mul_f32_e32 v190, v190, v238
	v_mul_f32_e32 v191, v191, v239
	v_mul_f32_e32 v192, v192, v240
	v_mul_f32_e32 v193, v193, v241
	v_pk_mul_f32 v[102:103], v[102:103], v[194:195]
	v_pk_mul_f32 v[104:105], v[104:105], v[172:173]
	v_pk_mul_f32 v[98:99], v[98:99], v[190:191]
	v_pk_mul_f32 v[100:101], v[100:101], v[192:193]
	s_waitcnt vmcnt(0)
	s_add_u32 s38, s10, 0x3b0000
	s_addc_u32 s39, s11, 0
	global_load_dwordx4 v[178:181], v153, s[38:39]
	global_load_dwordx4 v[182:185], v153, s[38:39] offset:256
	s_add_u32 s60, s10, 0x3b1000
	s_addc_u32 s61, s11, 0
	global_load_dwordx4 v[226:229], v153, s[60:61]
	global_load_dwordx4 v[230:233], v153, s[60:61] offset:256
	s_add_u32 s62, s10, 0x426000
	s_addc_u32 s63, s11, 0
	global_load_dwordx4 v[186:189], v153, s[62:63]
	global_load_dwordx4 v[190:193], v153, s[62:63] offset:256
	s_add_u32 s64, s10, 0x427000
	s_addc_u32 s65, s11, 0
	global_load_dwordx4 v[234:237], v153, s[64:65]
	global_load_dwordx4 v[238:241], v153, s[64:65] offset:256
	v_lshlrev_b32_e32 v194, 16, v210
	v_and_b32_e32 v195, 0xffff0000, v210
	v_lshlrev_b32_e32 v172, 16, v211
	v_and_b32_e32 v173, 0xffff0000, v211
	v_lshlrev_b32_e32 v210, 16, v212
	v_and_b32_e32 v211, 0xffff0000, v212
	v_lshlrev_b32_e32 v212, 16, v213
	v_and_b32_e32 v213, 0xffff0000, v213
	v_mul_f32_e32 v194, 0xbfb8aa3b, v194
	v_mul_f32_e32 v195, 0xbfb8aa3b, v195
	v_mul_f32_e32 v172, 0xbfb8aa3b, v172
	v_mul_f32_e32 v173, 0xbfb8aa3b, v173
	v_mul_f32_e32 v210, 0xbfb8aa3b, v210
	v_mul_f32_e32 v211, 0xbfb8aa3b, v211
	v_mul_f32_e32 v212, 0xbfb8aa3b, v212
	v_mul_f32_e32 v213, 0xbfb8aa3b, v213
	v_min_f32_e32 v194, 0x42700000, v194
	v_min_f32_e32 v195, 0x42700000, v195
	v_min_f32_e32 v172, 0x42700000, v172
	v_min_f32_e32 v173, 0x42700000, v173
	v_min_f32_e32 v210, 0x42700000, v210
	v_min_f32_e32 v211, 0x42700000, v211
	v_min_f32_e32 v212, 0x42700000, v212
	v_min_f32_e32 v213, 0x42700000, v213
	v_exp_f32_e32 v194, v194
	v_exp_f32_e32 v195, v195
	v_exp_f32_e32 v172, v172
	v_exp_f32_e32 v173, v173
	v_exp_f32_e32 v210, v210
	v_exp_f32_e32 v211, v211
	v_exp_f32_e32 v212, v212
	v_exp_f32_e32 v213, v213
; __device__ __forceinline__ float sigmoidf_(float x) { return __builtin_amdgcn_rcpf(1.f + __expf(-x)); }
;     __device__ __forceinline__ void operator()(const pg8::f32x4 (&acc)[2][2][4][2], const pg8::Unit& u, int wr, int wc, int fr, int fq) const {
;     ...
;                     const u32x4v gw = *(const u32x4v*)(mg + r * PP + (size_t)u.z * D + col);
;                     float gt[8];
;                     gt[0] = __builtin_bit_cast(float, gw.x << 16); gt[1] = __builtin_bit_cast(float, gw.x & 0xffff0000u); gt[2] = __builtin_bit_cast(float, gw.y << 16); gt[3] = __builtin_bit_cast(float, gw.y & 0xffff0000u);
;                     gt[4] = __builtin_bit_cast(float, gw.z << 16); gt[5] = __builtin_bit_cast(float, gw.z & 0xffff0000u); gt[6] = __builtin_bit_cast(float, gw.w << 16); gt[7] = __builtin_bit_cast(float, gw.w & 0xffff0000u);
;                     pg8::f32x4 v0 = acc[ai][bj][m][0], v1 = acc[ai][bj][m][1];
; #pragma unroll
;                     for (int e = 0; e < 4; ++e) { v0[e] *= sigmoidf_(gt[e]); v1[e] *= sigmoidf_(gt[4 + e]); }
	v_add_f32_e32 v194, 1.0, v194
	v_add_f32_e32 v195, 1.0, v195
	v_add_f32_e32 v172, 1.0, v172
	v_add_f32_e32 v173, 1.0, v173
	v_add_f32_e32 v210, 1.0, v210
	v_add_f32_e32 v211, 1.0, v211
	v_add_f32_e32 v212, 1.0, v212
	v_add_f32_e32 v213, 1.0, v213
	v_lshlrev_b32_e32 v144, 16, v154
	v_and_b32_e32 v145, 0xffff0000, v154
	v_lshlrev_b32_e32 v146, 16, v155
	v_and_b32_e32 v147, 0xffff0000, v155
	v_lshlrev_b32_e32 v154, 16, v156
	v_and_b32_e32 v155, 0xffff0000, v156
	v_lshlrev_b32_e32 v156, 16, v157
	v_and_b32_e32 v157, 0xffff0000, v157
	v_mul_f32_e32 v144, 0xbfb8aa3b, v144
	v_mul_f32_e32 v145, 0xbfb8aa3b, v145
	v_mul_f32_e32 v146, 0xbfb8aa3b, v146
	v_mul_f32_e32 v147, 0xbfb8aa3b, v147
	v_mul_f32_e32 v154, 0xbfb8aa3b, v154
	v_mul_f32_e32 v155, 0xbfb8aa3b, v155
	v_mul_f32_e32 v156, 0xbfb8aa3b, v156
	v_mul_f32_e32 v157, 0xbfb8aa3b, v157
	v_min_f32_e32 v144, 0x42700000, v144
	v_min_f32_e32 v145, 0x42700000, v145
	v_min_f32_e32 v146, 0x42700000, v146
	v_min_f32_e32 v147, 0x42700000, v147
	v_min_f32_e32 v154, 0x42700000, v154
	v_min_f32_e32 v155, 0x42700000, v155
	v_min_f32_e32 v156, 0x42700000, v156
	v_min_f32_e32 v157, 0x42700000, v157
	v_exp_f32_e32 v144, v144
	v_exp_f32_e32 v145, v145
	v_exp_f32_e32 v146, v146
	v_exp_f32_e32 v147, v147
	v_exp_f32_e32 v154, v154
	v_exp_f32_e32 v155, v155
	v_exp_f32_e32 v156, v156
	v_exp_f32_e32 v157, v157
	v_add_f32_e32 v144, 1.0, v144
	v_add_f32_e32 v145, 1.0, v145
	v_add_f32_e32 v146, 1.0, v146
	v_add_f32_e32 v147, 1.0, v147
	v_add_f32_e32 v154, 1.0, v154
	v_add_f32_e32 v155, 1.0, v155
	v_add_f32_e32 v156, 1.0, v156
	v_add_f32_e32 v157, 1.0, v157
	v_rcp_f32_e32 v194, v194
	v_rcp_f32_e32 v195, v195
	v_rcp_f32_e32 v172, v172
	v_rcp_f32_e32 v173, v173
	v_rcp_f32_e32 v210, v210
	v_rcp_f32_e32 v211, v211
	v_rcp_f32_e32 v212, v212
	v_rcp_f32_e32 v213, v213
	v_mul_f32_e32 v194, v194, v144
	v_mul_f32_e32 v195, v195, v145
	v_mul_f32_e32 v172, v172, v146
	v_mul_f32_e32 v173, v173, v147
	v_mul_f32_e32 v210, v210, v154
	v_mul_f32_e32 v211, v211, v155
	v_mul_f32_e32 v212, v212, v156
	v_mul_f32_e32 v213, v213, v157
	v_pk_mul_f32 v[94:95], v[94:95], v[194:195]
	v_pk_mul_f32 v[96:97], v[96:97], v[172:173]
	v_pk_mul_f32 v[90:91], v[90:91], v[210:211]
	v_pk_mul_f32 v[92:93], v[92:93], v[212:213]
	v_lshlrev_b32_e32 v194, 16, v214
	v_and_b32_e32 v195, 0xffff0000, v214
	v_lshlrev_b32_e32 v172, 16, v215
	v_and_b32_e32 v173, 0xffff0000, v215
	v_lshlrev_b32_e32 v214, 16, v216
	v_and_b32_e32 v215, 0xffff0000, v216
	v_lshlrev_b32_e32 v216, 16, v217
	v_and_b32_e32 v217, 0xffff0000, v217
	v_mul_f32_e32 v194, 0xbfb8aa3b, v194
	v_mul_f32_e32 v195, 0xbfb8aa3b, v195
	v_mul_f32_e32 v172, 0xbfb8aa3b, v172
	v_mul_f32_e32 v173, 0xbfb8aa3b, v173
	v_mul_f32_e32 v214, 0xbfb8aa3b, v214
	v_mul_f32_e32 v215, 0xbfb8aa3b, v215
	v_mul_f32_e32 v216, 0xbfb8aa3b, v216
	v_mul_f32_e32 v217, 0xbfb8aa3b, v217
	v_min_f32_e32 v194, 0x42700000, v194
	v_min_f32_e32 v195, 0x42700000, v195
	v_min_f32_e32 v172, 0x42700000, v172
	v_min_f32_e32 v173, 0x42700000, v173
	v_min_f32_e32 v214, 0x42700000, v214
	v_min_f32_e32 v215, 0x42700000, v215
	v_min_f32_e32 v216, 0x42700000, v216
	v_min_f32_e32 v217, 0x42700000, v217
	v_exp_f32_e32 v194, v194
	v_exp_f32_e32 v195, v195
	v_exp_f32_e32 v172, v172
	v_exp_f32_e32 v173, v173
	v_exp_f32_e32 v214, v214
	v_exp_f32_e32 v215, v215
	v_exp_f32_e32 v216, v216
	v_exp_f32_e32 v217, v217
	v_add_f32_e32 v194, 1.0, v194
	v_add_f32_e32 v195, 1.0, v195
	v_add_f32_e32 v172, 1.0, v172
	v_add_f32_e32 v173, 1.0, v173
	v_add_f32_e32 v214, 1.0, v214
	v_add_f32_e32 v215, 1.0, v215
	v_add_f32_e32 v216, 1.0, v216
	v_add_f32_e32 v217, 1.0, v217
	v_lshlrev_b32_e32 v144, 16, v158
	v_and_b32_e32 v145, 0xffff0000, v158
	v_lshlrev_b32_e32 v146, 16, v159
	v_and_b32_e32 v147, 0xffff0000, v159
	v_lshlrev_b32_e32 v158, 16, v160
	v_and_b32_e32 v159, 0xffff0000, v160
	v_lshlrev_b32_e32 v160, 16, v161
	v_and_b32_e32 v161, 0xffff0000, v161
	v_mul_f32_e32 v144, 0xbfb8aa3b, v144
	v_mul_f32_e32 v145, 0xbfb8aa3b, v145
	v_mul_f32_e32 v146, 0xbfb8aa3b, v146
	v_mul_f32_e32 v147, 0xbfb8aa3b, v147
	v_mul_f32_e32 v158, 0xbfb8aa3b, v158
	v_mul_f32_e32 v159, 0xbfb8aa3b, v159
	v_mul_f32_e32 v160, 0xbfb8aa3b, v160
	v_mul_f32_e32 v161, 0xbfb8aa3b, v161
	v_min_f32_e32 v144, 0x42700000, v144
	v_min_f32_e32 v145, 0x42700000, v145
	v_min_f32_e32 v146, 0x42700000, v146
	v_min_f32_e32 v147, 0x42700000, v147
	v_min_f32_e32 v158, 0x42700000, v158
	v_min_f32_e32 v159, 0x42700000, v159
	v_min_f32_e32 v160, 0x42700000, v160
	v_min_f32_e32 v161, 0x42700000, v161
	v_exp_f32_e32 v144, v144
	v_exp_f32_e32 v145, v145
	v_exp_f32_e32 v146, v146
	v_exp_f32_e32 v147, v147
	v_exp_f32_e32 v158, v158
	v_exp_f32_e32 v159, v159
	v_exp_f32_e32 v160, v160
	v_exp_f32_e32 v161, v161
	v_add_f32_e32 v144, 1.0, v144
	v_add_f32_e32 v145, 1.0, v145
	v_add_f32_e32 v146, 1.0, v146
	v_add_f32_e32 v147, 1.0, v147
	v_add_f32_e32 v158, 1.0, v158
	v_add_f32_e32 v159, 1.0, v159
	v_add_f32_e32 v160, 1.0, v160
	v_add_f32_e32 v161, 1.0, v161
	v_rcp_f32_e32 v194, v194
	v_rcp_f32_e32 v195, v195
	v_rcp_f32_e32 v172, v172
	v_rcp_f32_e32 v173, v173
	v_rcp_f32_e32 v214, v214
	v_rcp_f32_e32 v215, v215
	v_rcp_f32_e32 v216, v216
	v_rcp_f32_e32 v217, v217
	v_mul_f32_e32 v194, v194, v144
	v_mul_f32_e32 v195, v195, v145
	v_mul_f32_e32 v172, v172, v146
	v_mul_f32_e32 v173, v173, v147
	v_mul_f32_e32 v214, v214, v158
	v_mul_f32_e32 v215, v215, v159
	v_mul_f32_e32 v216, v216, v160
	v_mul_f32_e32 v217, v217, v161
	v_pk_mul_f32 v[86:87], v[86:87], v[194:195]
	v_pk_mul_f32 v[88:89], v[88:89], v[172:173]
	v_pk_mul_f32 v[82:83], v[82:83], v[214:215]
	v_pk_mul_f32 v[84:85], v[84:85], v[216:217]
	v_lshlrev_b32_e32 v194, 16, v218
; __device__ __forceinline__ float sigmoidf_(float x) { return __builtin_amdgcn_rcpf(1.f + __expf(-x)); }
;     __device__ __forceinline__ void operator()(const pg8::f32x4 (&acc)[2][2][4][2], const pg8::Unit& u, int wr, int wc, int fr, int fq) const {
;     ...
;                     const u32x4v gw = *(const u32x4v*)(mg + r * PP + (size_t)u.z * D + col);
;                     float gt[8];
;                     gt[0] = __builtin_bit_cast(float, gw.x << 16); gt[1] = __builtin_bit_cast(float, gw.x & 0xffff0000u); gt[2] = __builtin_bit_cast(float, gw.y << 16); gt[3] = __builtin_bit_cast(float, gw.y & 0xffff0000u);
;                     gt[4] = __builtin_bit_cast(float, gw.z << 16); gt[5] = __builtin_bit_cast(float, gw.z & 0xffff0000u); gt[6] = __builtin_bit_cast(float, gw.w << 16); gt[7] = __builtin_bit_cast(float, gw.w & 0xffff0000u);
;                     pg8::f32x4 v0 = acc[ai][bj][m][0], v1 = acc[ai][bj][m][1];
; #pragma unroll
;                     for (int e = 0; e < 4; ++e) { v0[e] *= sigmoidf_(gt[e]); v1[e] *= sigmoidf_(gt[4 + e]); }
	v_and_b32_e32 v195, 0xffff0000, v218
	v_lshlrev_b32_e32 v172, 16, v219
	v_and_b32_e32 v173, 0xffff0000, v219
	v_lshlrev_b32_e32 v218, 16, v220
	v_and_b32_e32 v219, 0xffff0000, v220
	v_lshlrev_b32_e32 v220, 16, v221
	v_and_b32_e32 v221, 0xffff0000, v221
	v_mul_f32_e32 v194, 0xbfb8aa3b, v194
	v_mul_f32_e32 v195, 0xbfb8aa3b, v195
	v_mul_f32_e32 v172, 0xbfb8aa3b, v172
	v_mul_f32_e32 v173, 0xbfb8aa3b, v173
	v_mul_f32_e32 v218, 0xbfb8aa3b, v218
	v_mul_f32_e32 v219, 0xbfb8aa3b, v219
	v_mul_f32_e32 v220, 0xbfb8aa3b, v220
	v_mul_f32_e32 v221, 0xbfb8aa3b, v221
	v_min_f32_e32 v194, 0x42700000, v194
	v_min_f32_e32 v195, 0x42700000, v195
	v_min_f32_e32 v172, 0x42700000, v172
	v_min_f32_e32 v173, 0x42700000, v173
	v_min_f32_e32 v218, 0x42700000, v218
	v_min_f32_e32 v219, 0x42700000, v219
	v_min_f32_e32 v220, 0x42700000, v220
	v_min_f32_e32 v221, 0x42700000, v221
	v_exp_f32_e32 v194, v194
	v_exp_f32_e32 v195, v195
	v_exp_f32_e32 v172, v172
	v_exp_f32_e32 v173, v173
	v_exp_f32_e32 v218, v218
	v_exp_f32_e32 v219, v219
	v_exp_f32_e32 v220, v220
	v_exp_f32_e32 v221, v221
	v_add_f32_e32 v194, 1.0, v194
	v_add_f32_e32 v195, 1.0, v195
	v_add_f32_e32 v172, 1.0, v172
	v_add_f32_e32 v173, 1.0, v173
	v_add_f32_e32 v218, 1.0, v218
	v_add_f32_e32 v219, 1.0, v219
	v_add_f32_e32 v220, 1.0, v220
	v_add_f32_e32 v221, 1.0, v221
	v_lshlrev_b32_e32 v144, 16, v168
	v_and_b32_e32 v145, 0xffff0000, v168
	v_lshlrev_b32_e32 v146, 16, v169
	v_and_b32_e32 v147, 0xffff0000, v169
	v_lshlrev_b32_e32 v168, 16, v170
	v_and_b32_e32 v169, 0xffff0000, v170
	v_lshlrev_b32_e32 v170, 16, v171
	v_and_b32_e32 v171, 0xffff0000, v171
	v_mul_f32_e32 v144, 0xbfb8aa3b, v144
	v_mul_f32_e32 v145, 0xbfb8aa3b, v145
	v_mul_f32_e32 v146, 0xbfb8aa3b, v146
	v_mul_f32_e32 v147, 0xbfb8aa3b, v147
	v_mul_f32_e32 v168, 0xbfb8aa3b, v168
	v_mul_f32_e32 v169, 0xbfb8aa3b, v169
	v_mul_f32_e32 v170, 0xbfb8aa3b, v170
	v_mul_f32_e32 v171, 0xbfb8aa3b, v171
	v_min_f32_e32 v144, 0x42700000, v144
	v_min_f32_e32 v145, 0x42700000, v145
	v_min_f32_e32 v146, 0x42700000, v146
	v_min_f32_e32 v147, 0x42700000, v147
	v_min_f32_e32 v168, 0x42700000, v168
	v_min_f32_e32 v169, 0x42700000, v169
	v_min_f32_e32 v170, 0x42700000, v170
	v_min_f32_e32 v171, 0x42700000, v171
	v_exp_f32_e32 v144, v144
	v_exp_f32_e32 v145, v145
	v_exp_f32_e32 v146, v146
	v_exp_f32_e32 v147, v147
	v_exp_f32_e32 v168, v168
	v_exp_f32_e32 v169, v169
	v_exp_f32_e32 v170, v170
	v_exp_f32_e32 v171, v171
	v_add_f32_e32 v144, 1.0, v144
	v_add_f32_e32 v145, 1.0, v145
	v_add_f32_e32 v146, 1.0, v146
	v_add_f32_e32 v147, 1.0, v147
	v_add_f32_e32 v168, 1.0, v168
	v_add_f32_e32 v169, 1.0, v169
	v_add_f32_e32 v170, 1.0, v170
	v_add_f32_e32 v171, 1.0, v171
	v_rcp_f32_e32 v194, v194
	v_rcp_f32_e32 v195, v195
	v_rcp_f32_e32 v172, v172
	v_rcp_f32_e32 v173, v173
	v_rcp_f32_e32 v218, v218
	v_rcp_f32_e32 v219, v219
	v_rcp_f32_e32 v220, v220
	v_rcp_f32_e32 v221, v221
	v_mul_f32_e32 v194, v194, v144
	v_mul_f32_e32 v195, v195, v145
	v_mul_f32_e32 v172, v172, v146
	v_mul_f32_e32 v173, v173, v147
	v_mul_f32_e32 v218, v218, v168
	v_mul_f32_e32 v219, v219, v169
	v_mul_f32_e32 v220, v220, v170
	v_mul_f32_e32 v221, v221, v171
	v_pk_mul_f32 v[78:79], v[78:79], v[194:195]
	v_pk_mul_f32 v[80:81], v[80:81], v[172:173]
	v_pk_mul_f32 v[74:75], v[74:75], v[218:219]
	v_pk_mul_f32 v[76:77], v[76:77], v[220:221]
	v_lshlrev_b32_e32 v194, 16, v222
	v_and_b32_e32 v195, 0xffff0000, v222
	v_lshlrev_b32_e32 v172, 16, v223
	v_and_b32_e32 v173, 0xffff0000, v223
	v_lshlrev_b32_e32 v222, 16, v224
	v_and_b32_e32 v223, 0xffff0000, v224
	v_lshlrev_b32_e32 v224, 16, v225
	v_and_b32_e32 v225, 0xffff0000, v225
	v_mul_f32_e32 v194, 0xbfb8aa3b, v194
	v_mul_f32_e32 v195, 0xbfb8aa3b, v195
	v_mul_f32_e32 v172, 0xbfb8aa3b, v172
	v_mul_f32_e32 v173, 0xbfb8aa3b, v173
	v_mul_f32_e32 v222, 0xbfb8aa3b, v222
	v_mul_f32_e32 v223, 0xbfb8aa3b, v223
	v_mul_f32_e32 v224, 0xbfb8aa3b, v224
	v_mul_f32_e32 v225, 0xbfb8aa3b, v225
	v_min_f32_e32 v194, 0x42700000, v194
	v_min_f32_e32 v195, 0x42700000, v195
	v_min_f32_e32 v172, 0x42700000, v172
	v_min_f32_e32 v173, 0x42700000, v173
	v_min_f32_e32 v222, 0x42700000, v222
	v_min_f32_e32 v223, 0x42700000, v223
	v_min_f32_e32 v224, 0x42700000, v224
	v_min_f32_e32 v225, 0x42700000, v225
	v_exp_f32_e32 v194, v194
	v_exp_f32_e32 v195, v195
	v_exp_f32_e32 v172, v172
	v_exp_f32_e32 v173, v173
	v_exp_f32_e32 v222, v222
	v_exp_f32_e32 v223, v223
	v_exp_f32_e32 v224, v224
	v_exp_f32_e32 v225, v225
	v_add_f32_e32 v194, 1.0, v194
	v_add_f32_e32 v195, 1.0, v195
	v_add_f32_e32 v172, 1.0, v172
	v_add_f32_e32 v173, 1.0, v173
	v_add_f32_e32 v222, 1.0, v222
	v_add_f32_e32 v223, 1.0, v223
	v_add_f32_e32 v224, 1.0, v224
	v_add_f32_e32 v225, 1.0, v225
	v_lshlrev_b32_e32 v144, 16, v140
	v_and_b32_e32 v145, 0xffff0000, v140
	v_lshlrev_b32_e32 v146, 16, v141
	v_and_b32_e32 v147, 0xffff0000, v141
	v_lshlrev_b32_e32 v140, 16, v142
	v_and_b32_e32 v141, 0xffff0000, v142
	v_lshlrev_b32_e32 v142, 16, v143
	v_and_b32_e32 v143, 0xffff0000, v143
	v_mul_f32_e32 v144, 0xbfb8aa3b, v144
	v_mul_f32_e32 v145, 0xbfb8aa3b, v145
	v_mul_f32_e32 v146, 0xbfb8aa3b, v146
	v_mul_f32_e32 v147, 0xbfb8aa3b, v147
	v_mul_f32_e32 v140, 0xbfb8aa3b, v140
	v_mul_f32_e32 v141, 0xbfb8aa3b, v141
	v_mul_f32_e32 v142, 0xbfb8aa3b, v142
	v_mul_f32_e32 v143, 0xbfb8aa3b, v143
	v_min_f32_e32 v144, 0x42700000, v144
	v_min_f32_e32 v145, 0x42700000, v145
	v_min_f32_e32 v146, 0x42700000, v146
	v_min_f32_e32 v147, 0x42700000, v147
	v_min_f32_e32 v140, 0x42700000, v140
	v_min_f32_e32 v141, 0x42700000, v141
	v_min_f32_e32 v142, 0x42700000, v142
	v_min_f32_e32 v143, 0x42700000, v143
	v_exp_f32_e32 v144, v144
	v_exp_f32_e32 v145, v145
	v_exp_f32_e32 v146, v146
	v_exp_f32_e32 v147, v147
	v_exp_f32_e32 v140, v140
	v_exp_f32_e32 v141, v141
	v_exp_f32_e32 v142, v142
	v_exp_f32_e32 v143, v143
	v_add_f32_e32 v144, 1.0, v144
	v_add_f32_e32 v145, 1.0, v145
	v_add_f32_e32 v146, 1.0, v146
	v_add_f32_e32 v147, 1.0, v147
	v_add_f32_e32 v140, 1.0, v140
	v_add_f32_e32 v141, 1.0, v141
	v_add_f32_e32 v142, 1.0, v142
	v_add_f32_e32 v143, 1.0, v143
	v_rcp_f32_e32 v194, v194
	v_rcp_f32_e32 v195, v195
	v_rcp_f32_e32 v172, v172
	v_rcp_f32_e32 v173, v173
	v_rcp_f32_e32 v222, v222
	v_rcp_f32_e32 v223, v223
	v_rcp_f32_e32 v224, v224
	v_rcp_f32_e32 v225, v225
	v_mul_f32_e32 v194, v194, v144
	v_mul_f32_e32 v195, v195, v145
	v_mul_f32_e32 v172, v172, v146
	v_mul_f32_e32 v173, v173, v147
	v_mul_f32_e32 v222, v222, v140
	v_mul_f32_e32 v223, v223, v141
	v_mul_f32_e32 v224, v224, v142
	v_mul_f32_e32 v225, v225, v143
	v_pk_mul_f32 v[70:71], v[70:71], v[194:195]
	v_pk_mul_f32 v[72:73], v[72:73], v[172:173]
	v_pk_mul_f32 v[66:67], v[66:67], v[222:223]
	v_pk_mul_f32 v[68:69], v[68:69], v[224:225]
	s_waitcnt vmcnt(0)
; __device__ __forceinline__ float sigmoidf_(float x) { return __builtin_amdgcn_rcpf(1.f + __expf(-x)); }
;     __device__ __forceinline__ void operator()(const pg8::f32x4 (&acc)[2][2][4][2], const pg8::Unit& u, int wr, int wc, int fr, int fq) const {
;     ...
;                     const u32x4v gw = *(const u32x4v*)(mg + r * PP + (size_t)u.z * D + col);
;                     float gt[8];
;                     gt[0] = __builtin_bit_cast(float, gw.x << 16); gt[1] = __builtin_bit_cast(float, gw.x & 0xffff0000u); gt[2] = __builtin_bit_cast(float, gw.y << 16); gt[3] = __builtin_bit_cast(float, gw.y & 0xffff0000u);
;                     gt[4] = __builtin_bit_cast(float, gw.z << 16); gt[5] = __builtin_bit_cast(float, gw.z & 0xffff0000u); gt[6] = __builtin_bit_cast(float, gw.w << 16); gt[7] = __builtin_bit_cast(float, gw.w & 0xffff0000u);
;                     pg8::f32x4 v0 = acc[ai][bj][m][0], v1 = acc[ai][bj][m][1];
; #pragma unroll
;                     for (int e = 0; e < 4; ++e) { v0[e] *= sigmoidf_(gt[e]); v1[e] *= sigmoidf_(gt[4 + e]); }
	s_add_u32 s4, s10, 0x49c000
	s_addc_u32 s5, s11, 0
	global_load_dwordx4 v[210:213], v153, s[4:5]
	global_load_dwordx4 v[214:217], v153, s[4:5] offset:256
	s_add_u32 s8, s10, 0x49d000
	s_addc_u32 s9, s11, 0
	global_load_dwordx4 v[154:157], v153, s[8:9]
	global_load_dwordx4 v[158:161], v153, s[8:9] offset:256
	s_add_u32 s38, s10, 0x512000
	s_addc_u32 s39, s11, 0
	global_load_dwordx4 v[218:221], v153, s[38:39]
	global_load_dwordx4 v[222:225], v153, s[38:39] offset:256
	s_add_u32 s60, s10, 0x513000
	s_addc_u32 s61, s11, 0
	global_load_dwordx4 v[168:171], v153, s[60:61]
	global_load_dwordx4 v[140:143], v153, s[60:61] offset:256
	v_lshlrev_b32_e32 v194, 16, v178
	v_and_b32_e32 v195, 0xffff0000, v178
	v_lshlrev_b32_e32 v172, 16, v179
	v_and_b32_e32 v173, 0xffff0000, v179
	v_lshlrev_b32_e32 v178, 16, v180
	v_and_b32_e32 v179, 0xffff0000, v180
	v_lshlrev_b32_e32 v180, 16, v181
	v_and_b32_e32 v181, 0xffff0000, v181
	v_mul_f32_e32 v194, 0xbfb8aa3b, v194
	v_mul_f32_e32 v195, 0xbfb8aa3b, v195
	v_mul_f32_e32 v172, 0xbfb8aa3b, v172
	v_mul_f32_e32 v173, 0xbfb8aa3b, v173
	v_mul_f32_e32 v178, 0xbfb8aa3b, v178
	v_mul_f32_e32 v179, 0xbfb8aa3b, v179
	v_mul_f32_e32 v180, 0xbfb8aa3b, v180
	v_mul_f32_e32 v181, 0xbfb8aa3b, v181
	v_min_f32_e32 v194, 0x42700000, v194
	v_min_f32_e32 v195, 0x42700000, v195
	v_min_f32_e32 v172, 0x42700000, v172
	v_min_f32_e32 v173, 0x42700000, v173
	v_min_f32_e32 v178, 0x42700000, v178
	v_min_f32_e32 v179, 0x42700000, v179
	v_min_f32_e32 v180, 0x42700000, v180
	v_min_f32_e32 v181, 0x42700000, v181
	v_exp_f32_e32 v194, v194
	v_exp_f32_e32 v195, v195
	v_exp_f32_e32 v172, v172
	v_exp_f32_e32 v173, v173
	v_exp_f32_e32 v178, v178
	v_exp_f32_e32 v179, v179
	v_exp_f32_e32 v180, v180
	v_exp_f32_e32 v181, v181
	v_add_f32_e32 v194, 1.0, v194
	v_add_f32_e32 v195, 1.0, v195
	v_add_f32_e32 v172, 1.0, v172
	v_add_f32_e32 v173, 1.0, v173
	v_add_f32_e32 v178, 1.0, v178
	v_add_f32_e32 v179, 1.0, v179
	v_add_f32_e32 v180, 1.0, v180
	v_add_f32_e32 v181, 1.0, v181
	v_lshlrev_b32_e32 v144, 16, v226
	v_and_b32_e32 v145, 0xffff0000, v226
	v_lshlrev_b32_e32 v146, 16, v227
	v_and_b32_e32 v147, 0xffff0000, v227
	v_lshlrev_b32_e32 v226, 16, v228
	v_and_b32_e32 v227, 0xffff0000, v228
	v_lshlrev_b32_e32 v228, 16, v229
	v_and_b32_e32 v229, 0xffff0000, v229
	v_mul_f32_e32 v144, 0xbfb8aa3b, v144
	v_mul_f32_e32 v145, 0xbfb8aa3b, v145
	v_mul_f32_e32 v146, 0xbfb8aa3b, v146
	v_mul_f32_e32 v147, 0xbfb8aa3b, v147
	v_mul_f32_e32 v226, 0xbfb8aa3b, v226
	v_mul_f32_e32 v227, 0xbfb8aa3b, v227
	v_mul_f32_e32 v228, 0xbfb8aa3b, v228
	v_mul_f32_e32 v229, 0xbfb8aa3b, v229
	v_min_f32_e32 v144, 0x42700000, v144
	v_min_f32_e32 v145, 0x42700000, v145
	v_min_f32_e32 v146, 0x42700000, v146
	v_min_f32_e32 v147, 0x42700000, v147
	v_min_f32_e32 v226, 0x42700000, v226
	v_min_f32_e32 v227, 0x42700000, v227
	v_min_f32_e32 v228, 0x42700000, v228
	v_min_f32_e32 v229, 0x42700000, v229
	v_exp_f32_e32 v144, v144
	v_exp_f32_e32 v145, v145
	v_exp_f32_e32 v146, v146
	v_exp_f32_e32 v147, v147
	v_exp_f32_e32 v226, v226
	v_exp_f32_e32 v227, v227
	v_exp_f32_e32 v228, v228
	v_exp_f32_e32 v229, v229
	v_add_f32_e32 v144, 1.0, v144
	v_add_f32_e32 v145, 1.0, v145
	v_add_f32_e32 v146, 1.0, v146
	v_add_f32_e32 v147, 1.0, v147
	v_add_f32_e32 v226, 1.0, v226
	v_add_f32_e32 v227, 1.0, v227
	v_add_f32_e32 v228, 1.0, v228
	v_add_f32_e32 v229, 1.0, v229
	v_rcp_f32_e32 v194, v194
	v_rcp_f32_e32 v195, v195
	v_rcp_f32_e32 v172, v172
	v_rcp_f32_e32 v173, v173
	v_rcp_f32_e32 v178, v178
	v_rcp_f32_e32 v179, v179
	v_rcp_f32_e32 v180, v180
	v_rcp_f32_e32 v181, v181
	v_mul_f32_e32 v194, v194, v144
	v_mul_f32_e32 v195, v195, v145
	v_mul_f32_e32 v172, v172, v146
	v_mul_f32_e32 v173, v173, v147
	v_mul_f32_e32 v178, v178, v226
	v_mul_f32_e32 v179, v179, v227
	v_mul_f32_e32 v180, v180, v228
	v_mul_f32_e32 v181, v181, v229
	v_pk_mul_f32 v[62:63], v[62:63], v[194:195]
	v_pk_mul_f32 v[64:65], v[64:65], v[172:173]
	v_pk_mul_f32 v[58:59], v[58:59], v[178:179]
	v_pk_mul_f32 v[60:61], v[60:61], v[180:181]
	v_lshlrev_b32_e32 v194, 16, v182
	v_and_b32_e32 v195, 0xffff0000, v182
	v_lshlrev_b32_e32 v172, 16, v183
	v_and_b32_e32 v173, 0xffff0000, v183
	v_lshlrev_b32_e32 v182, 16, v184
	v_and_b32_e32 v183, 0xffff0000, v184
	v_lshlrev_b32_e32 v184, 16, v185
	v_and_b32_e32 v185, 0xffff0000, v185
	v_mul_f32_e32 v194, 0xbfb8aa3b, v194
	v_mul_f32_e32 v195, 0xbfb8aa3b, v195
	v_mul_f32_e32 v172, 0xbfb8aa3b, v172
	v_mul_f32_e32 v173, 0xbfb8aa3b, v173
	v_mul_f32_e32 v182, 0xbfb8aa3b, v182
	v_mul_f32_e32 v183, 0xbfb8aa3b, v183
	v_mul_f32_e32 v184, 0xbfb8aa3b, v184
	v_mul_f32_e32 v185, 0xbfb8aa3b, v185
	v_min_f32_e32 v194, 0x42700000, v194
	v_min_f32_e32 v195, 0x42700000, v195
	v_min_f32_e32 v172, 0x42700000, v172
	v_min_f32_e32 v173, 0x42700000, v173
	v_min_f32_e32 v182, 0x42700000, v182
	v_min_f32_e32 v183, 0x42700000, v183
	v_min_f32_e32 v184, 0x42700000, v184
	v_min_f32_e32 v185, 0x42700000, v185
	v_exp_f32_e32 v194, v194
	v_exp_f32_e32 v195, v195
	v_exp_f32_e32 v172, v172
	v_exp_f32_e32 v173, v173
	v_exp_f32_e32 v182, v182
	v_exp_f32_e32 v183, v183
	v_exp_f32_e32 v184, v184
	v_exp_f32_e32 v185, v185
	v_add_f32_e32 v194, 1.0, v194
	v_add_f32_e32 v195, 1.0, v195
	v_add_f32_e32 v172, 1.0, v172
	v_add_f32_e32 v173, 1.0, v173
	v_add_f32_e32 v182, 1.0, v182
	v_add_f32_e32 v183, 1.0, v183
	v_add_f32_e32 v184, 1.0, v184
	v_add_f32_e32 v185, 1.0, v185
	v_lshlrev_b32_e32 v144, 16, v230
	v_and_b32_e32 v145, 0xffff0000, v230
	v_lshlrev_b32_e32 v146, 16, v231
	v_and_b32_e32 v147, 0xffff0000, v231
	v_lshlrev_b32_e32 v230, 16, v232
	v_and_b32_e32 v231, 0xffff0000, v232
	v_lshlrev_b32_e32 v232, 16, v233
	v_and_b32_e32 v233, 0xffff0000, v233
	v_mul_f32_e32 v144, 0xbfb8aa3b, v144
; __device__ __forceinline__ float sigmoidf_(float x) { return __builtin_amdgcn_rcpf(1.f + __expf(-x)); }
;     __device__ __forceinline__ void operator()(const pg8::f32x4 (&acc)[2][2][4][2], const pg8::Unit& u, int wr, int wc, int fr, int fq) const {
;     ...
;                     const u32x4v gw = *(const u32x4v*)(mg + r * PP + (size_t)u.z * D + col);
;                     float gt[8];
;                     gt[0] = __builtin_bit_cast(float, gw.x << 16); gt[1] = __builtin_bit_cast(float, gw.x & 0xffff0000u); gt[2] = __builtin_bit_cast(float, gw.y << 16); gt[3] = __builtin_bit_cast(float, gw.y & 0xffff0000u);
;                     gt[4] = __builtin_bit_cast(float, gw.z << 16); gt[5] = __builtin_bit_cast(float, gw.z & 0xffff0000u); gt[6] = __builtin_bit_cast(float, gw.w << 16); gt[7] = __builtin_bit_cast(float, gw.w & 0xffff0000u);
;                     pg8::f32x4 v0 = acc[ai][bj][m][0], v1 = acc[ai][bj][m][1];
; #pragma unroll
;                     for (int e = 0; e < 4; ++e) { v0[e] *= sigmoidf_(gt[e]); v1[e] *= sigmoidf_(gt[4 + e]); }
	v_mul_f32_e32 v145, 0xbfb8aa3b, v145
	v_mul_f32_e32 v146, 0xbfb8aa3b, v146
	v_mul_f32_e32 v147, 0xbfb8aa3b, v147
	v_mul_f32_e32 v230, 0xbfb8aa3b, v230
	v_mul_f32_e32 v231, 0xbfb8aa3b, v231
	v_mul_f32_e32 v232, 0xbfb8aa3b, v232
	v_mul_f32_e32 v233, 0xbfb8aa3b, v233
	v_min_f32_e32 v144, 0x42700000, v144
	v_min_f32_e32 v145, 0x42700000, v145
	v_min_f32_e32 v146, 0x42700000, v146
	v_min_f32_e32 v147, 0x42700000, v147
	v_min_f32_e32 v230, 0x42700000, v230
	v_min_f32_e32 v231, 0x42700000, v231
	v_min_f32_e32 v232, 0x42700000, v232
	v_min_f32_e32 v233, 0x42700000, v233
	v_exp_f32_e32 v144, v144
	v_exp_f32_e32 v145, v145
	v_exp_f32_e32 v146, v146
	v_exp_f32_e32 v147, v147
	v_exp_f32_e32 v230, v230
	v_exp_f32_e32 v231, v231
	v_exp_f32_e32 v232, v232
	v_exp_f32_e32 v233, v233
	v_add_f32_e32 v144, 1.0, v144
	v_add_f32_e32 v145, 1.0, v145
	v_add_f32_e32 v146, 1.0, v146
	v_add_f32_e32 v147, 1.0, v147
	v_add_f32_e32 v230, 1.0, v230
	v_add_f32_e32 v231, 1.0, v231
	v_add_f32_e32 v232, 1.0, v232
	v_add_f32_e32 v233, 1.0, v233
	v_rcp_f32_e32 v194, v194
	v_rcp_f32_e32 v195, v195
	v_rcp_f32_e32 v172, v172
	v_rcp_f32_e32 v173, v173
	v_rcp_f32_e32 v182, v182
	v_rcp_f32_e32 v183, v183
	v_rcp_f32_e32 v184, v184
	v_rcp_f32_e32 v185, v185
	v_mul_f32_e32 v194, v194, v144
	v_mul_f32_e32 v195, v195, v145
	v_mul_f32_e32 v172, v172, v146
	v_mul_f32_e32 v173, v173, v147
	v_mul_f32_e32 v182, v182, v230
	v_mul_f32_e32 v183, v183, v231
	v_mul_f32_e32 v184, v184, v232
	v_mul_f32_e32 v185, v185, v233
	v_pk_mul_f32 v[54:55], v[54:55], v[194:195]
	v_pk_mul_f32 v[56:57], v[56:57], v[172:173]
	v_pk_mul_f32 v[50:51], v[50:51], v[182:183]
	v_pk_mul_f32 v[52:53], v[52:53], v[184:185]
	v_lshlrev_b32_e32 v194, 16, v186
	v_and_b32_e32 v195, 0xffff0000, v186
	v_lshlrev_b32_e32 v172, 16, v187
	v_and_b32_e32 v173, 0xffff0000, v187
	v_lshlrev_b32_e32 v186, 16, v188
	v_and_b32_e32 v187, 0xffff0000, v188
	v_lshlrev_b32_e32 v188, 16, v189
	v_and_b32_e32 v189, 0xffff0000, v189
	v_mul_f32_e32 v194, 0xbfb8aa3b, v194
	v_mul_f32_e32 v195, 0xbfb8aa3b, v195
	v_mul_f32_e32 v172, 0xbfb8aa3b, v172
	v_mul_f32_e32 v173, 0xbfb8aa3b, v173
	v_mul_f32_e32 v186, 0xbfb8aa3b, v186
	v_mul_f32_e32 v187, 0xbfb8aa3b, v187
	v_mul_f32_e32 v188, 0xbfb8aa3b, v188
	v_mul_f32_e32 v189, 0xbfb8aa3b, v189
	v_min_f32_e32 v194, 0x42700000, v194
	v_min_f32_e32 v195, 0x42700000, v195
	v_min_f32_e32 v172, 0x42700000, v172
	v_min_f32_e32 v173, 0x42700000, v173
	v_min_f32_e32 v186, 0x42700000, v186
	v_min_f32_e32 v187, 0x42700000, v187
	v_min_f32_e32 v188, 0x42700000, v188
	v_min_f32_e32 v189, 0x42700000, v189
	v_exp_f32_e32 v194, v194
	v_exp_f32_e32 v195, v195
	v_exp_f32_e32 v172, v172
	v_exp_f32_e32 v173, v173
	v_exp_f32_e32 v186, v186
	v_exp_f32_e32 v187, v187
	v_exp_f32_e32 v188, v188
	v_exp_f32_e32 v189, v189
	v_add_f32_e32 v194, 1.0, v194
	v_add_f32_e32 v195, 1.0, v195
	v_add_f32_e32 v172, 1.0, v172
	v_add_f32_e32 v173, 1.0, v173
	v_add_f32_e32 v186, 1.0, v186
	v_add_f32_e32 v187, 1.0, v187
	v_add_f32_e32 v188, 1.0, v188
	v_add_f32_e32 v189, 1.0, v189
	v_lshlrev_b32_e32 v144, 16, v234
	v_and_b32_e32 v145, 0xffff0000, v234
	v_lshlrev_b32_e32 v146, 16, v235
	v_and_b32_e32 v147, 0xffff0000, v235
	v_lshlrev_b32_e32 v234, 16, v236
	v_and_b32_e32 v235, 0xffff0000, v236
	v_lshlrev_b32_e32 v236, 16, v237
	v_and_b32_e32 v237, 0xffff0000, v237
	v_mul_f32_e32 v144, 0xbfb8aa3b, v144
	v_mul_f32_e32 v145, 0xbfb8aa3b, v145
	v_mul_f32_e32 v146, 0xbfb8aa3b, v146
	v_mul_f32_e32 v147, 0xbfb8aa3b, v147
	v_mul_f32_e32 v234, 0xbfb8aa3b, v234
	v_mul_f32_e32 v235, 0xbfb8aa3b, v235
	v_mul_f32_e32 v236, 0xbfb8aa3b, v236
	v_mul_f32_e32 v237, 0xbfb8aa3b, v237
	v_min_f32_e32 v144, 0x42700000, v144
	v_min_f32_e32 v145, 0x42700000, v145
	v_min_f32_e32 v146, 0x42700000, v146
	v_min_f32_e32 v147, 0x42700000, v147
	v_min_f32_e32 v234, 0x42700000, v234
	v_min_f32_e32 v235, 0x42700000, v235
	v_min_f32_e32 v236, 0x42700000, v236
	v_min_f32_e32 v237, 0x42700000, v237
	v_exp_f32_e32 v144, v144
	v_exp_f32_e32 v145, v145
	v_exp_f32_e32 v146, v146
	v_exp_f32_e32 v147, v147
	v_exp_f32_e32 v234, v234
	v_exp_f32_e32 v235, v235
	v_exp_f32_e32 v236, v236
	v_exp_f32_e32 v237, v237
	v_add_f32_e32 v144, 1.0, v144
	v_add_f32_e32 v145, 1.0, v145
	v_add_f32_e32 v146, 1.0, v146
	v_add_f32_e32 v147, 1.0, v147
	v_add_f32_e32 v234, 1.0, v234
	v_add_f32_e32 v235, 1.0, v235
	v_add_f32_e32 v236, 1.0, v236
	v_add_f32_e32 v237, 1.0, v237
	v_rcp_f32_e32 v194, v194
	v_rcp_f32_e32 v195, v195
	v_rcp_f32_e32 v172, v172
	v_rcp_f32_e32 v173, v173
	v_rcp_f32_e32 v186, v186
	v_rcp_f32_e32 v187, v187
	v_rcp_f32_e32 v188, v188
	v_rcp_f32_e32 v189, v189
	v_mul_f32_e32 v194, v194, v144
	v_mul_f32_e32 v195, v195, v145
	v_mul_f32_e32 v172, v172, v146
	v_mul_f32_e32 v173, v173, v147
	v_mul_f32_e32 v186, v186, v234
	v_mul_f32_e32 v187, v187, v235
	v_mul_f32_e32 v188, v188, v236
	v_mul_f32_e32 v189, v189, v237
	v_pk_mul_f32 v[46:47], v[46:47], v[194:195]
	v_pk_mul_f32 v[48:49], v[48:49], v[172:173]
	v_pk_mul_f32 v[42:43], v[42:43], v[186:187]
	v_pk_mul_f32 v[44:45], v[44:45], v[188:189]
	v_lshlrev_b32_e32 v194, 16, v190
	v_and_b32_e32 v195, 0xffff0000, v190
	v_lshlrev_b32_e32 v172, 16, v191
	v_and_b32_e32 v173, 0xffff0000, v191
	v_lshlrev_b32_e32 v190, 16, v192
	v_and_b32_e32 v191, 0xffff0000, v192
	v_lshlrev_b32_e32 v192, 16, v193
	v_and_b32_e32 v193, 0xffff0000, v193
	v_mul_f32_e32 v194, 0xbfb8aa3b, v194
	v_mul_f32_e32 v195, 0xbfb8aa3b, v195
	v_mul_f32_e32 v172, 0xbfb8aa3b, v172
	v_mul_f32_e32 v173, 0xbfb8aa3b, v173
	v_mul_f32_e32 v190, 0xbfb8aa3b, v190
	v_mul_f32_e32 v191, 0xbfb8aa3b, v191
	v_mul_f32_e32 v192, 0xbfb8aa3b, v192
	v_mul_f32_e32 v193, 0xbfb8aa3b, v193
	v_min_f32_e32 v194, 0x42700000, v194
; __device__ __forceinline__ float sigmoidf_(float x) { return __builtin_amdgcn_rcpf(1.f + __expf(-x)); }
;     __device__ __forceinline__ void operator()(const pg8::f32x4 (&acc)[2][2][4][2], const pg8::Unit& u, int wr, int wc, int fr, int fq) const {
;     ...
;                     const u32x4v gw = *(const u32x4v*)(mg + r * PP + (size_t)u.z * D + col);
;                     float gt[8];
;                     gt[0] = __builtin_bit_cast(float, gw.x << 16); gt[1] = __builtin_bit_cast(float, gw.x & 0xffff0000u); gt[2] = __builtin_bit_cast(float, gw.y << 16); gt[3] = __builtin_bit_cast(float, gw.y & 0xffff0000u);
;                     gt[4] = __builtin_bit_cast(float, gw.z << 16); gt[5] = __builtin_bit_cast(float, gw.z & 0xffff0000u); gt[6] = __builtin_bit_cast(float, gw.w << 16); gt[7] = __builtin_bit_cast(float, gw.w & 0xffff0000u);
;                     pg8::f32x4 v0 = acc[ai][bj][m][0], v1 = acc[ai][bj][m][1];
; #pragma unroll
;                     for (int e = 0; e < 4; ++e) { v0[e] *= sigmoidf_(gt[e]); v1[e] *= sigmoidf_(gt[4 + e]); }
	v_min_f32_e32 v195, 0x42700000, v195
	v_min_f32_e32 v172, 0x42700000, v172
	v_min_f32_e32 v173, 0x42700000, v173
	v_min_f32_e32 v190, 0x42700000, v190
	v_min_f32_e32 v191, 0x42700000, v191
	v_min_f32_e32 v192, 0x42700000, v192
	v_min_f32_e32 v193, 0x42700000, v193
	v_exp_f32_e32 v194, v194
	v_exp_f32_e32 v195, v195
	v_exp_f32_e32 v172, v172
	v_exp_f32_e32 v173, v173
	v_exp_f32_e32 v190, v190
	v_exp_f32_e32 v191, v191
	v_exp_f32_e32 v192, v192
	v_exp_f32_e32 v193, v193
	v_add_f32_e32 v194, 1.0, v194
	v_add_f32_e32 v195, 1.0, v195
	v_add_f32_e32 v172, 1.0, v172
	v_add_f32_e32 v173, 1.0, v173
	v_add_f32_e32 v190, 1.0, v190
	v_add_f32_e32 v191, 1.0, v191
	v_add_f32_e32 v192, 1.0, v192
	v_add_f32_e32 v193, 1.0, v193
	v_lshlrev_b32_e32 v144, 16, v238
	v_and_b32_e32 v145, 0xffff0000, v238
	v_lshlrev_b32_e32 v146, 16, v239
	v_and_b32_e32 v147, 0xffff0000, v239
	v_lshlrev_b32_e32 v238, 16, v240
	v_and_b32_e32 v239, 0xffff0000, v240
	v_lshlrev_b32_e32 v240, 16, v241
	v_and_b32_e32 v241, 0xffff0000, v241
	v_mul_f32_e32 v144, 0xbfb8aa3b, v144
	v_mul_f32_e32 v145, 0xbfb8aa3b, v145
	v_mul_f32_e32 v146, 0xbfb8aa3b, v146
	v_mul_f32_e32 v147, 0xbfb8aa3b, v147
	v_mul_f32_e32 v238, 0xbfb8aa3b, v238
	v_mul_f32_e32 v239, 0xbfb8aa3b, v239
	v_mul_f32_e32 v240, 0xbfb8aa3b, v240
	v_mul_f32_e32 v241, 0xbfb8aa3b, v241
	v_min_f32_e32 v144, 0x42700000, v144
	v_min_f32_e32 v145, 0x42700000, v145
	v_min_f32_e32 v146, 0x42700000, v146
	v_min_f32_e32 v147, 0x42700000, v147
	v_min_f32_e32 v238, 0x42700000, v238
	v_min_f32_e32 v239, 0x42700000, v239
	v_min_f32_e32 v240, 0x42700000, v240
	v_min_f32_e32 v241, 0x42700000, v241
	v_exp_f32_e32 v144, v144
	v_exp_f32_e32 v145, v145
	v_exp_f32_e32 v146, v146
	v_exp_f32_e32 v147, v147
	v_exp_f32_e32 v238, v238
	v_exp_f32_e32 v239, v239
	v_exp_f32_e32 v240, v240
	v_exp_f32_e32 v241, v241
	v_add_f32_e32 v144, 1.0, v144
	v_add_f32_e32 v145, 1.0, v145
	v_add_f32_e32 v146, 1.0, v146
	v_add_f32_e32 v147, 1.0, v147
	v_add_f32_e32 v238, 1.0, v238
	v_add_f32_e32 v239, 1.0, v239
	v_add_f32_e32 v240, 1.0, v240
	v_add_f32_e32 v241, 1.0, v241
	v_rcp_f32_e32 v194, v194
	v_rcp_f32_e32 v195, v195
	v_rcp_f32_e32 v172, v172
	v_rcp_f32_e32 v173, v173
	v_rcp_f32_e32 v190, v190
	v_rcp_f32_e32 v191, v191
	v_rcp_f32_e32 v192, v192
	v_rcp_f32_e32 v193, v193
	v_mul_f32_e32 v194, v194, v144
	v_mul_f32_e32 v195, v195, v145
	v_mul_f32_e32 v172, v172, v146
	v_mul_f32_e32 v173, v173, v147
	v_mul_f32_e32 v190, v190, v238
	v_mul_f32_e32 v191, v191, v239
	v_mul_f32_e32 v192, v192, v240
	v_mul_f32_e32 v193, v193, v241
	v_pk_mul_f32 v[38:39], v[38:39], v[194:195]
	v_pk_mul_f32 v[40:41], v[40:41], v[172:173]
	v_pk_mul_f32 v[34:35], v[34:35], v[190:191]
	v_pk_mul_f32 v[36:37], v[36:37], v[192:193]
	s_waitcnt vmcnt(0)
	v_lshlrev_b32_e32 v194, 16, v210
	v_and_b32_e32 v195, 0xffff0000, v210
	v_lshlrev_b32_e32 v172, 16, v211
	v_and_b32_e32 v173, 0xffff0000, v211
	v_lshlrev_b32_e32 v210, 16, v212
	v_and_b32_e32 v211, 0xffff0000, v212
	v_lshlrev_b32_e32 v212, 16, v213
	v_and_b32_e32 v213, 0xffff0000, v213
	v_mul_f32_e32 v194, 0xbfb8aa3b, v194
	v_mul_f32_e32 v195, 0xbfb8aa3b, v195
	v_mul_f32_e32 v172, 0xbfb8aa3b, v172
	v_mul_f32_e32 v173, 0xbfb8aa3b, v173
	v_mul_f32_e32 v210, 0xbfb8aa3b, v210
	v_mul_f32_e32 v211, 0xbfb8aa3b, v211
	v_mul_f32_e32 v212, 0xbfb8aa3b, v212
	v_mul_f32_e32 v213, 0xbfb8aa3b, v213
	v_min_f32_e32 v194, 0x42700000, v194
	v_min_f32_e32 v195, 0x42700000, v195
	v_min_f32_e32 v172, 0x42700000, v172
	v_min_f32_e32 v173, 0x42700000, v173
	v_min_f32_e32 v210, 0x42700000, v210
	v_min_f32_e32 v211, 0x42700000, v211
	v_min_f32_e32 v212, 0x42700000, v212
	v_min_f32_e32 v213, 0x42700000, v213
	v_exp_f32_e32 v194, v194
	v_exp_f32_e32 v195, v195
	v_exp_f32_e32 v172, v172
	v_exp_f32_e32 v173, v173
	v_exp_f32_e32 v210, v210
	v_exp_f32_e32 v211, v211
	v_exp_f32_e32 v212, v212
	v_exp_f32_e32 v213, v213
	v_add_f32_e32 v194, 1.0, v194
	v_add_f32_e32 v195, 1.0, v195
	v_add_f32_e32 v172, 1.0, v172
	v_add_f32_e32 v173, 1.0, v173
	v_add_f32_e32 v210, 1.0, v210
	v_add_f32_e32 v211, 1.0, v211
	v_add_f32_e32 v212, 1.0, v212
	v_add_f32_e32 v213, 1.0, v213
	v_lshlrev_b32_e32 v144, 16, v154
	v_and_b32_e32 v145, 0xffff0000, v154
	v_lshlrev_b32_e32 v146, 16, v155
	v_and_b32_e32 v147, 0xffff0000, v155
	v_lshlrev_b32_e32 v154, 16, v156
	v_and_b32_e32 v155, 0xffff0000, v156
	v_lshlrev_b32_e32 v156, 16, v157
	v_and_b32_e32 v157, 0xffff0000, v157
	v_mul_f32_e32 v144, 0xbfb8aa3b, v144
	v_mul_f32_e32 v145, 0xbfb8aa3b, v145
	v_mul_f32_e32 v146, 0xbfb8aa3b, v146
	v_mul_f32_e32 v147, 0xbfb8aa3b, v147
	v_mul_f32_e32 v154, 0xbfb8aa3b, v154
	v_mul_f32_e32 v155, 0xbfb8aa3b, v155
	v_mul_f32_e32 v156, 0xbfb8aa3b, v156
	v_mul_f32_e32 v157, 0xbfb8aa3b, v157
	v_min_f32_e32 v144, 0x42700000, v144
	v_min_f32_e32 v145, 0x42700000, v145
	v_min_f32_e32 v146, 0x42700000, v146
	v_min_f32_e32 v147, 0x42700000, v147
	v_min_f32_e32 v154, 0x42700000, v154
	v_min_f32_e32 v155, 0x42700000, v155
	v_min_f32_e32 v156, 0x42700000, v156
	v_min_f32_e32 v157, 0x42700000, v157
	v_exp_f32_e32 v144, v144
	v_exp_f32_e32 v145, v145
	v_exp_f32_e32 v146, v146
	v_exp_f32_e32 v147, v147
	v_exp_f32_e32 v154, v154
	v_exp_f32_e32 v155, v155
	v_exp_f32_e32 v156, v156
	v_exp_f32_e32 v157, v157
	v_add_f32_e32 v144, 1.0, v144
	v_add_f32_e32 v145, 1.0, v145
	v_add_f32_e32 v146, 1.0, v146
	v_add_f32_e32 v147, 1.0, v147
	v_add_f32_e32 v154, 1.0, v154
	v_add_f32_e32 v155, 1.0, v155
	v_add_f32_e32 v156, 1.0, v156
	v_add_f32_e32 v157, 1.0, v157
	v_rcp_f32_e32 v194, v194
	v_rcp_f32_e32 v195, v195
	v_rcp_f32_e32 v172, v172
	v_rcp_f32_e32 v173, v173
	v_rcp_f32_e32 v210, v210
	v_rcp_f32_e32 v211, v211
	v_rcp_f32_e32 v212, v212
	v_rcp_f32_e32 v213, v213
; __device__ __forceinline__ float sigmoidf_(float x) { return __builtin_amdgcn_rcpf(1.f + __expf(-x)); }
;     __device__ __forceinline__ void operator()(const pg8::f32x4 (&acc)[2][2][4][2], const pg8::Unit& u, int wr, int wc, int fr, int fq) const {
;     ...
;                     const u32x4v gw = *(const u32x4v*)(mg + r * PP + (size_t)u.z * D + col);
;                     float gt[8];
;                     gt[0] = __builtin_bit_cast(float, gw.x << 16); gt[1] = __builtin_bit_cast(float, gw.x & 0xffff0000u); gt[2] = __builtin_bit_cast(float, gw.y << 16); gt[3] = __builtin_bit_cast(float, gw.y & 0xffff0000u);
;                     gt[4] = __builtin_bit_cast(float, gw.z << 16); gt[5] = __builtin_bit_cast(float, gw.z & 0xffff0000u); gt[6] = __builtin_bit_cast(float, gw.w << 16); gt[7] = __builtin_bit_cast(float, gw.w & 0xffff0000u);
;                     pg8::f32x4 v0 = acc[ai][bj][m][0], v1 = acc[ai][bj][m][1];
; #pragma unroll
;                     for (int e = 0; e < 4; ++e) { v0[e] *= sigmoidf_(gt[e]); v1[e] *= sigmoidf_(gt[4 + e]); }
	v_mul_f32_e32 v194, v194, v144
	v_mul_f32_e32 v195, v195, v145
	v_mul_f32_e32 v172, v172, v146
	v_mul_f32_e32 v173, v173, v147
	v_mul_f32_e32 v210, v210, v154
	v_mul_f32_e32 v211, v211, v155
	v_mul_f32_e32 v212, v212, v156
	v_mul_f32_e32 v213, v213, v157
	v_pk_mul_f32 v[30:31], v[30:31], v[194:195]
	v_pk_mul_f32 v[32:33], v[32:33], v[172:173]
	v_pk_mul_f32 v[26:27], v[26:27], v[210:211]
	v_pk_mul_f32 v[28:29], v[28:29], v[212:213]
	v_lshlrev_b32_e32 v194, 16, v214
	v_and_b32_e32 v195, 0xffff0000, v214
	v_lshlrev_b32_e32 v172, 16, v215
	v_and_b32_e32 v173, 0xffff0000, v215
	v_lshlrev_b32_e32 v214, 16, v216
	v_and_b32_e32 v215, 0xffff0000, v216
	v_lshlrev_b32_e32 v216, 16, v217
	v_and_b32_e32 v217, 0xffff0000, v217
	v_mul_f32_e32 v194, 0xbfb8aa3b, v194
	v_mul_f32_e32 v195, 0xbfb8aa3b, v195
	v_mul_f32_e32 v172, 0xbfb8aa3b, v172
	v_mul_f32_e32 v173, 0xbfb8aa3b, v173
	v_mul_f32_e32 v214, 0xbfb8aa3b, v214
	v_mul_f32_e32 v215, 0xbfb8aa3b, v215
	v_mul_f32_e32 v216, 0xbfb8aa3b, v216
	v_mul_f32_e32 v217, 0xbfb8aa3b, v217
	v_min_f32_e32 v194, 0x42700000, v194
	v_min_f32_e32 v195, 0x42700000, v195
	v_min_f32_e32 v172, 0x42700000, v172
	v_min_f32_e32 v173, 0x42700000, v173
	v_min_f32_e32 v214, 0x42700000, v214
	v_min_f32_e32 v215, 0x42700000, v215
	v_min_f32_e32 v216, 0x42700000, v216
	v_min_f32_e32 v217, 0x42700000, v217
	v_exp_f32_e32 v194, v194
	v_exp_f32_e32 v195, v195
	v_exp_f32_e32 v172, v172
	v_exp_f32_e32 v173, v173
	v_exp_f32_e32 v214, v214
	v_exp_f32_e32 v215, v215
	v_exp_f32_e32 v216, v216
	v_exp_f32_e32 v217, v217
	v_add_f32_e32 v194, 1.0, v194
	v_add_f32_e32 v195, 1.0, v195
	v_add_f32_e32 v172, 1.0, v172
	v_add_f32_e32 v173, 1.0, v173
	v_add_f32_e32 v214, 1.0, v214
	v_add_f32_e32 v215, 1.0, v215
	v_add_f32_e32 v216, 1.0, v216
	v_add_f32_e32 v217, 1.0, v217
	v_lshlrev_b32_e32 v144, 16, v158
	v_and_b32_e32 v145, 0xffff0000, v158
	v_lshlrev_b32_e32 v146, 16, v159
	v_and_b32_e32 v147, 0xffff0000, v159
	v_lshlrev_b32_e32 v158, 16, v160
	v_and_b32_e32 v159, 0xffff0000, v160
	v_lshlrev_b32_e32 v160, 16, v161
	v_and_b32_e32 v161, 0xffff0000, v161
	v_mul_f32_e32 v144, 0xbfb8aa3b, v144
	v_mul_f32_e32 v145, 0xbfb8aa3b, v145
	v_mul_f32_e32 v146, 0xbfb8aa3b, v146
	v_mul_f32_e32 v147, 0xbfb8aa3b, v147
	v_mul_f32_e32 v158, 0xbfb8aa3b, v158
	v_mul_f32_e32 v159, 0xbfb8aa3b, v159
	v_mul_f32_e32 v160, 0xbfb8aa3b, v160
	v_mul_f32_e32 v161, 0xbfb8aa3b, v161
	v_min_f32_e32 v144, 0x42700000, v144
	v_min_f32_e32 v145, 0x42700000, v145
	v_min_f32_e32 v146, 0x42700000, v146
	v_min_f32_e32 v147, 0x42700000, v147
	v_min_f32_e32 v158, 0x42700000, v158
	v_min_f32_e32 v159, 0x42700000, v159
	v_min_f32_e32 v160, 0x42700000, v160
	v_min_f32_e32 v161, 0x42700000, v161
	v_exp_f32_e32 v144, v144
	v_exp_f32_e32 v145, v145
	v_exp_f32_e32 v146, v146
	v_exp_f32_e32 v147, v147
	v_exp_f32_e32 v158, v158
	v_exp_f32_e32 v159, v159
	v_exp_f32_e32 v160, v160
	v_exp_f32_e32 v161, v161
	v_add_f32_e32 v144, 1.0, v144
	v_add_f32_e32 v145, 1.0, v145
	v_add_f32_e32 v146, 1.0, v146
	v_add_f32_e32 v147, 1.0, v147
	v_add_f32_e32 v158, 1.0, v158
	v_add_f32_e32 v159, 1.0, v159
	v_add_f32_e32 v160, 1.0, v160
	v_add_f32_e32 v161, 1.0, v161
	v_rcp_f32_e32 v194, v194
	v_rcp_f32_e32 v195, v195
	v_rcp_f32_e32 v172, v172
	v_rcp_f32_e32 v173, v173
	v_rcp_f32_e32 v214, v214
	v_rcp_f32_e32 v215, v215
	v_rcp_f32_e32 v216, v216
	v_rcp_f32_e32 v217, v217
	v_mul_f32_e32 v194, v194, v144
	v_mul_f32_e32 v195, v195, v145
	v_mul_f32_e32 v172, v172, v146
	v_mul_f32_e32 v173, v173, v147
	v_mul_f32_e32 v214, v214, v158
	v_mul_f32_e32 v215, v215, v159
	v_mul_f32_e32 v216, v216, v160
	v_mul_f32_e32 v217, v217, v161
	v_pk_mul_f32 v[22:23], v[22:23], v[194:195]
	v_pk_mul_f32 v[24:25], v[24:25], v[172:173]
	v_pk_mul_f32 v[18:19], v[18:19], v[214:215]
	v_pk_mul_f32 v[20:21], v[20:21], v[216:217]
	v_lshlrev_b32_e32 v194, 16, v218
	v_and_b32_e32 v195, 0xffff0000, v218
	v_lshlrev_b32_e32 v172, 16, v219
	v_and_b32_e32 v173, 0xffff0000, v219
	v_lshlrev_b32_e32 v218, 16, v220
	v_and_b32_e32 v219, 0xffff0000, v220
	v_lshlrev_b32_e32 v220, 16, v221
	v_and_b32_e32 v221, 0xffff0000, v221
	v_mul_f32_e32 v194, 0xbfb8aa3b, v194
	v_mul_f32_e32 v195, 0xbfb8aa3b, v195
	v_mul_f32_e32 v172, 0xbfb8aa3b, v172
	v_mul_f32_e32 v173, 0xbfb8aa3b, v173
	v_mul_f32_e32 v218, 0xbfb8aa3b, v218
	v_mul_f32_e32 v219, 0xbfb8aa3b, v219
	v_mul_f32_e32 v220, 0xbfb8aa3b, v220
	v_mul_f32_e32 v221, 0xbfb8aa3b, v221
	v_min_f32_e32 v194, 0x42700000, v194
	v_min_f32_e32 v195, 0x42700000, v195
	v_min_f32_e32 v172, 0x42700000, v172
	v_min_f32_e32 v173, 0x42700000, v173
	v_min_f32_e32 v218, 0x42700000, v218
	v_min_f32_e32 v219, 0x42700000, v219
	v_min_f32_e32 v220, 0x42700000, v220
	v_min_f32_e32 v221, 0x42700000, v221
	v_exp_f32_e32 v194, v194
	v_exp_f32_e32 v195, v195
	v_exp_f32_e32 v172, v172
	v_exp_f32_e32 v173, v173
	v_exp_f32_e32 v218, v218
	v_exp_f32_e32 v219, v219
	v_exp_f32_e32 v220, v220
	v_exp_f32_e32 v221, v221
	v_add_f32_e32 v194, 1.0, v194
	v_add_f32_e32 v195, 1.0, v195
	v_add_f32_e32 v172, 1.0, v172
	v_add_f32_e32 v173, 1.0, v173
	v_add_f32_e32 v218, 1.0, v218
	v_add_f32_e32 v219, 1.0, v219
	v_add_f32_e32 v220, 1.0, v220
	v_add_f32_e32 v221, 1.0, v221
	v_lshlrev_b32_e32 v144, 16, v168
	v_and_b32_e32 v145, 0xffff0000, v168
	v_lshlrev_b32_e32 v146, 16, v169
	v_and_b32_e32 v147, 0xffff0000, v169
	v_lshlrev_b32_e32 v168, 16, v170
	v_and_b32_e32 v169, 0xffff0000, v170
	v_lshlrev_b32_e32 v170, 16, v171
	v_and_b32_e32 v171, 0xffff0000, v171
	v_mul_f32_e32 v144, 0xbfb8aa3b, v144
	v_mul_f32_e32 v145, 0xbfb8aa3b, v145
	v_mul_f32_e32 v146, 0xbfb8aa3b, v146
	v_mul_f32_e32 v147, 0xbfb8aa3b, v147
	v_mul_f32_e32 v168, 0xbfb8aa3b, v168
	v_mul_f32_e32 v169, 0xbfb8aa3b, v169
; __device__ __forceinline__ float sigmoidf_(float x) { return __builtin_amdgcn_rcpf(1.f + __expf(-x)); }
;     __device__ __forceinline__ void operator()(const pg8::f32x4 (&acc)[2][2][4][2], const pg8::Unit& u, int wr, int wc, int fr, int fq) const {
;     ...
;                     const u32x4v gw = *(const u32x4v*)(mg + r * PP + (size_t)u.z * D + col);
;                     float gt[8];
;                     gt[0] = __builtin_bit_cast(float, gw.x << 16); gt[1] = __builtin_bit_cast(float, gw.x & 0xffff0000u); gt[2] = __builtin_bit_cast(float, gw.y << 16); gt[3] = __builtin_bit_cast(float, gw.y & 0xffff0000u);
;                     gt[4] = __builtin_bit_cast(float, gw.z << 16); gt[5] = __builtin_bit_cast(float, gw.z & 0xffff0000u); gt[6] = __builtin_bit_cast(float, gw.w << 16); gt[7] = __builtin_bit_cast(float, gw.w & 0xffff0000u);
;                     pg8::f32x4 v0 = acc[ai][bj][m][0], v1 = acc[ai][bj][m][1];
; #pragma unroll
;                     for (int e = 0; e < 4; ++e) { v0[e] *= sigmoidf_(gt[e]); v1[e] *= sigmoidf_(gt[4 + e]); }
	v_mul_f32_e32 v170, 0xbfb8aa3b, v170
	v_mul_f32_e32 v171, 0xbfb8aa3b, v171
	v_min_f32_e32 v144, 0x42700000, v144
	v_min_f32_e32 v145, 0x42700000, v145
	v_min_f32_e32 v146, 0x42700000, v146
	v_min_f32_e32 v147, 0x42700000, v147
	v_min_f32_e32 v168, 0x42700000, v168
	v_min_f32_e32 v169, 0x42700000, v169
	v_min_f32_e32 v170, 0x42700000, v170
	v_min_f32_e32 v171, 0x42700000, v171
	v_exp_f32_e32 v144, v144
	v_exp_f32_e32 v145, v145
	v_exp_f32_e32 v146, v146
	v_exp_f32_e32 v147, v147
	v_exp_f32_e32 v168, v168
	v_exp_f32_e32 v169, v169
	v_exp_f32_e32 v170, v170
	v_exp_f32_e32 v171, v171
	v_add_f32_e32 v144, 1.0, v144
	v_add_f32_e32 v145, 1.0, v145
	v_add_f32_e32 v146, 1.0, v146
	v_add_f32_e32 v147, 1.0, v147
	v_add_f32_e32 v168, 1.0, v168
	v_add_f32_e32 v169, 1.0, v169
	v_add_f32_e32 v170, 1.0, v170
	v_add_f32_e32 v171, 1.0, v171
	v_rcp_f32_e32 v194, v194
	v_rcp_f32_e32 v195, v195
	v_rcp_f32_e32 v172, v172
	v_rcp_f32_e32 v173, v173
	v_rcp_f32_e32 v218, v218
	v_rcp_f32_e32 v219, v219
	v_rcp_f32_e32 v220, v220
	v_rcp_f32_e32 v221, v221
	v_mul_f32_e32 v194, v194, v144
	v_mul_f32_e32 v195, v195, v145
	v_mul_f32_e32 v172, v172, v146
	v_mul_f32_e32 v173, v173, v147
	v_mul_f32_e32 v218, v218, v168
	v_mul_f32_e32 v219, v219, v169
	v_mul_f32_e32 v220, v220, v170
	v_mul_f32_e32 v221, v221, v171
	v_pk_mul_f32 v[14:15], v[14:15], v[194:195]
	v_pk_mul_f32 v[16:17], v[16:17], v[172:173]
	v_pk_mul_f32 v[10:11], v[10:11], v[218:219]
	v_pk_mul_f32 v[12:13], v[12:13], v[220:221]
	v_lshlrev_b32_e32 v194, 16, v222
	v_and_b32_e32 v195, 0xffff0000, v222
	v_lshlrev_b32_e32 v172, 16, v223
	v_and_b32_e32 v173, 0xffff0000, v223
	v_lshlrev_b32_e32 v222, 16, v224
	v_and_b32_e32 v223, 0xffff0000, v224
	v_lshlrev_b32_e32 v224, 16, v225
	v_and_b32_e32 v225, 0xffff0000, v225
	v_mul_f32_e32 v194, 0xbfb8aa3b, v194
	v_mul_f32_e32 v195, 0xbfb8aa3b, v195
	v_mul_f32_e32 v172, 0xbfb8aa3b, v172
	v_mul_f32_e32 v173, 0xbfb8aa3b, v173
	v_mul_f32_e32 v222, 0xbfb8aa3b, v222
	v_mul_f32_e32 v223, 0xbfb8aa3b, v223
	v_mul_f32_e32 v224, 0xbfb8aa3b, v224
	v_mul_f32_e32 v225, 0xbfb8aa3b, v225
	v_min_f32_e32 v194, 0x42700000, v194
	v_min_f32_e32 v195, 0x42700000, v195
	v_min_f32_e32 v172, 0x42700000, v172
	v_min_f32_e32 v173, 0x42700000, v173
	v_min_f32_e32 v222, 0x42700000, v222
	v_min_f32_e32 v223, 0x42700000, v223
	v_min_f32_e32 v224, 0x42700000, v224
	v_min_f32_e32 v225, 0x42700000, v225
	v_exp_f32_e32 v194, v194
	v_exp_f32_e32 v195, v195
	v_exp_f32_e32 v172, v172
	v_exp_f32_e32 v173, v173
	v_exp_f32_e32 v222, v222
	v_exp_f32_e32 v223, v223
	v_exp_f32_e32 v224, v224
	v_exp_f32_e32 v225, v225
	v_add_f32_e32 v194, 1.0, v194
	v_add_f32_e32 v195, 1.0, v195
	v_add_f32_e32 v172, 1.0, v172
	v_add_f32_e32 v173, 1.0, v173
	v_add_f32_e32 v222, 1.0, v222
	v_add_f32_e32 v223, 1.0, v223
	v_add_f32_e32 v224, 1.0, v224
	v_add_f32_e32 v225, 1.0, v225
	v_lshlrev_b32_e32 v144, 16, v140
	v_and_b32_e32 v145, 0xffff0000, v140
	v_lshlrev_b32_e32 v146, 16, v141
	v_and_b32_e32 v147, 0xffff0000, v141
	v_lshlrev_b32_e32 v140, 16, v142
	v_and_b32_e32 v141, 0xffff0000, v142
	v_lshlrev_b32_e32 v142, 16, v143
	v_and_b32_e32 v143, 0xffff0000, v143
	v_mul_f32_e32 v144, 0xbfb8aa3b, v144
	v_mul_f32_e32 v145, 0xbfb8aa3b, v145
	v_mul_f32_e32 v146, 0xbfb8aa3b, v146
	v_mul_f32_e32 v147, 0xbfb8aa3b, v147
	v_mul_f32_e32 v140, 0xbfb8aa3b, v140
	v_mul_f32_e32 v141, 0xbfb8aa3b, v141
	v_mul_f32_e32 v142, 0xbfb8aa3b, v142
	v_mul_f32_e32 v143, 0xbfb8aa3b, v143
	v_min_f32_e32 v144, 0x42700000, v144
	v_min_f32_e32 v145, 0x42700000, v145
	v_min_f32_e32 v146, 0x42700000, v146
	v_min_f32_e32 v147, 0x42700000, v147
	v_min_f32_e32 v140, 0x42700000, v140
	v_min_f32_e32 v141, 0x42700000, v141
	v_min_f32_e32 v142, 0x42700000, v142
	v_min_f32_e32 v143, 0x42700000, v143
	v_exp_f32_e32 v144, v144
	v_exp_f32_e32 v145, v145
	v_exp_f32_e32 v146, v146
	v_exp_f32_e32 v147, v147
	v_exp_f32_e32 v140, v140
	v_exp_f32_e32 v141, v141
	v_exp_f32_e32 v142, v142
	v_exp_f32_e32 v143, v143
	v_add_f32_e32 v144, 1.0, v144
	v_add_f32_e32 v145, 1.0, v145
	v_add_f32_e32 v146, 1.0, v146
	v_add_f32_e32 v147, 1.0, v147
	v_add_f32_e32 v140, 1.0, v140
	v_add_f32_e32 v141, 1.0, v141
	v_add_f32_e32 v142, 1.0, v142
	v_add_f32_e32 v143, 1.0, v143
	v_rcp_f32_e32 v194, v194
	v_rcp_f32_e32 v195, v195
	v_rcp_f32_e32 v172, v172
	v_rcp_f32_e32 v173, v173
	v_rcp_f32_e32 v222, v222
	v_rcp_f32_e32 v223, v223
	v_rcp_f32_e32 v224, v224
	v_rcp_f32_e32 v225, v225
	v_mul_f32_e32 v194, v194, v144
	v_mul_f32_e32 v195, v195, v145
	v_mul_f32_e32 v172, v172, v146
	v_mul_f32_e32 v173, v173, v147
	v_mul_f32_e32 v222, v222, v140
	v_mul_f32_e32 v223, v223, v141
	v_mul_f32_e32 v224, v224, v142
	v_mul_f32_e32 v225, v225, v143
	v_pk_mul_f32 v[6:7], v[6:7], v[194:195]
	v_pk_mul_f32 v[8:9], v[8:9], v[172:173]
	v_pk_mul_f32 v[2:3], v[2:3], v[222:223]
	v_pk_mul_f32 v[4:5], v[4:5], v[224:225]
	s_branch .Lemx_done
; __device__ __forceinline__ unsigned pk2(float lo, float hi) { f32x2_t v = {lo, hi}; bf16x2_t b = __builtin_convertvector(v, bf16x2_t); return __builtin_bit_cast(unsigned, b); }
; __device__ __forceinline__ float sigmoidf_(float x) { return __builtin_amdgcn_rcpf(1.f + __expf(-x)); }
;     __device__ __forceinline__ void operator()(const pg8::f32x4 (&acc)[2][2][4][2], const pg8::Unit& u, int wr, int wc, int fr, int fq) const {
;     ...
;                 const size_t r = (size_t)(row0 + ai * 128 + m * 16);
; #pragma unroll
;                 for (int bj = 0; bj < 2; ++bj) {
;                     const int col = col0 + bj * 128;
;                     const u32x4v gw = *(const u32x4v*)(mg + r * PP + (size_t)u.z * D + col);
;                     float gt[8];
;                     gt[0] = __builtin_bit_cast(float, gw.x << 16); gt[1] = __builtin_bit_cast(float, gw.x & 0xffff0000u); gt[2] = __builtin_bit_cast(float, gw.y << 16); gt[3] = __builtin_bit_cast(float, gw.y & 0xffff0000u);
;                     gt[4] = __builtin_bit_cast(float, gw.z << 16); gt[5] = __builtin_bit_cast(float, gw.z & 0xffff0000u); gt[6] = __builtin_bit_cast(float, gw.w << 16); gt[7] = __builtin_bit_cast(float, gw.w & 0xffff0000u);
;                     pg8::f32x4 v0 = acc[ai][bj][m][0], v1 = acc[ai][bj][m][1];
; #pragma unroll
;                     for (int e = 0; e < 4; ++e) { v0[e] *= sigmoidf_(gt[e]); v1[e] *= sigmoidf_(gt[4 + e]); }
;                     float* ap = accb + r * D + col;
;                     if (u.z > 0) { v0 += *(const pg8::f32x4*)ap; v1 += *(const pg8::f32x4*)(ap + 4); }
;                     if (u.z < 2) { *(pg8::f32x4*)ap = v0; *(pg8::f32x4*)(ap + 4) = v1; }
;                     else { pg8::u32x4 w; w.x = pk2(v0[0], v0[1]); w.y = pk2(v0[2], v0[3]); w.z = pk2(v1[0], v1[1]); w.w = pk2(v1[2], v1[3]); *(pg8::u32x4*)(out + r * D + col) = w; }
.Lemx_final:
	s_add_u32 s62, s10, 0x0
	s_addc_u32 s63, s11, 0
	global_load_dwordx4 v[178:181], v153, s[62:63]
	global_load_dwordx4 v[182:185], v153, s[62:63] offset:256
	s_add_u32 s64, s10, 0x76000
	s_addc_u32 s65, s11, 0
	global_load_dwordx4 v[186:189], v153, s[64:65]
	global_load_dwordx4 v[190:193], v153, s[64:65] offset:256
	s_waitcnt vmcnt(0)
	s_add_u32 s4, s10, 0xec000
	s_addc_u32 s5, s11, 0
	global_load_dwordx4 v[210:213], v153, s[4:5]
	global_load_dwordx4 v[214:217], v153, s[4:5] offset:256
	s_add_u32 s8, s10, 0x162000
	s_addc_u32 s9, s11, 0
	global_load_dwordx4 v[218:221], v153, s[8:9]
	global_load_dwordx4 v[222:225], v153, s[8:9] offset:256
	v_lshlrev_b32_e32 v194, 16, v178
	v_and_b32_e32 v195, 0xffff0000, v178
	v_lshlrev_b32_e32 v172, 16, v179
	v_and_b32_e32 v173, 0xffff0000, v179
	v_lshlrev_b32_e32 v178, 16, v180
	v_and_b32_e32 v179, 0xffff0000, v180
	v_lshlrev_b32_e32 v180, 16, v181
	v_and_b32_e32 v181, 0xffff0000, v181
	v_mul_f32_e32 v194, 0xbfb8aa3b, v194
	v_mul_f32_e32 v195, 0xbfb8aa3b, v195
	v_mul_f32_e32 v172, 0xbfb8aa3b, v172
	v_mul_f32_e32 v173, 0xbfb8aa3b, v173
	v_mul_f32_e32 v178, 0xbfb8aa3b, v178
	v_mul_f32_e32 v179, 0xbfb8aa3b, v179
	v_mul_f32_e32 v180, 0xbfb8aa3b, v180
	v_mul_f32_e32 v181, 0xbfb8aa3b, v181
	v_min_f32_e32 v194, 0x42700000, v194
	v_min_f32_e32 v195, 0x42700000, v195
	v_min_f32_e32 v172, 0x42700000, v172
	v_min_f32_e32 v173, 0x42700000, v173
	v_min_f32_e32 v178, 0x42700000, v178
	v_min_f32_e32 v179, 0x42700000, v179
	v_min_f32_e32 v180, 0x42700000, v180
	v_min_f32_e32 v181, 0x42700000, v181
	v_exp_f32_e32 v194, v194
	v_exp_f32_e32 v195, v195
	v_exp_f32_e32 v172, v172
	v_exp_f32_e32 v173, v173
	v_exp_f32_e32 v178, v178
	v_exp_f32_e32 v179, v179
	v_exp_f32_e32 v180, v180
	v_exp_f32_e32 v181, v181
	v_add_f32_e32 v194, 1.0, v194
	v_add_f32_e32 v195, 1.0, v195
	v_add_f32_e32 v172, 1.0, v172
	v_add_f32_e32 v173, 1.0, v173
	v_add_f32_e32 v178, 1.0, v178
	v_add_f32_e32 v179, 1.0, v179
	v_add_f32_e32 v180, 1.0, v180
	v_add_f32_e32 v181, 1.0, v181
	v_rcp_f32_e32 v194, v194
	v_rcp_f32_e32 v195, v195
	v_rcp_f32_e32 v172, v172
	v_rcp_f32_e32 v173, v173
	v_rcp_f32_e32 v178, v178
	v_rcp_f32_e32 v179, v179
	v_rcp_f32_e32 v180, v180
	v_rcp_f32_e32 v181, v181
	s_nop 0
	v_pk_mul_f32 v[126:127], v[126:127], v[194:195]
	v_pk_mul_f32 v[128:129], v[128:129], v[172:173]
	v_pk_mul_f32 v[122:123], v[122:123], v[178:179]
	v_pk_mul_f32 v[124:125], v[124:125], v[180:181]
	v_cvt_pk_bf16_f32 v178, v126, v127
	v_cvt_pk_bf16_f32 v179, v128, v129
	v_cvt_pk_bf16_f32 v180, v122, v123
	v_cvt_pk_bf16_f32 v181, v124, v125
	s_add_u32 s38, s76, 0x0
	s_addc_u32 s39, s77, 0
	global_store_dwordx4 v149, v[178:181], s[38:39] offset:0
	v_lshlrev_b32_e32 v194, 16, v182
	v_and_b32_e32 v195, 0xffff0000, v182
	v_lshlrev_b32_e32 v172, 16, v183
	v_and_b32_e32 v173, 0xffff0000, v183
	v_lshlrev_b32_e32 v182, 16, v184
	v_and_b32_e32 v183, 0xffff0000, v184
	v_lshlrev_b32_e32 v184, 16, v185
	v_and_b32_e32 v185, 0xffff0000, v185
	v_mul_f32_e32 v194, 0xbfb8aa3b, v194
	v_mul_f32_e32 v195, 0xbfb8aa3b, v195
	v_mul_f32_e32 v172, 0xbfb8aa3b, v172
	v_mul_f32_e32 v173, 0xbfb8aa3b, v173
	v_mul_f32_e32 v182, 0xbfb8aa3b, v182
	v_mul_f32_e32 v183, 0xbfb8aa3b, v183
	v_mul_f32_e32 v184, 0xbfb8aa3b, v184
	v_mul_f32_e32 v185, 0xbfb8aa3b, v185
	v_min_f32_e32 v194, 0x42700000, v194
	v_min_f32_e32 v195, 0x42700000, v195
	v_min_f32_e32 v172, 0x42700000, v172
	v_min_f32_e32 v173, 0x42700000, v173
	v_min_f32_e32 v182, 0x42700000, v182
	v_min_f32_e32 v183, 0x42700000, v183
	v_min_f32_e32 v184, 0x42700000, v184
	v_min_f32_e32 v185, 0x42700000, v185
	v_exp_f32_e32 v194, v194
	v_exp_f32_e32 v195, v195
	v_exp_f32_e32 v172, v172
	v_exp_f32_e32 v173, v173
	v_exp_f32_e32 v182, v182
	v_exp_f32_e32 v183, v183
	v_exp_f32_e32 v184, v184
	v_exp_f32_e32 v185, v185
	v_add_f32_e32 v194, 1.0, v194
	v_add_f32_e32 v195, 1.0, v195
	v_add_f32_e32 v172, 1.0, v172
	v_add_f32_e32 v173, 1.0, v173
	v_add_f32_e32 v182, 1.0, v182
	v_add_f32_e32 v183, 1.0, v183
	v_add_f32_e32 v184, 1.0, v184
	v_add_f32_e32 v185, 1.0, v185
	v_rcp_f32_e32 v194, v194
	v_rcp_f32_e32 v195, v195
	v_rcp_f32_e32 v172, v172
	v_rcp_f32_e32 v173, v173
	v_rcp_f32_e32 v182, v182
	v_rcp_f32_e32 v183, v183
	v_rcp_f32_e32 v184, v184
	v_rcp_f32_e32 v185, v185
	s_nop 0
	v_pk_mul_f32 v[118:119], v[118:119], v[194:195]
	v_pk_mul_f32 v[120:121], v[120:121], v[172:173]
	v_pk_mul_f32 v[114:115], v[114:115], v[182:183]
	v_pk_mul_f32 v[116:117], v[116:117], v[184:185]
	v_cvt_pk_bf16_f32 v182, v118, v119
	v_cvt_pk_bf16_f32 v183, v120, v121
	v_cvt_pk_bf16_f32 v184, v114, v115
	v_cvt_pk_bf16_f32 v185, v116, v117
	s_add_u32 s60, s76, 0x0
	s_addc_u32 s61, s77, 0
	global_store_dwordx4 v149, v[182:185], s[60:61] offset:256
	v_lshlrev_b32_e32 v194, 16, v186
	v_and_b32_e32 v195, 0xffff0000, v186
	v_lshlrev_b32_e32 v172, 16, v187
	v_and_b32_e32 v173, 0xffff0000, v187
	v_lshlrev_b32_e32 v186, 16, v188
	v_and_b32_e32 v187, 0xffff0000, v188
	v_lshlrev_b32_e32 v188, 16, v189
	v_and_b32_e32 v189, 0xffff0000, v189
	v_mul_f32_e32 v194, 0xbfb8aa3b, v194
	v_mul_f32_e32 v195, 0xbfb8aa3b, v195
	v_mul_f32_e32 v172, 0xbfb8aa3b, v172
	v_mul_f32_e32 v173, 0xbfb8aa3b, v173
	v_mul_f32_e32 v186, 0xbfb8aa3b, v186
	v_mul_f32_e32 v187, 0xbfb8aa3b, v187
	v_mul_f32_e32 v188, 0xbfb8aa3b, v188
	v_mul_f32_e32 v189, 0xbfb8aa3b, v189
	v_min_f32_e32 v194, 0x42700000, v194
	v_min_f32_e32 v195, 0x42700000, v195
	v_min_f32_e32 v172, 0x42700000, v172
	v_min_f32_e32 v173, 0x42700000, v173
	v_min_f32_e32 v186, 0x42700000, v186
	v_min_f32_e32 v187, 0x42700000, v187
	v_min_f32_e32 v188, 0x42700000, v188
	v_min_f32_e32 v189, 0x42700000, v189
	v_exp_f32_e32 v194, v194
	v_exp_f32_e32 v195, v195
; __device__ __forceinline__ unsigned pk2(float lo, float hi) { f32x2_t v = {lo, hi}; bf16x2_t b = __builtin_convertvector(v, bf16x2_t); return __builtin_bit_cast(unsigned, b); }
; __device__ __forceinline__ float sigmoidf_(float x) { return __builtin_amdgcn_rcpf(1.f + __expf(-x)); }
;     __device__ __forceinline__ void operator()(const pg8::f32x4 (&acc)[2][2][4][2], const pg8::Unit& u, int wr, int wc, int fr, int fq) const {
;     ...
;                 const size_t r = (size_t)(row0 + ai * 128 + m * 16);
; #pragma unroll
;                 for (int bj = 0; bj < 2; ++bj) {
;                     const int col = col0 + bj * 128;
;                     const u32x4v gw = *(const u32x4v*)(mg + r * PP + (size_t)u.z * D + col);
;                     float gt[8];
;                     gt[0] = __builtin_bit_cast(float, gw.x << 16); gt[1] = __builtin_bit_cast(float, gw.x & 0xffff0000u); gt[2] = __builtin_bit_cast(float, gw.y << 16); gt[3] = __builtin_bit_cast(float, gw.y & 0xffff0000u);
;                     gt[4] = __builtin_bit_cast(float, gw.z << 16); gt[5] = __builtin_bit_cast(float, gw.z & 0xffff0000u); gt[6] = __builtin_bit_cast(float, gw.w << 16); gt[7] = __builtin_bit_cast(float, gw.w & 0xffff0000u);
;                     pg8::f32x4 v0 = acc[ai][bj][m][0], v1 = acc[ai][bj][m][1];
; #pragma unroll
;                     for (int e = 0; e < 4; ++e) { v0[e] *= sigmoidf_(gt[e]); v1[e] *= sigmoidf_(gt[4 + e]); }
;                     float* ap = accb + r * D + col;
;                     if (u.z > 0) { v0 += *(const pg8::f32x4*)ap; v1 += *(const pg8::f32x4*)(ap + 4); }
;                     if (u.z < 2) { *(pg8::f32x4*)ap = v0; *(pg8::f32x4*)(ap + 4) = v1; }
;                     else { pg8::u32x4 w; w.x = pk2(v0[0], v0[1]); w.y = pk2(v0[2], v0[3]); w.z = pk2(v1[0], v1[1]); w.w = pk2(v1[2], v1[3]); *(pg8::u32x4*)(out + r * D + col) = w; }
	v_exp_f32_e32 v172, v172
	v_exp_f32_e32 v173, v173
	v_exp_f32_e32 v186, v186
	v_exp_f32_e32 v187, v187
	v_exp_f32_e32 v188, v188
	v_exp_f32_e32 v189, v189
	v_add_f32_e32 v194, 1.0, v194
	v_add_f32_e32 v195, 1.0, v195
	v_add_f32_e32 v172, 1.0, v172
	v_add_f32_e32 v173, 1.0, v173
	v_add_f32_e32 v186, 1.0, v186
	v_add_f32_e32 v187, 1.0, v187
	v_add_f32_e32 v188, 1.0, v188
	v_add_f32_e32 v189, 1.0, v189
	v_rcp_f32_e32 v194, v194
	v_rcp_f32_e32 v195, v195
	v_rcp_f32_e32 v172, v172
	v_rcp_f32_e32 v173, v173
	v_rcp_f32_e32 v186, v186
	v_rcp_f32_e32 v187, v187
	v_rcp_f32_e32 v188, v188
	v_rcp_f32_e32 v189, v189
	s_nop 0
	v_pk_mul_f32 v[110:111], v[110:111], v[194:195]
	v_pk_mul_f32 v[112:113], v[112:113], v[172:173]
	v_pk_mul_f32 v[106:107], v[106:107], v[186:187]
	v_pk_mul_f32 v[108:109], v[108:109], v[188:189]
	v_cvt_pk_bf16_f32 v186, v110, v111
	v_cvt_pk_bf16_f32 v187, v112, v113
	v_cvt_pk_bf16_f32 v188, v106, v107
	v_cvt_pk_bf16_f32 v189, v108, v109
	s_add_u32 s62, s76, 0x10000
	s_addc_u32 s63, s77, 0
	global_store_dwordx4 v149, v[186:189], s[62:63] offset:0
	v_lshlrev_b32_e32 v194, 16, v190
	v_and_b32_e32 v195, 0xffff0000, v190
	v_lshlrev_b32_e32 v172, 16, v191
	v_and_b32_e32 v173, 0xffff0000, v191
	v_lshlrev_b32_e32 v190, 16, v192
	v_and_b32_e32 v191, 0xffff0000, v192
	v_lshlrev_b32_e32 v192, 16, v193
	v_and_b32_e32 v193, 0xffff0000, v193
	v_mul_f32_e32 v194, 0xbfb8aa3b, v194
	v_mul_f32_e32 v195, 0xbfb8aa3b, v195
	v_mul_f32_e32 v172, 0xbfb8aa3b, v172
	v_mul_f32_e32 v173, 0xbfb8aa3b, v173
	v_mul_f32_e32 v190, 0xbfb8aa3b, v190
	v_mul_f32_e32 v191, 0xbfb8aa3b, v191
	v_mul_f32_e32 v192, 0xbfb8aa3b, v192
	v_mul_f32_e32 v193, 0xbfb8aa3b, v193
	v_min_f32_e32 v194, 0x42700000, v194
	v_min_f32_e32 v195, 0x42700000, v195
	v_min_f32_e32 v172, 0x42700000, v172
	v_min_f32_e32 v173, 0x42700000, v173
	v_min_f32_e32 v190, 0x42700000, v190
	v_min_f32_e32 v191, 0x42700000, v191
	v_min_f32_e32 v192, 0x42700000, v192
	v_min_f32_e32 v193, 0x42700000, v193
	v_exp_f32_e32 v194, v194
	v_exp_f32_e32 v195, v195
	v_exp_f32_e32 v172, v172
	v_exp_f32_e32 v173, v173
	v_exp_f32_e32 v190, v190
	v_exp_f32_e32 v191, v191
	v_exp_f32_e32 v192, v192
	v_exp_f32_e32 v193, v193
	v_add_f32_e32 v194, 1.0, v194
	v_add_f32_e32 v195, 1.0, v195
	v_add_f32_e32 v172, 1.0, v172
	v_add_f32_e32 v173, 1.0, v173
	v_add_f32_e32 v190, 1.0, v190
	v_add_f32_e32 v191, 1.0, v191
	v_add_f32_e32 v192, 1.0, v192
	v_add_f32_e32 v193, 1.0, v193
	v_rcp_f32_e32 v194, v194
	v_rcp_f32_e32 v195, v195
	v_rcp_f32_e32 v172, v172
	v_rcp_f32_e32 v173, v173
	v_rcp_f32_e32 v190, v190
	v_rcp_f32_e32 v191, v191
	v_rcp_f32_e32 v192, v192
	v_rcp_f32_e32 v193, v193
	s_nop 0
	v_pk_mul_f32 v[102:103], v[102:103], v[194:195]
	v_pk_mul_f32 v[104:105], v[104:105], v[172:173]
	v_pk_mul_f32 v[98:99], v[98:99], v[190:191]
	v_pk_mul_f32 v[100:101], v[100:101], v[192:193]
	v_cvt_pk_bf16_f32 v190, v102, v103
	v_cvt_pk_bf16_f32 v191, v104, v105
	v_cvt_pk_bf16_f32 v192, v98, v99
	v_cvt_pk_bf16_f32 v193, v100, v101
	s_add_u32 s64, s76, 0x10000
	s_addc_u32 s65, s77, 0
	global_store_dwordx4 v149, v[190:193], s[64:65] offset:256
	s_waitcnt vmcnt(0)
	s_add_u32 s4, s10, 0x3b0000
	s_addc_u32 s5, s11, 0
	global_load_dwordx4 v[178:181], v153, s[4:5]
	global_load_dwordx4 v[182:185], v153, s[4:5] offset:256
	s_add_u32 s8, s10, 0x426000
	s_addc_u32 s9, s11, 0
	global_load_dwordx4 v[186:189], v153, s[8:9]
	global_load_dwordx4 v[190:193], v153, s[8:9] offset:256
	v_lshlrev_b32_e32 v194, 16, v210
	v_and_b32_e32 v195, 0xffff0000, v210
	v_lshlrev_b32_e32 v172, 16, v211
	v_and_b32_e32 v173, 0xffff0000, v211
	v_lshlrev_b32_e32 v210, 16, v212
	v_and_b32_e32 v211, 0xffff0000, v212
	v_lshlrev_b32_e32 v212, 16, v213
	v_and_b32_e32 v213, 0xffff0000, v213
	v_mul_f32_e32 v194, 0xbfb8aa3b, v194
	v_mul_f32_e32 v195, 0xbfb8aa3b, v195
	v_mul_f32_e32 v172, 0xbfb8aa3b, v172
	v_mul_f32_e32 v173, 0xbfb8aa3b, v173
	v_mul_f32_e32 v210, 0xbfb8aa3b, v210
	v_mul_f32_e32 v211, 0xbfb8aa3b, v211
	v_mul_f32_e32 v212, 0xbfb8aa3b, v212
	v_mul_f32_e32 v213, 0xbfb8aa3b, v213
	v_min_f32_e32 v194, 0x42700000, v194
	v_min_f32_e32 v195, 0x42700000, v195
	v_min_f32_e32 v172, 0x42700000, v172
	v_min_f32_e32 v173, 0x42700000, v173
	v_min_f32_e32 v210, 0x42700000, v210
	v_min_f32_e32 v211, 0x42700000, v211
	v_min_f32_e32 v212, 0x42700000, v212
	v_min_f32_e32 v213, 0x42700000, v213
	v_exp_f32_e32 v194, v194
	v_exp_f32_e32 v195, v195
	v_exp_f32_e32 v172, v172
	v_exp_f32_e32 v173, v173
	v_exp_f32_e32 v210, v210
	v_exp_f32_e32 v211, v211
	v_exp_f32_e32 v212, v212
	v_exp_f32_e32 v213, v213
	v_add_f32_e32 v194, 1.0, v194
	v_add_f32_e32 v195, 1.0, v195
	v_add_f32_e32 v172, 1.0, v172
	v_add_f32_e32 v173, 1.0, v173
	v_add_f32_e32 v210, 1.0, v210
	v_add_f32_e32 v211, 1.0, v211
	v_add_f32_e32 v212, 1.0, v212
	v_add_f32_e32 v213, 1.0, v213
	v_rcp_f32_e32 v194, v194
	v_rcp_f32_e32 v195, v195
	v_rcp_f32_e32 v172, v172
	v_rcp_f32_e32 v173, v173
	v_rcp_f32_e32 v210, v210
	v_rcp_f32_e32 v211, v211
	v_rcp_f32_e32 v212, v212
	v_rcp_f32_e32 v213, v213
	s_nop 0
	v_pk_mul_f32 v[94:95], v[94:95], v[194:195]
	v_pk_mul_f32 v[96:97], v[96:97], v[172:173]
	v_pk_mul_f32 v[90:91], v[90:91], v[210:211]
	v_pk_mul_f32 v[92:93], v[92:93], v[212:213]
	v_cvt_pk_bf16_f32 v210, v94, v95
	v_cvt_pk_bf16_f32 v211, v96, v97
	v_cvt_pk_bf16_f32 v212, v90, v91
	v_cvt_pk_bf16_f32 v213, v92, v93
	s_add_u32 s38, s76, 0x20000
	s_addc_u32 s39, s77, 0
	global_store_dwordx4 v149, v[210:213], s[38:39] offset:0
	v_lshlrev_b32_e32 v194, 16, v214
	v_and_b32_e32 v195, 0xffff0000, v214
	v_lshlrev_b32_e32 v172, 16, v215
	v_and_b32_e32 v173, 0xffff0000, v215
	v_lshlrev_b32_e32 v214, 16, v216
	v_and_b32_e32 v215, 0xffff0000, v216
; __device__ __forceinline__ unsigned pk2(float lo, float hi) { f32x2_t v = {lo, hi}; bf16x2_t b = __builtin_convertvector(v, bf16x2_t); return __builtin_bit_cast(unsigned, b); }
; __device__ __forceinline__ float sigmoidf_(float x) { return __builtin_amdgcn_rcpf(1.f + __expf(-x)); }
;     __device__ __forceinline__ void operator()(const pg8::f32x4 (&acc)[2][2][4][2], const pg8::Unit& u, int wr, int wc, int fr, int fq) const {
;     ...
;                 const size_t r = (size_t)(row0 + ai * 128 + m * 16);
; #pragma unroll
;                 for (int bj = 0; bj < 2; ++bj) {
;                     const int col = col0 + bj * 128;
;                     const u32x4v gw = *(const u32x4v*)(mg + r * PP + (size_t)u.z * D + col);
;                     float gt[8];
;                     gt[0] = __builtin_bit_cast(float, gw.x << 16); gt[1] = __builtin_bit_cast(float, gw.x & 0xffff0000u); gt[2] = __builtin_bit_cast(float, gw.y << 16); gt[3] = __builtin_bit_cast(float, gw.y & 0xffff0000u);
;                     gt[4] = __builtin_bit_cast(float, gw.z << 16); gt[5] = __builtin_bit_cast(float, gw.z & 0xffff0000u); gt[6] = __builtin_bit_cast(float, gw.w << 16); gt[7] = __builtin_bit_cast(float, gw.w & 0xffff0000u);
;                     pg8::f32x4 v0 = acc[ai][bj][m][0], v1 = acc[ai][bj][m][1];
; #pragma unroll
;                     for (int e = 0; e < 4; ++e) { v0[e] *= sigmoidf_(gt[e]); v1[e] *= sigmoidf_(gt[4 + e]); }
;                     float* ap = accb + r * D + col;
;                     if (u.z > 0) { v0 += *(const pg8::f32x4*)ap; v1 += *(const pg8::f32x4*)(ap + 4); }
;                     if (u.z < 2) { *(pg8::f32x4*)ap = v0; *(pg8::f32x4*)(ap + 4) = v1; }
;                     else { pg8::u32x4 w; w.x = pk2(v0[0], v0[1]); w.y = pk2(v0[2], v0[3]); w.z = pk2(v1[0], v1[1]); w.w = pk2(v1[2], v1[3]); *(pg8::u32x4*)(out + r * D + col) = w; }
	v_lshlrev_b32_e32 v216, 16, v217
	v_and_b32_e32 v217, 0xffff0000, v217
	v_mul_f32_e32 v194, 0xbfb8aa3b, v194
	v_mul_f32_e32 v195, 0xbfb8aa3b, v195
	v_mul_f32_e32 v172, 0xbfb8aa3b, v172
	v_mul_f32_e32 v173, 0xbfb8aa3b, v173
	v_mul_f32_e32 v214, 0xbfb8aa3b, v214
	v_mul_f32_e32 v215, 0xbfb8aa3b, v215
	v_mul_f32_e32 v216, 0xbfb8aa3b, v216
	v_mul_f32_e32 v217, 0xbfb8aa3b, v217
	v_min_f32_e32 v194, 0x42700000, v194
	v_min_f32_e32 v195, 0x42700000, v195
	v_min_f32_e32 v172, 0x42700000, v172
	v_min_f32_e32 v173, 0x42700000, v173
	v_min_f32_e32 v214, 0x42700000, v214
	v_min_f32_e32 v215, 0x42700000, v215
	v_min_f32_e32 v216, 0x42700000, v216
	v_min_f32_e32 v217, 0x42700000, v217
	v_exp_f32_e32 v194, v194
	v_exp_f32_e32 v195, v195
	v_exp_f32_e32 v172, v172
	v_exp_f32_e32 v173, v173
	v_exp_f32_e32 v214, v214
	v_exp_f32_e32 v215, v215
	v_exp_f32_e32 v216, v216
	v_exp_f32_e32 v217, v217
	v_add_f32_e32 v194, 1.0, v194
	v_add_f32_e32 v195, 1.0, v195
	v_add_f32_e32 v172, 1.0, v172
	v_add_f32_e32 v173, 1.0, v173
	v_add_f32_e32 v214, 1.0, v214
	v_add_f32_e32 v215, 1.0, v215
	v_add_f32_e32 v216, 1.0, v216
	v_add_f32_e32 v217, 1.0, v217
	v_rcp_f32_e32 v194, v194
	v_rcp_f32_e32 v195, v195
	v_rcp_f32_e32 v172, v172
	v_rcp_f32_e32 v173, v173
	v_rcp_f32_e32 v214, v214
	v_rcp_f32_e32 v215, v215
	v_rcp_f32_e32 v216, v216
	v_rcp_f32_e32 v217, v217
	s_nop 0
	v_pk_mul_f32 v[86:87], v[86:87], v[194:195]
	v_pk_mul_f32 v[88:89], v[88:89], v[172:173]
	v_pk_mul_f32 v[82:83], v[82:83], v[214:215]
	v_pk_mul_f32 v[84:85], v[84:85], v[216:217]
	v_cvt_pk_bf16_f32 v214, v86, v87
	v_cvt_pk_bf16_f32 v215, v88, v89
	v_cvt_pk_bf16_f32 v216, v82, v83
	v_cvt_pk_bf16_f32 v217, v84, v85
	s_add_u32 s60, s76, 0x20000
	s_addc_u32 s61, s77, 0
	global_store_dwordx4 v149, v[214:217], s[60:61] offset:256
	v_lshlrev_b32_e32 v194, 16, v218
	v_and_b32_e32 v195, 0xffff0000, v218
	v_lshlrev_b32_e32 v172, 16, v219
	v_and_b32_e32 v173, 0xffff0000, v219
	v_lshlrev_b32_e32 v218, 16, v220
	v_and_b32_e32 v219, 0xffff0000, v220
	v_lshlrev_b32_e32 v220, 16, v221
	v_and_b32_e32 v221, 0xffff0000, v221
	v_mul_f32_e32 v194, 0xbfb8aa3b, v194
	v_mul_f32_e32 v195, 0xbfb8aa3b, v195
	v_mul_f32_e32 v172, 0xbfb8aa3b, v172
	v_mul_f32_e32 v173, 0xbfb8aa3b, v173
	v_mul_f32_e32 v218, 0xbfb8aa3b, v218
	v_mul_f32_e32 v219, 0xbfb8aa3b, v219
	v_mul_f32_e32 v220, 0xbfb8aa3b, v220
	v_mul_f32_e32 v221, 0xbfb8aa3b, v221
	v_min_f32_e32 v194, 0x42700000, v194
	v_min_f32_e32 v195, 0x42700000, v195
	v_min_f32_e32 v172, 0x42700000, v172
	v_min_f32_e32 v173, 0x42700000, v173
	v_min_f32_e32 v218, 0x42700000, v218
	v_min_f32_e32 v219, 0x42700000, v219
	v_min_f32_e32 v220, 0x42700000, v220
	v_min_f32_e32 v221, 0x42700000, v221
	v_exp_f32_e32 v194, v194
	v_exp_f32_e32 v195, v195
	v_exp_f32_e32 v172, v172
	v_exp_f32_e32 v173, v173
	v_exp_f32_e32 v218, v218
	v_exp_f32_e32 v219, v219
	v_exp_f32_e32 v220, v220
	v_exp_f32_e32 v221, v221
	v_add_f32_e32 v194, 1.0, v194
	v_add_f32_e32 v195, 1.0, v195
	v_add_f32_e32 v172, 1.0, v172
	v_add_f32_e32 v173, 1.0, v173
	v_add_f32_e32 v218, 1.0, v218
	v_add_f32_e32 v219, 1.0, v219
	v_add_f32_e32 v220, 1.0, v220
	v_add_f32_e32 v221, 1.0, v221
	v_rcp_f32_e32 v194, v194
	v_rcp_f32_e32 v195, v195
	v_rcp_f32_e32 v172, v172
	v_rcp_f32_e32 v173, v173
	v_rcp_f32_e32 v218, v218
	v_rcp_f32_e32 v219, v219
	v_rcp_f32_e32 v220, v220
	v_rcp_f32_e32 v221, v221
	s_nop 0
	v_pk_mul_f32 v[78:79], v[78:79], v[194:195]
	v_pk_mul_f32 v[80:81], v[80:81], v[172:173]
	v_pk_mul_f32 v[74:75], v[74:75], v[218:219]
	v_pk_mul_f32 v[76:77], v[76:77], v[220:221]
	v_cvt_pk_bf16_f32 v218, v78, v79
	v_cvt_pk_bf16_f32 v219, v80, v81
	v_cvt_pk_bf16_f32 v220, v74, v75
	v_cvt_pk_bf16_f32 v221, v76, v77
	s_add_u32 s62, s76, 0x30000
	s_addc_u32 s63, s77, 0
	global_store_dwordx4 v149, v[218:221], s[62:63] offset:0
	v_lshlrev_b32_e32 v194, 16, v222
	v_and_b32_e32 v195, 0xffff0000, v222
	v_lshlrev_b32_e32 v172, 16, v223
	v_and_b32_e32 v173, 0xffff0000, v223
	v_lshlrev_b32_e32 v222, 16, v224
	v_and_b32_e32 v223, 0xffff0000, v224
	v_lshlrev_b32_e32 v224, 16, v225
	v_and_b32_e32 v225, 0xffff0000, v225
	v_mul_f32_e32 v194, 0xbfb8aa3b, v194
	v_mul_f32_e32 v195, 0xbfb8aa3b, v195
	v_mul_f32_e32 v172, 0xbfb8aa3b, v172
	v_mul_f32_e32 v173, 0xbfb8aa3b, v173
	v_mul_f32_e32 v222, 0xbfb8aa3b, v222
	v_mul_f32_e32 v223, 0xbfb8aa3b, v223
	v_mul_f32_e32 v224, 0xbfb8aa3b, v224
	v_mul_f32_e32 v225, 0xbfb8aa3b, v225
	v_min_f32_e32 v194, 0x42700000, v194
	v_min_f32_e32 v195, 0x42700000, v195
	v_min_f32_e32 v172, 0x42700000, v172
	v_min_f32_e32 v173, 0x42700000, v173
	v_min_f32_e32 v222, 0x42700000, v222
	v_min_f32_e32 v223, 0x42700000, v223
	v_min_f32_e32 v224, 0x42700000, v224
	v_min_f32_e32 v225, 0x42700000, v225
	v_exp_f32_e32 v194, v194
	v_exp_f32_e32 v195, v195
	v_exp_f32_e32 v172, v172
	v_exp_f32_e32 v173, v173
	v_exp_f32_e32 v222, v222
	v_exp_f32_e32 v223, v223
	v_exp_f32_e32 v224, v224
	v_exp_f32_e32 v225, v225
	v_add_f32_e32 v194, 1.0, v194
	v_add_f32_e32 v195, 1.0, v195
	v_add_f32_e32 v172, 1.0, v172
	v_add_f32_e32 v173, 1.0, v173
	v_add_f32_e32 v222, 1.0, v222
	v_add_f32_e32 v223, 1.0, v223
	v_add_f32_e32 v224, 1.0, v224
	v_add_f32_e32 v225, 1.0, v225
	v_rcp_f32_e32 v194, v194
	v_rcp_f32_e32 v195, v195
	v_rcp_f32_e32 v172, v172
	v_rcp_f32_e32 v173, v173
	v_rcp_f32_e32 v222, v222
	v_rcp_f32_e32 v223, v223
	v_rcp_f32_e32 v224, v224
	v_rcp_f32_e32 v225, v225
	s_nop 0
	v_pk_mul_f32 v[70:71], v[70:71], v[194:195]
	v_pk_mul_f32 v[72:73], v[72:73], v[172:173]
	v_pk_mul_f32 v[66:67], v[66:67], v[222:223]
	v_pk_mul_f32 v[68:69], v[68:69], v[224:225]
	v_cvt_pk_bf16_f32 v222, v70, v71
	v_cvt_pk_bf16_f32 v223, v72, v73
	v_cvt_pk_bf16_f32 v224, v66, v67
	v_cvt_pk_bf16_f32 v225, v68, v69
	s_add_u32 s64, s76, 0x30000
	s_addc_u32 s65, s77, 0
	global_store_dwordx4 v149, v[222:225], s[64:65] offset:256
	s_waitcnt vmcnt(0)
; __device__ __forceinline__ unsigned pk2(float lo, float hi) { f32x2_t v = {lo, hi}; bf16x2_t b = __builtin_convertvector(v, bf16x2_t); return __builtin_bit_cast(unsigned, b); }
; __device__ __forceinline__ float sigmoidf_(float x) { return __builtin_amdgcn_rcpf(1.f + __expf(-x)); }
;     __device__ __forceinline__ void operator()(const pg8::f32x4 (&acc)[2][2][4][2], const pg8::Unit& u, int wr, int wc, int fr, int fq) const {
;     ...
;                 const size_t r = (size_t)(row0 + ai * 128 + m * 16);
; #pragma unroll
;                 for (int bj = 0; bj < 2; ++bj) {
;                     const int col = col0 + bj * 128;
;                     const u32x4v gw = *(const u32x4v*)(mg + r * PP + (size_t)u.z * D + col);
;                     float gt[8];
;                     gt[0] = __builtin_bit_cast(float, gw.x << 16); gt[1] = __builtin_bit_cast(float, gw.x & 0xffff0000u); gt[2] = __builtin_bit_cast(float, gw.y << 16); gt[3] = __builtin_bit_cast(float, gw.y & 0xffff0000u);
;                     gt[4] = __builtin_bit_cast(float, gw.z << 16); gt[5] = __builtin_bit_cast(float, gw.z & 0xffff0000u); gt[6] = __builtin_bit_cast(float, gw.w << 16); gt[7] = __builtin_bit_cast(float, gw.w & 0xffff0000u);
;                     pg8::f32x4 v0 = acc[ai][bj][m][0], v1 = acc[ai][bj][m][1];
; #pragma unroll
;                     for (int e = 0; e < 4; ++e) { v0[e] *= sigmoidf_(gt[e]); v1[e] *= sigmoidf_(gt[4 + e]); }
;                     float* ap = accb + r * D + col;
;                     if (u.z > 0) { v0 += *(const pg8::f32x4*)ap; v1 += *(const pg8::f32x4*)(ap + 4); }
;                     if (u.z < 2) { *(pg8::f32x4*)ap = v0; *(pg8::f32x4*)(ap + 4) = v1; }
;                     else { pg8::u32x4 w; w.x = pk2(v0[0], v0[1]); w.y = pk2(v0[2], v0[3]); w.z = pk2(v1[0], v1[1]); w.w = pk2(v1[2], v1[3]); *(pg8::u32x4*)(out + r * D + col) = w; }
	s_add_u32 s4, s10, 0x49c000
	s_addc_u32 s5, s11, 0
	global_load_dwordx4 v[210:213], v153, s[4:5]
	global_load_dwordx4 v[214:217], v153, s[4:5] offset:256
	s_add_u32 s8, s10, 0x512000
	s_addc_u32 s9, s11, 0
	global_load_dwordx4 v[218:221], v153, s[8:9]
	global_load_dwordx4 v[222:225], v153, s[8:9] offset:256
	v_lshlrev_b32_e32 v194, 16, v178
	v_and_b32_e32 v195, 0xffff0000, v178
	v_lshlrev_b32_e32 v172, 16, v179
	v_and_b32_e32 v173, 0xffff0000, v179
	v_lshlrev_b32_e32 v178, 16, v180
	v_and_b32_e32 v179, 0xffff0000, v180
	v_lshlrev_b32_e32 v180, 16, v181
	v_and_b32_e32 v181, 0xffff0000, v181
	v_mul_f32_e32 v194, 0xbfb8aa3b, v194
	v_mul_f32_e32 v195, 0xbfb8aa3b, v195
	v_mul_f32_e32 v172, 0xbfb8aa3b, v172
	v_mul_f32_e32 v173, 0xbfb8aa3b, v173
	v_mul_f32_e32 v178, 0xbfb8aa3b, v178
	v_mul_f32_e32 v179, 0xbfb8aa3b, v179
	v_mul_f32_e32 v180, 0xbfb8aa3b, v180
	v_mul_f32_e32 v181, 0xbfb8aa3b, v181
	v_min_f32_e32 v194, 0x42700000, v194
	v_min_f32_e32 v195, 0x42700000, v195
	v_min_f32_e32 v172, 0x42700000, v172
	v_min_f32_e32 v173, 0x42700000, v173
	v_min_f32_e32 v178, 0x42700000, v178
	v_min_f32_e32 v179, 0x42700000, v179
	v_min_f32_e32 v180, 0x42700000, v180
	v_min_f32_e32 v181, 0x42700000, v181
	v_exp_f32_e32 v194, v194
	v_exp_f32_e32 v195, v195
	v_exp_f32_e32 v172, v172
	v_exp_f32_e32 v173, v173
	v_exp_f32_e32 v178, v178
	v_exp_f32_e32 v179, v179
	v_exp_f32_e32 v180, v180
	v_exp_f32_e32 v181, v181
	v_add_f32_e32 v194, 1.0, v194
	v_add_f32_e32 v195, 1.0, v195
	v_add_f32_e32 v172, 1.0, v172
	v_add_f32_e32 v173, 1.0, v173
	v_add_f32_e32 v178, 1.0, v178
	v_add_f32_e32 v179, 1.0, v179
	v_add_f32_e32 v180, 1.0, v180
	v_add_f32_e32 v181, 1.0, v181
	v_rcp_f32_e32 v194, v194
	v_rcp_f32_e32 v195, v195
	v_rcp_f32_e32 v172, v172
	v_rcp_f32_e32 v173, v173
	v_rcp_f32_e32 v178, v178
	v_rcp_f32_e32 v179, v179
	v_rcp_f32_e32 v180, v180
	v_rcp_f32_e32 v181, v181
	s_nop 0
	v_pk_mul_f32 v[62:63], v[62:63], v[194:195]
	v_pk_mul_f32 v[64:65], v[64:65], v[172:173]
	v_pk_mul_f32 v[58:59], v[58:59], v[178:179]
	v_pk_mul_f32 v[60:61], v[60:61], v[180:181]
	v_cvt_pk_bf16_f32 v178, v62, v63
	v_cvt_pk_bf16_f32 v179, v64, v65
	v_cvt_pk_bf16_f32 v180, v58, v59
	v_cvt_pk_bf16_f32 v181, v60, v61
	s_add_u32 s38, s76, 0x80000
	s_addc_u32 s39, s77, 0
	global_store_dwordx4 v149, v[178:181], s[38:39] offset:0
	v_lshlrev_b32_e32 v194, 16, v182
	v_and_b32_e32 v195, 0xffff0000, v182
	v_lshlrev_b32_e32 v172, 16, v183
	v_and_b32_e32 v173, 0xffff0000, v183
	v_lshlrev_b32_e32 v182, 16, v184
	v_and_b32_e32 v183, 0xffff0000, v184
	v_lshlrev_b32_e32 v184, 16, v185
	v_and_b32_e32 v185, 0xffff0000, v185
	v_mul_f32_e32 v194, 0xbfb8aa3b, v194
	v_mul_f32_e32 v195, 0xbfb8aa3b, v195
	v_mul_f32_e32 v172, 0xbfb8aa3b, v172
	v_mul_f32_e32 v173, 0xbfb8aa3b, v173
	v_mul_f32_e32 v182, 0xbfb8aa3b, v182
	v_mul_f32_e32 v183, 0xbfb8aa3b, v183
	v_mul_f32_e32 v184, 0xbfb8aa3b, v184
	v_mul_f32_e32 v185, 0xbfb8aa3b, v185
	v_min_f32_e32 v194, 0x42700000, v194
	v_min_f32_e32 v195, 0x42700000, v195
	v_min_f32_e32 v172, 0x42700000, v172
	v_min_f32_e32 v173, 0x42700000, v173
	v_min_f32_e32 v182, 0x42700000, v182
	v_min_f32_e32 v183, 0x42700000, v183
	v_min_f32_e32 v184, 0x42700000, v184
	v_min_f32_e32 v185, 0x42700000, v185
	v_exp_f32_e32 v194, v194
	v_exp_f32_e32 v195, v195
	v_exp_f32_e32 v172, v172
	v_exp_f32_e32 v173, v173
	v_exp_f32_e32 v182, v182
	v_exp_f32_e32 v183, v183
	v_exp_f32_e32 v184, v184
	v_exp_f32_e32 v185, v185
	v_add_f32_e32 v194, 1.0, v194
	v_add_f32_e32 v195, 1.0, v195
	v_add_f32_e32 v172, 1.0, v172
	v_add_f32_e32 v173, 1.0, v173
	v_add_f32_e32 v182, 1.0, v182
	v_add_f32_e32 v183, 1.0, v183
	v_add_f32_e32 v184, 1.0, v184
	v_add_f32_e32 v185, 1.0, v185
	v_rcp_f32_e32 v194, v194
	v_rcp_f32_e32 v195, v195
	v_rcp_f32_e32 v172, v172
	v_rcp_f32_e32 v173, v173
	v_rcp_f32_e32 v182, v182
	v_rcp_f32_e32 v183, v183
	v_rcp_f32_e32 v184, v184
	v_rcp_f32_e32 v185, v185
	s_nop 0
	v_pk_mul_f32 v[54:55], v[54:55], v[194:195]
	v_pk_mul_f32 v[56:57], v[56:57], v[172:173]
	v_pk_mul_f32 v[50:51], v[50:51], v[182:183]
	v_pk_mul_f32 v[52:53], v[52:53], v[184:185]
	v_cvt_pk_bf16_f32 v182, v54, v55
	v_cvt_pk_bf16_f32 v183, v56, v57
	v_cvt_pk_bf16_f32 v184, v50, v51
	v_cvt_pk_bf16_f32 v185, v52, v53
	s_add_u32 s60, s76, 0x80000
	s_addc_u32 s61, s77, 0
	global_store_dwordx4 v149, v[182:185], s[60:61] offset:256
	v_lshlrev_b32_e32 v194, 16, v186
	v_and_b32_e32 v195, 0xffff0000, v186
	v_lshlrev_b32_e32 v172, 16, v187
	v_and_b32_e32 v173, 0xffff0000, v187
	v_lshlrev_b32_e32 v186, 16, v188
	v_and_b32_e32 v187, 0xffff0000, v188
	v_lshlrev_b32_e32 v188, 16, v189
	v_and_b32_e32 v189, 0xffff0000, v189
	v_mul_f32_e32 v194, 0xbfb8aa3b, v194
	v_mul_f32_e32 v195, 0xbfb8aa3b, v195
	v_mul_f32_e32 v172, 0xbfb8aa3b, v172
	v_mul_f32_e32 v173, 0xbfb8aa3b, v173
	v_mul_f32_e32 v186, 0xbfb8aa3b, v186
	v_mul_f32_e32 v187, 0xbfb8aa3b, v187
	v_mul_f32_e32 v188, 0xbfb8aa3b, v188
	v_mul_f32_e32 v189, 0xbfb8aa3b, v189
	v_min_f32_e32 v194, 0x42700000, v194
	v_min_f32_e32 v195, 0x42700000, v195
	v_min_f32_e32 v172, 0x42700000, v172
	v_min_f32_e32 v173, 0x42700000, v173
	v_min_f32_e32 v186, 0x42700000, v186
	v_min_f32_e32 v187, 0x42700000, v187
	v_min_f32_e32 v188, 0x42700000, v188
	v_min_f32_e32 v189, 0x42700000, v189
	v_exp_f32_e32 v194, v194
	v_exp_f32_e32 v195, v195
	v_exp_f32_e32 v172, v172
	v_exp_f32_e32 v173, v173
	v_exp_f32_e32 v186, v186
	v_exp_f32_e32 v187, v187
	v_exp_f32_e32 v188, v188
	v_exp_f32_e32 v189, v189
	v_add_f32_e32 v194, 1.0, v194
	v_add_f32_e32 v195, 1.0, v195
	v_add_f32_e32 v172, 1.0, v172
	v_add_f32_e32 v173, 1.0, v173
	v_add_f32_e32 v186, 1.0, v186
	v_add_f32_e32 v187, 1.0, v187
	v_add_f32_e32 v188, 1.0, v188
; __device__ __forceinline__ unsigned pk2(float lo, float hi) { f32x2_t v = {lo, hi}; bf16x2_t b = __builtin_convertvector(v, bf16x2_t); return __builtin_bit_cast(unsigned, b); }
; __device__ __forceinline__ float sigmoidf_(float x) { return __builtin_amdgcn_rcpf(1.f + __expf(-x)); }
;     __device__ __forceinline__ void operator()(const pg8::f32x4 (&acc)[2][2][4][2], const pg8::Unit& u, int wr, int wc, int fr, int fq) const {
;     ...
;                 const size_t r = (size_t)(row0 + ai * 128 + m * 16);
; #pragma unroll
;                 for (int bj = 0; bj < 2; ++bj) {
;                     const int col = col0 + bj * 128;
;                     const u32x4v gw = *(const u32x4v*)(mg + r * PP + (size_t)u.z * D + col);
;                     float gt[8];
;                     gt[0] = __builtin_bit_cast(float, gw.x << 16); gt[1] = __builtin_bit_cast(float, gw.x & 0xffff0000u); gt[2] = __builtin_bit_cast(float, gw.y << 16); gt[3] = __builtin_bit_cast(float, gw.y & 0xffff0000u);
;                     gt[4] = __builtin_bit_cast(float, gw.z << 16); gt[5] = __builtin_bit_cast(float, gw.z & 0xffff0000u); gt[6] = __builtin_bit_cast(float, gw.w << 16); gt[7] = __builtin_bit_cast(float, gw.w & 0xffff0000u);
;                     pg8::f32x4 v0 = acc[ai][bj][m][0], v1 = acc[ai][bj][m][1];
; #pragma unroll
;                     for (int e = 0; e < 4; ++e) { v0[e] *= sigmoidf_(gt[e]); v1[e] *= sigmoidf_(gt[4 + e]); }
;                     float* ap = accb + r * D + col;
;                     if (u.z > 0) { v0 += *(const pg8::f32x4*)ap; v1 += *(const pg8::f32x4*)(ap + 4); }
;                     if (u.z < 2) { *(pg8::f32x4*)ap = v0; *(pg8::f32x4*)(ap + 4) = v1; }
;                     else { pg8::u32x4 w; w.x = pk2(v0[0], v0[1]); w.y = pk2(v0[2], v0[3]); w.z = pk2(v1[0], v1[1]); w.w = pk2(v1[2], v1[3]); *(pg8::u32x4*)(out + r * D + col) = w; }
	v_add_f32_e32 v189, 1.0, v189
	v_rcp_f32_e32 v194, v194
	v_rcp_f32_e32 v195, v195
	v_rcp_f32_e32 v172, v172
	v_rcp_f32_e32 v173, v173
	v_rcp_f32_e32 v186, v186
	v_rcp_f32_e32 v187, v187
	v_rcp_f32_e32 v188, v188
	v_rcp_f32_e32 v189, v189
	s_nop 0
	v_pk_mul_f32 v[46:47], v[46:47], v[194:195]
	v_pk_mul_f32 v[48:49], v[48:49], v[172:173]
	v_pk_mul_f32 v[42:43], v[42:43], v[186:187]
	v_pk_mul_f32 v[44:45], v[44:45], v[188:189]
	v_cvt_pk_bf16_f32 v186, v46, v47
	v_cvt_pk_bf16_f32 v187, v48, v49
	v_cvt_pk_bf16_f32 v188, v42, v43
	v_cvt_pk_bf16_f32 v189, v44, v45
	s_add_u32 s62, s76, 0x90000
	s_addc_u32 s63, s77, 0
	global_store_dwordx4 v149, v[186:189], s[62:63] offset:0
	v_lshlrev_b32_e32 v194, 16, v190
	v_and_b32_e32 v195, 0xffff0000, v190
	v_lshlrev_b32_e32 v172, 16, v191
	v_and_b32_e32 v173, 0xffff0000, v191
	v_lshlrev_b32_e32 v190, 16, v192
	v_and_b32_e32 v191, 0xffff0000, v192
	v_lshlrev_b32_e32 v192, 16, v193
	v_and_b32_e32 v193, 0xffff0000, v193
	v_mul_f32_e32 v194, 0xbfb8aa3b, v194
	v_mul_f32_e32 v195, 0xbfb8aa3b, v195
	v_mul_f32_e32 v172, 0xbfb8aa3b, v172
	v_mul_f32_e32 v173, 0xbfb8aa3b, v173
	v_mul_f32_e32 v190, 0xbfb8aa3b, v190
	v_mul_f32_e32 v191, 0xbfb8aa3b, v191
	v_mul_f32_e32 v192, 0xbfb8aa3b, v192
	v_mul_f32_e32 v193, 0xbfb8aa3b, v193
	v_min_f32_e32 v194, 0x42700000, v194
	v_min_f32_e32 v195, 0x42700000, v195
	v_min_f32_e32 v172, 0x42700000, v172
	v_min_f32_e32 v173, 0x42700000, v173
	v_min_f32_e32 v190, 0x42700000, v190
	v_min_f32_e32 v191, 0x42700000, v191
	v_min_f32_e32 v192, 0x42700000, v192
	v_min_f32_e32 v193, 0x42700000, v193
	v_exp_f32_e32 v194, v194
	v_exp_f32_e32 v195, v195
	v_exp_f32_e32 v172, v172
	v_exp_f32_e32 v173, v173
	v_exp_f32_e32 v190, v190
	v_exp_f32_e32 v191, v191
	v_exp_f32_e32 v192, v192
	v_exp_f32_e32 v193, v193
	v_add_f32_e32 v194, 1.0, v194
	v_add_f32_e32 v195, 1.0, v195
	v_add_f32_e32 v172, 1.0, v172
	v_add_f32_e32 v173, 1.0, v173
	v_add_f32_e32 v190, 1.0, v190
	v_add_f32_e32 v191, 1.0, v191
	v_add_f32_e32 v192, 1.0, v192
	v_add_f32_e32 v193, 1.0, v193
	v_rcp_f32_e32 v194, v194
	v_rcp_f32_e32 v195, v195
	v_rcp_f32_e32 v172, v172
	v_rcp_f32_e32 v173, v173
	v_rcp_f32_e32 v190, v190
	v_rcp_f32_e32 v191, v191
	v_rcp_f32_e32 v192, v192
	v_rcp_f32_e32 v193, v193
	s_nop 0
	v_pk_mul_f32 v[38:39], v[38:39], v[194:195]
	v_pk_mul_f32 v[40:41], v[40:41], v[172:173]
	v_pk_mul_f32 v[34:35], v[34:35], v[190:191]
	v_pk_mul_f32 v[36:37], v[36:37], v[192:193]
	v_cvt_pk_bf16_f32 v190, v38, v39
	v_cvt_pk_bf16_f32 v191, v40, v41
	v_cvt_pk_bf16_f32 v192, v34, v35
	v_cvt_pk_bf16_f32 v193, v36, v37
	s_add_u32 s64, s76, 0x90000
	s_addc_u32 s65, s77, 0
	global_store_dwordx4 v149, v[190:193], s[64:65] offset:256
	s_waitcnt vmcnt(0)
	v_lshlrev_b32_e32 v194, 16, v210
	v_and_b32_e32 v195, 0xffff0000, v210
	v_lshlrev_b32_e32 v172, 16, v211
	v_and_b32_e32 v173, 0xffff0000, v211
	v_lshlrev_b32_e32 v210, 16, v212
	v_and_b32_e32 v211, 0xffff0000, v212
	v_lshlrev_b32_e32 v212, 16, v213
	v_and_b32_e32 v213, 0xffff0000, v213
	v_mul_f32_e32 v194, 0xbfb8aa3b, v194
	v_mul_f32_e32 v195, 0xbfb8aa3b, v195
	v_mul_f32_e32 v172, 0xbfb8aa3b, v172
	v_mul_f32_e32 v173, 0xbfb8aa3b, v173
	v_mul_f32_e32 v210, 0xbfb8aa3b, v210
	v_mul_f32_e32 v211, 0xbfb8aa3b, v211
	v_mul_f32_e32 v212, 0xbfb8aa3b, v212
	v_mul_f32_e32 v213, 0xbfb8aa3b, v213
	v_min_f32_e32 v194, 0x42700000, v194
	v_min_f32_e32 v195, 0x42700000, v195
	v_min_f32_e32 v172, 0x42700000, v172
	v_min_f32_e32 v173, 0x42700000, v173
	v_min_f32_e32 v210, 0x42700000, v210
	v_min_f32_e32 v211, 0x42700000, v211
	v_min_f32_e32 v212, 0x42700000, v212
	v_min_f32_e32 v213, 0x42700000, v213
	v_exp_f32_e32 v194, v194
	v_exp_f32_e32 v195, v195
	v_exp_f32_e32 v172, v172
	v_exp_f32_e32 v173, v173
	v_exp_f32_e32 v210, v210
	v_exp_f32_e32 v211, v211
	v_exp_f32_e32 v212, v212
	v_exp_f32_e32 v213, v213
	v_add_f32_e32 v194, 1.0, v194
	v_add_f32_e32 v195, 1.0, v195
	v_add_f32_e32 v172, 1.0, v172
	v_add_f32_e32 v173, 1.0, v173
	v_add_f32_e32 v210, 1.0, v210
	v_add_f32_e32 v211, 1.0, v211
	v_add_f32_e32 v212, 1.0, v212
	v_add_f32_e32 v213, 1.0, v213
	v_rcp_f32_e32 v194, v194
	v_rcp_f32_e32 v195, v195
	v_rcp_f32_e32 v172, v172
	v_rcp_f32_e32 v173, v173
	v_rcp_f32_e32 v210, v210
	v_rcp_f32_e32 v211, v211
	v_rcp_f32_e32 v212, v212
	v_rcp_f32_e32 v213, v213
	s_nop 0
	v_pk_mul_f32 v[30:31], v[30:31], v[194:195]
	v_pk_mul_f32 v[32:33], v[32:33], v[172:173]
	v_pk_mul_f32 v[26:27], v[26:27], v[210:211]
	v_pk_mul_f32 v[28:29], v[28:29], v[212:213]
	v_cvt_pk_bf16_f32 v210, v30, v31
	v_cvt_pk_bf16_f32 v211, v32, v33
	v_cvt_pk_bf16_f32 v212, v26, v27
	v_cvt_pk_bf16_f32 v213, v28, v29
	s_add_u32 s4, s76, 0xa0000
	s_addc_u32 s5, s77, 0
	global_store_dwordx4 v149, v[210:213], s[4:5] offset:0
	v_lshlrev_b32_e32 v194, 16, v214
	v_and_b32_e32 v195, 0xffff0000, v214
	v_lshlrev_b32_e32 v172, 16, v215
	v_and_b32_e32 v173, 0xffff0000, v215
	v_lshlrev_b32_e32 v214, 16, v216
	v_and_b32_e32 v215, 0xffff0000, v216
	v_lshlrev_b32_e32 v216, 16, v217
	v_and_b32_e32 v217, 0xffff0000, v217
	v_mul_f32_e32 v194, 0xbfb8aa3b, v194
	v_mul_f32_e32 v195, 0xbfb8aa3b, v195
	v_mul_f32_e32 v172, 0xbfb8aa3b, v172
	v_mul_f32_e32 v173, 0xbfb8aa3b, v173
	v_mul_f32_e32 v214, 0xbfb8aa3b, v214
	v_mul_f32_e32 v215, 0xbfb8aa3b, v215
	v_mul_f32_e32 v216, 0xbfb8aa3b, v216
	v_mul_f32_e32 v217, 0xbfb8aa3b, v217
	v_min_f32_e32 v194, 0x42700000, v194
; __device__ __forceinline__ unsigned pk2(float lo, float hi) { f32x2_t v = {lo, hi}; bf16x2_t b = __builtin_convertvector(v, bf16x2_t); return __builtin_bit_cast(unsigned, b); }
; __device__ __forceinline__ float sigmoidf_(float x) { return __builtin_amdgcn_rcpf(1.f + __expf(-x)); }
;     __device__ __forceinline__ void operator()(const pg8::f32x4 (&acc)[2][2][4][2], const pg8::Unit& u, int wr, int wc, int fr, int fq) const {
;     ...
;                 const size_t r = (size_t)(row0 + ai * 128 + m * 16);
; #pragma unroll
;                 for (int bj = 0; bj < 2; ++bj) {
;                     const int col = col0 + bj * 128;
;                     const u32x4v gw = *(const u32x4v*)(mg + r * PP + (size_t)u.z * D + col);
;                     float gt[8];
;                     gt[0] = __builtin_bit_cast(float, gw.x << 16); gt[1] = __builtin_bit_cast(float, gw.x & 0xffff0000u); gt[2] = __builtin_bit_cast(float, gw.y << 16); gt[3] = __builtin_bit_cast(float, gw.y & 0xffff0000u);
;                     gt[4] = __builtin_bit_cast(float, gw.z << 16); gt[5] = __builtin_bit_cast(float, gw.z & 0xffff0000u); gt[6] = __builtin_bit_cast(float, gw.w << 16); gt[7] = __builtin_bit_cast(float, gw.w & 0xffff0000u);
;                     pg8::f32x4 v0 = acc[ai][bj][m][0], v1 = acc[ai][bj][m][1];
; #pragma unroll
;                     for (int e = 0; e < 4; ++e) { v0[e] *= sigmoidf_(gt[e]); v1[e] *= sigmoidf_(gt[4 + e]); }
;                     float* ap = accb + r * D + col;
;                     if (u.z > 0) { v0 += *(const pg8::f32x4*)ap; v1 += *(const pg8::f32x4*)(ap + 4); }
;                     if (u.z < 2) { *(pg8::f32x4*)ap = v0; *(pg8::f32x4*)(ap + 4) = v1; }
;                     else { pg8::u32x4 w; w.x = pk2(v0[0], v0[1]); w.y = pk2(v0[2], v0[3]); w.z = pk2(v1[0], v1[1]); w.w = pk2(v1[2], v1[3]); *(pg8::u32x4*)(out + r * D + col) = w; }
	v_min_f32_e32 v195, 0x42700000, v195
	v_min_f32_e32 v172, 0x42700000, v172
	v_min_f32_e32 v173, 0x42700000, v173
	v_min_f32_e32 v214, 0x42700000, v214
	v_min_f32_e32 v215, 0x42700000, v215
	v_min_f32_e32 v216, 0x42700000, v216
	v_min_f32_e32 v217, 0x42700000, v217
	v_exp_f32_e32 v194, v194
	v_exp_f32_e32 v195, v195
	v_exp_f32_e32 v172, v172
	v_exp_f32_e32 v173, v173
	v_exp_f32_e32 v214, v214
	v_exp_f32_e32 v215, v215
	v_exp_f32_e32 v216, v216
	v_exp_f32_e32 v217, v217
	v_add_f32_e32 v194, 1.0, v194
	v_add_f32_e32 v195, 1.0, v195
	v_add_f32_e32 v172, 1.0, v172
	v_add_f32_e32 v173, 1.0, v173
	v_add_f32_e32 v214, 1.0, v214
	v_add_f32_e32 v215, 1.0, v215
	v_add_f32_e32 v216, 1.0, v216
	v_add_f32_e32 v217, 1.0, v217
	v_rcp_f32_e32 v194, v194
	v_rcp_f32_e32 v195, v195
	v_rcp_f32_e32 v172, v172
	v_rcp_f32_e32 v173, v173
	v_rcp_f32_e32 v214, v214
	v_rcp_f32_e32 v215, v215
	v_rcp_f32_e32 v216, v216
	v_rcp_f32_e32 v217, v217
	s_nop 0
	v_pk_mul_f32 v[22:23], v[22:23], v[194:195]
	v_pk_mul_f32 v[24:25], v[24:25], v[172:173]
	v_pk_mul_f32 v[18:19], v[18:19], v[214:215]
	v_pk_mul_f32 v[20:21], v[20:21], v[216:217]
	v_cvt_pk_bf16_f32 v214, v22, v23
	v_cvt_pk_bf16_f32 v215, v24, v25
	v_cvt_pk_bf16_f32 v216, v18, v19
	v_cvt_pk_bf16_f32 v217, v20, v21
	s_add_u32 s8, s76, 0xa0000
	s_addc_u32 s9, s77, 0
	global_store_dwordx4 v149, v[214:217], s[8:9] offset:256
	v_lshlrev_b32_e32 v194, 16, v218
	v_and_b32_e32 v195, 0xffff0000, v218
	v_lshlrev_b32_e32 v172, 16, v219
	v_and_b32_e32 v173, 0xffff0000, v219
	v_lshlrev_b32_e32 v218, 16, v220
	v_and_b32_e32 v219, 0xffff0000, v220
	v_lshlrev_b32_e32 v220, 16, v221
	v_and_b32_e32 v221, 0xffff0000, v221
	v_mul_f32_e32 v194, 0xbfb8aa3b, v194
	v_mul_f32_e32 v195, 0xbfb8aa3b, v195
	v_mul_f32_e32 v172, 0xbfb8aa3b, v172
	v_mul_f32_e32 v173, 0xbfb8aa3b, v173
	v_mul_f32_e32 v218, 0xbfb8aa3b, v218
	v_mul_f32_e32 v219, 0xbfb8aa3b, v219
	v_mul_f32_e32 v220, 0xbfb8aa3b, v220
	v_mul_f32_e32 v221, 0xbfb8aa3b, v221
	v_min_f32_e32 v194, 0x42700000, v194
	v_min_f32_e32 v195, 0x42700000, v195
	v_min_f32_e32 v172, 0x42700000, v172
	v_min_f32_e32 v173, 0x42700000, v173
	v_min_f32_e32 v218, 0x42700000, v218
	v_min_f32_e32 v219, 0x42700000, v219
	v_min_f32_e32 v220, 0x42700000, v220
	v_min_f32_e32 v221, 0x42700000, v221
	v_exp_f32_e32 v194, v194
	v_exp_f32_e32 v195, v195
	v_exp_f32_e32 v172, v172
	v_exp_f32_e32 v173, v173
	v_exp_f32_e32 v218, v218
	v_exp_f32_e32 v219, v219
	v_exp_f32_e32 v220, v220
	v_exp_f32_e32 v221, v221
	v_add_f32_e32 v194, 1.0, v194
	v_add_f32_e32 v195, 1.0, v195
	v_add_f32_e32 v172, 1.0, v172
	v_add_f32_e32 v173, 1.0, v173
	v_add_f32_e32 v218, 1.0, v218
	v_add_f32_e32 v219, 1.0, v219
	v_add_f32_e32 v220, 1.0, v220
	v_add_f32_e32 v221, 1.0, v221
	v_rcp_f32_e32 v194, v194
	v_rcp_f32_e32 v195, v195
	v_rcp_f32_e32 v172, v172
	v_rcp_f32_e32 v173, v173
	v_rcp_f32_e32 v218, v218
	v_rcp_f32_e32 v219, v219
	v_rcp_f32_e32 v220, v220
	v_rcp_f32_e32 v221, v221
	s_nop 0
	v_pk_mul_f32 v[14:15], v[14:15], v[194:195]
	v_pk_mul_f32 v[16:17], v[16:17], v[172:173]
	v_pk_mul_f32 v[10:11], v[10:11], v[218:219]
	v_pk_mul_f32 v[12:13], v[12:13], v[220:221]
	v_cvt_pk_bf16_f32 v218, v14, v15
	v_cvt_pk_bf16_f32 v219, v16, v17
	v_cvt_pk_bf16_f32 v220, v10, v11
	v_cvt_pk_bf16_f32 v221, v12, v13
	s_add_u32 s38, s76, 0xb0000
	s_addc_u32 s39, s77, 0
	global_store_dwordx4 v149, v[218:221], s[38:39] offset:0
	v_lshlrev_b32_e32 v194, 16, v222
	v_and_b32_e32 v195, 0xffff0000, v222
	v_lshlrev_b32_e32 v172, 16, v223
	v_and_b32_e32 v173, 0xffff0000, v223
	v_lshlrev_b32_e32 v222, 16, v224
	v_and_b32_e32 v223, 0xffff0000, v224
	v_lshlrev_b32_e32 v224, 16, v225
	v_and_b32_e32 v225, 0xffff0000, v225
	v_mul_f32_e32 v194, 0xbfb8aa3b, v194
	v_mul_f32_e32 v195, 0xbfb8aa3b, v195
	v_mul_f32_e32 v172, 0xbfb8aa3b, v172
	v_mul_f32_e32 v173, 0xbfb8aa3b, v173
	v_mul_f32_e32 v222, 0xbfb8aa3b, v222
	v_mul_f32_e32 v223, 0xbfb8aa3b, v223
	v_mul_f32_e32 v224, 0xbfb8aa3b, v224
	v_mul_f32_e32 v225, 0xbfb8aa3b, v225
	v_min_f32_e32 v194, 0x42700000, v194
	v_min_f32_e32 v195, 0x42700000, v195
	v_min_f32_e32 v172, 0x42700000, v172
	v_min_f32_e32 v173, 0x42700000, v173
	v_min_f32_e32 v222, 0x42700000, v222
	v_min_f32_e32 v223, 0x42700000, v223
	v_min_f32_e32 v224, 0x42700000, v224
	v_min_f32_e32 v225, 0x42700000, v225
	v_exp_f32_e32 v194, v194
	v_exp_f32_e32 v195, v195
	v_exp_f32_e32 v172, v172
	v_exp_f32_e32 v173, v173
	v_exp_f32_e32 v222, v222
	v_exp_f32_e32 v223, v223
	v_exp_f32_e32 v224, v224
	v_exp_f32_e32 v225, v225
	v_add_f32_e32 v194, 1.0, v194
	v_add_f32_e32 v195, 1.0, v195
	v_add_f32_e32 v172, 1.0, v172
	v_add_f32_e32 v173, 1.0, v173
	v_add_f32_e32 v222, 1.0, v222
	v_add_f32_e32 v223, 1.0, v223
	v_add_f32_e32 v224, 1.0, v224
	v_add_f32_e32 v225, 1.0, v225
	v_rcp_f32_e32 v194, v194
	v_rcp_f32_e32 v195, v195
	v_rcp_f32_e32 v172, v172
	v_rcp_f32_e32 v173, v173
	v_rcp_f32_e32 v222, v222
	v_rcp_f32_e32 v223, v223
	v_rcp_f32_e32 v224, v224
	v_rcp_f32_e32 v225, v225
	s_nop 0
	v_pk_mul_f32 v[6:7], v[6:7], v[194:195]
	v_pk_mul_f32 v[8:9], v[8:9], v[172:173]
	v_pk_mul_f32 v[2:3], v[2:3], v[222:223]
	v_pk_mul_f32 v[4:5], v[4:5], v[224:225]
	v_cvt_pk_bf16_f32 v222, v6, v7
	v_cvt_pk_bf16_f32 v223, v8, v9
	v_cvt_pk_bf16_f32 v224, v2, v3
	v_cvt_pk_bf16_f32 v225, v4, v5
	s_add_u32 s60, s76, 0xb0000
	s_addc_u32 s61, s77, 0
	global_store_dwordx4 v149, v[222:225], s[60:61] offset:256
